# P5 intra/sample loops: loads hoisted; P3: conv units rebalanced over workgroups (sample units to workgroups with a short first attention unit); output copies batched
# speedup vs baseline: 1.0341x; 1.0037x over previous
; #define PHASE_BEGIN() do { int t_ = C.tid; asm volatile("" : "+v"(t_)); C.tid = t_; C.lane = t_ & 63; C.wave = __builtin_amdgcn_readfirstlane(t_ >> 6); \
;         int g_ = C.G, b_ = C.bid; asm volatile("" : "+s"(g_), "+s"(b_)); C.G = g_; C.bid = b_; } while (0)
; __global__ void __launch_bounds__(512) fwd_megakernel(Args args) {
;     ...
;             if (rep == REP_P3 - 1) {
;                 for (int u = C.bid; u < NBD + NBP * NPC; u += C.G) { PHASE_BEGIN(); if (u < NBD) conv_unit<true>(C, l, u); else conv_unit<false>(C, l, u - NBD); }
;             }
.LBB0_520:
	v_readlane_b32 s2, v255, 40
	v_readlane_b32 s3, v255, 41
	s_mov_b32 s3, s79
	s_lshl_b64 s[16:17], s[2:3], 14
	s_lshl_b64 s[18:19], s[2:3], 12
	s_mov_b64 s[14:15], s[2:3]
	s_cmpk_gt_i32 s4, 0x21f
	s_movk_i32 s35, 0x5000
	s_cbranch_scc1 .LBB0_534
	v_readlane_b32 s40, v253, 18
	v_readlane_b32 s54, v253, 32
	v_readlane_b32 s41, v253, 19
	v_readlane_b32 s42, v253, 20
	v_readlane_b32 s43, v253, 21
	v_readlane_b32 s44, v253, 22
	v_readlane_b32 s45, v253, 23
	v_readlane_b32 s46, v253, 24
	v_readlane_b32 s47, v253, 25
	v_readlane_b32 s48, v253, 26
	v_readlane_b32 s49, v253, 27
	v_readlane_b32 s50, v253, 28
	v_readlane_b32 s51, v253, 29
	v_readlane_b32 s52, v253, 30
	v_readlane_b32 s53, v253, 31
	v_readlane_b32 s55, v253, 33
	s_add_u32 s2, s54, s16
	s_addc_u32 s3, s55, s17
	v_readlane_b32 s40, v253, 34
	v_readlane_b32 s41, v253, 35
	s_add_u32 s6, s40, s18
	s_addc_u32 s7, s41, s19
	s_mov_b32 s72, s4
	v_readlane_b32 s42, v253, 36
	v_readlane_b32 s43, v253, 37
	v_readlane_b32 s44, v253, 38
	v_readlane_b32 s45, v253, 39
	v_readlane_b32 s46, v253, 40
	v_readlane_b32 s47, v253, 41
	v_readlane_b32 s48, v253, 42
	v_readlane_b32 s49, v253, 43
	v_readlane_b32 s50, v253, 44
	v_readlane_b32 s51, v253, 45
	v_readlane_b32 s52, v253, 46
	v_readlane_b32 s53, v253, 47
	v_readlane_b32 s54, v253, 48
	v_readlane_b32 s55, v253, 49
	s_cmp_eq_u32 s26, 0x100
	s_cbranch_scc0 .Lconv_init_done
	s_addk_i32 s4, 32
.Lconv_init_done:
	s_branch .LBB0_524
.LBB0_522:
	s_or_b64 exec, exec, s[10:11]
.LBB0_523:
	s_cmp_eq_u32 s26, 0x100
	s_cbranch_scc0 .Lconv_generic
	s_cmp_lt_u32 s4, 24
	s_cbranch_scc1 .Lconv_fourth
	s_cmp_lt_u32 s4, 32
	s_cbranch_scc1 .LBB0_535
	s_cmp_lt_u32 s4, 0x120
	s_cbranch_scc0 .Lconv_third
	s_addk_i32 s4, 0x100
	s_branch .LBB0_524
.Lconv_third:
	s_sub_u32 s5, s4, 0x120
	s_bitcmp1_b32 s5, 0
	s_cbranch_scc1 .LBB0_535
	s_cmp_lt_u32 s5, 48
	s_cbranch_scc0 .LBB0_535
	s_lshr_b32 s4, s5, 1
	s_branch .LBB0_524
.Lconv_fourth:
	s_cmp_lt_u32 s4, 8
	s_cbranch_scc0 .LBB0_535
	s_addk_i32 s4, 24
	s_branch .LBB0_524

; __device__ __forceinline__ float bf1(bf16 h) { return __uint_as_float((unsigned)h << 16); }
;     __device__ __forceinline__ bf16* U() const { return (bf16*)(ws + WS_U); }
; #define PHASE_BEGIN() do { int t_ = C.tid; asm volatile("" : "+v"(t_)); C.tid = t_; C.lane = t_ & 63; C.wave = __builtin_amdgcn_readfirstlane(t_ >> 6); \
;         int g_ = C.G, b_ = C.bid; asm volatile("" : "+s"(g_), "+s"(b_)); C.G = g_; C.bid = b_; } while (0)
; __global__ void __launch_bounds__(512) fwd_megakernel(Args args) {
;     ...
;                 for (int u = C.bid; u < NBD + NBP * NPC; u += C.G) { PHASE_BEGIN(); if (u < NBD) conv_unit<true>(C, l, u); else conv_unit<false>(C, l, u - NBD); }
;             }
;             }
;             PHASE_BEGIN();
;             for (int rep = 0; rep < REP_COPY; ++rep) {
;             const int gt = C.bid * 512 + C.tid, NT = C.G * 512;
;             for (int e = gt; e < NBP * 512 * 512; e += NT) { const int b = e >> 18, t = (e >> 9) & 511, cc = e & 511; const size_t row = (size_t)b * SEQ + 7680 + t;
;                 C.out[O_NKP + (size_t)l * NBP * 262144 + e] = bf1(C.U()[row * UW + C_KA + cc]); }
.LBB0_535:
	s_cmp_eq_u32 s26, 0x100
	s_cbranch_scc0 .Lcopy_generic1
	s_mov_b64 s[4:5], exec
	s_branch .LBB0_543

; #define LAS __attribute__((address_space(3)))
; __global__ void __launch_bounds__(512) fwd_megakernel(Args args) {
;     ...
;             for (int e = gt; e < NBP * 512 * 512; e += NT) { const int b = e >> 18, t = (e >> 9) & 511, cc = e & 511; const size_t row = (size_t)b * SEQ + 7680 + t;
;                 C.out[O_NKP + (size_t)l * NBP * 262144 + e] = bf1(C.U()[row * UW + C_KA + cc]); }
;             {
;                 LAS float* T = (LAS float*)(lds + 32768);
;                 __syncthreads();
;                 for (int tile = C.bid; tile < NBP * 64; tile += C.G) {
;                     const int b = tile >> 6, tb = (tile >> 3) & 7, cb8 = tile & 7;
;                     { const int ccl = C.tid >> 3, t8 = (C.tid & 7) * 8; const size_t row = (size_t)b * SEQ + 7680 + tb * 64 + t8;
;                       float x[8]; unpack8(*(const u32x4*)(C.KVt() + (size_t)(R_VA + cb8 * 64 + ccl) * MT + row), x);
; #pragma unroll
;                       for (int e = 0; e < 8; ++e) T[ccl * 65 + t8 + e] = x[e]; }
;                     __syncthreads();
;                     { const int tl = C.tid >> 3, c8 = (C.tid & 7) * 8;
;                       float* o = C.out + O_NVP + (size_t)l * NBP * 262144 + ((size_t)b * 512 + tb * 64 + tl) * 512 + cb8 * 64 + c8;
;                       f32x4 a, c;
;                       a.x = T[(c8 + 0) * 65 + tl]; a.y = T[(c8 + 1) * 65 + tl]; a.z = T[(c8 + 2) * 65 + tl]; a.w = T[(c8 + 3) * 65 + tl];
;                       c.x = T[(c8 + 4) * 65 + tl]; c.y = T[(c8 + 5) * 65 + tl]; c.z = T[(c8 + 6) * 65 + tl]; c.w = T[(c8 + 7) * 65 + tl];
;                       *(f32x4*)o = a; *(f32x4*)(o + 4) = c; }
;                     __syncthreads();
;                 }
;             }
;             for (int e = gt; e < NBD * TS * 512; e += NT) { const int bd = e >> 14, t = (e >> 9) & 31, cc = e & 511; const size_t row = (size_t)MP + bd * TS + t;
;                 C.out[O_NKS + (size_t)l * NBD * TS * 512 + e] = bf1(C.U()[row * UW + C_KA + cc]);
;                 C.out[O_NVS + (size_t)l * NBD * TS * 512 + e] = bf1(C.KVt()[(size_t)(R_VA + cc) * MT + row]); }
;             for (int e = gt; e < NBP * 3 * 1024; e += NT) { const int b = e / 3072, j = (e / 1024) % 3, ch = e & 1023;
;                 C.out[O_NCVP + (size_t)l * NBP * 3072 + e] = bf1(C.HALO()[((size_t)(b * NPC + NPC - 1) * 3 + j) * 1024 + ch]); }
.LBB0_546:
	s_cmp_eq_u32 s26, 0x100
	s_cbranch_scc0 .Lcopy_generic2
	v_lshlrev_b32_e32 v20, 1, v202
	v_lshlrev_b32_e32 v21, 2, v202
	v_mul_u32_u24_e32 v22, 0x10800, v202
	s_add_u32 s42, s72, 0x1e00
	s_mul_i32 s42, s42, 0x2400
	s_add_u32 s42, s42, 0x400
	s_add_u32 s43, s42, 0x0
	s_add_u32 s40, s90, s43
	s_addc_u32 s41, s91, 0
	global_load_ushort v42, v20, s[40:41]
	s_add_u32 s43, s42, 0x240000
	s_add_u32 s40, s90, s43
	s_addc_u32 s41, s91, 0
	global_load_ushort v43, v20, s[40:41]
	s_add_u32 s43, s42, 0x4800000
	s_add_u32 s40, s90, s43
	s_addc_u32 s41, s91, 0
	global_load_ushort v44, v20, s[40:41]
	s_add_u32 s43, s42, 0x4a40000
	s_add_u32 s40, s90, s43
	s_addc_u32 s41, s91, 0
	global_load_ushort v45, v20, s[40:41]
	s_add_u32 s43, s42, 0x9000000
	s_add_u32 s40, s90, s43
	s_addc_u32 s41, s91, 0
	global_load_ushort v46, v20, s[40:41]
	s_add_u32 s43, s42, 0x9240000
	s_add_u32 s40, s90, s43
	s_addc_u32 s41, s91, 0
	global_load_ushort v47, v20, s[40:41]
	s_add_u32 s43, s42, 0xd800000
	s_add_u32 s40, s90, s43
	s_addc_u32 s41, s91, 0
	global_load_ushort v48, v20, s[40:41]
	s_add_u32 s43, s42, 0xda40000
	s_add_u32 s40, s90, s43
	s_addc_u32 s41, s91, 0
	global_load_ushort v49, v20, s[40:41]
	s_add_u32 s42, s72, 0x8000
	s_mul_i32 s42, s42, 0x2400
	s_add_u32 s42, s42, 0x400
	s_add_u32 s43, s42, 0x0
	s_add_u32 s40, s90, s43
	s_addc_u32 s41, s91, 0
	global_load_ushort v50, v20, s[40:41]
	s_add_u32 s43, s42, 0x240000
	s_add_u32 s40, s90, s43
	s_addc_u32 s41, s91, 0
	global_load_ushort v51, v20, s[40:41]
	s_add_u32 s43, s42, 0x480000
	s_add_u32 s40, s90, s43
	s_addc_u32 s41, s91, 0
	global_load_ushort v52, v20, s[40:41]
	s_add_u32 s43, s42, 0x6c0000
	s_add_u32 s40, s90, s43
	s_addc_u32 s41, s91, 0
	global_load_ushort v53, v20, s[40:41]
	s_lshl_b32 s42, s72, 1
	s_add_u32 s42, s42, 0x12910000
	s_add_u32 s43, s42, 0x0
	s_add_u32 s40, s90, s43
	s_addc_u32 s41, s91, 0
	global_load_ushort v54, v22, s[40:41]
	s_add_u32 s43, s42, 0x200
	s_add_u32 s40, s90, s43
	s_addc_u32 s41, s91, 0
	global_load_ushort v55, v22, s[40:41]
	s_add_u32 s43, s42, 0x400
	s_add_u32 s40, s90, s43
	s_addc_u32 s41, s91, 0
	global_load_ushort v56, v22, s[40:41]
	s_add_u32 s43, s42, 0x600
	s_add_u32 s40, s90, s43
	s_addc_u32 s41, s91, 0
	global_load_ushort v57, v22, s[40:41]
	s_cmp_lt_u32 s72, 0xc0
	s_cbranch_scc0 .Lcopy_ld_done
	s_lshl_b32 s42, s72, 10
	s_add_u32 s42, s42, 0x1f080000
	s_add_u32 s40, s90, s42
	s_addc_u32 s41, s91, 0
	global_load_ushort v58, v20, s[40:41]
	s_cmp_lt_u32 s72, 24
	s_cbranch_scc0 .Lcopy_ld_done
	s_lshr_b32 s42, s72, 1
	s_mul_i32 s42, s42, 11
	s_lshr_b32 s42, s42, 5
	s_add_u32 s42, s42, 1
	s_mul_i32 s42, s42, 0xbe800
	s_lshl_b32 s43, s72, 10
	s_add_u32 s42, s42, s43
	s_add_u32 s42, s42, 0x1ed80000
	s_add_u32 s40, s90, s42
	s_addc_u32 s41, s91, 0
	global_load_ushort v59, v20, s[40:41]
.Lcopy_ld_done:
	s_waitcnt vmcnt(0)
	v_lshlrev_b32_e32 v42, 16, v42
	v_lshlrev_b32_e32 v43, 16, v43
	v_lshlrev_b32_e32 v44, 16, v44
	v_lshlrev_b32_e32 v45, 16, v45
	v_lshlrev_b32_e32 v46, 16, v46
	v_lshlrev_b32_e32 v47, 16, v47
	v_lshlrev_b32_e32 v48, 16, v48
	v_lshlrev_b32_e32 v49, 16, v49
	v_lshlrev_b32_e32 v50, 16, v50
	v_lshlrev_b32_e32 v51, 16, v51
	v_lshlrev_b32_e32 v52, 16, v52
	v_lshlrev_b32_e32 v53, 16, v53
	v_lshlrev_b32_e32 v54, 16, v54
	v_lshlrev_b32_e32 v55, 16, v55
	v_lshlrev_b32_e32 v56, 16, v56
	v_lshlrev_b32_e32 v57, 16, v57
	s_lshl_b32 s44, s72, 11
	s_mul_i32 s42, s14, 0x400000
	s_add_u32 s42, s42, 0x8400000
	s_add_u32 s42, s42, s44
	s_add_u32 s40, s88, s42
	s_addc_u32 s41, s89, 0
	global_store_dword v21, v42, s[40:41]
	s_mul_i32 s42, s14, 0x400000
	s_add_u32 s42, s42, 0x8480000
	s_add_u32 s42, s42, s44
	s_add_u32 s40, s88, s42
	s_addc_u32 s41, s89, 0
	global_store_dword v21, v43, s[40:41]
	s_mul_i32 s42, s14, 0x400000
	s_add_u32 s42, s42, 0x8500000
	s_add_u32 s42, s42, s44
	s_add_u32 s40, s88, s42
	s_addc_u32 s41, s89, 0
	global_store_dword v21, v44, s[40:41]
	s_mul_i32 s42, s14, 0x400000
	s_add_u32 s42, s42, 0x8580000
	s_add_u32 s42, s42, s44
	s_add_u32 s40, s88, s42
	s_addc_u32 s41, s89, 0
	global_store_dword v21, v45, s[40:41]
	s_mul_i32 s42, s14, 0x400000
	s_add_u32 s42, s42, 0x8600000
	s_add_u32 s42, s42, s44
	s_add_u32 s40, s88, s42
	s_addc_u32 s41, s89, 0
	global_store_dword v21, v46, s[40:41]
	s_mul_i32 s42, s14, 0x400000
	s_add_u32 s42, s42, 0x8680000
	s_add_u32 s42, s42, s44
	s_add_u32 s40, s88, s42
	s_addc_u32 s41, s89, 0
	global_store_dword v21, v47, s[40:41]
	s_mul_i32 s42, s14, 0x400000
	s_add_u32 s42, s42, 0x8700000
	s_add_u32 s42, s42, s44
	s_add_u32 s40, s88, s42
	s_addc_u32 s41, s89, 0
	global_store_dword v21, v48, s[40:41]
	s_mul_i32 s42, s14, 0x400000
	s_add_u32 s42, s42, 0x8780000
	s_add_u32 s42, s42, s44
	s_add_u32 s40, s88, s42
	s_addc_u32 s41, s89, 0
	global_store_dword v21, v49, s[40:41]
	s_mul_i32 s42, s14, 0x200000
	s_add_u32 s42, s42, 0x961c080
	s_add_u32 s42, s42, s44
	s_add_u32 s40, s88, s42
	s_addc_u32 s41, s89, 0
	global_store_dword v21, v50, s[40:41]
	s_mul_i32 s42, s14, 0x200000
	s_add_u32 s42, s42, 0x969c080
	s_add_u32 s42, s42, s44
	s_add_u32 s40, s88, s42
	s_addc_u32 s41, s89, 0
	global_store_dword v21, v51, s[40:41]
	s_mul_i32 s42, s14, 0x200000
	s_add_u32 s42, s42, 0x971c080
	s_add_u32 s42, s42, s44
	s_add_u32 s40, s88, s42
	s_addc_u32 s41, s89, 0
	global_store_dword v21, v52, s[40:41]
	s_mul_i32 s42, s14, 0x200000
	s_add_u32 s42, s42, 0x979c080
	s_add_u32 s42, s42, s44
	s_add_u32 s40, s88, s42
	s_addc_u32 s41, s89, 0
	global_store_dword v21, v53, s[40:41]
	s_mul_i32 s42, s14, 0x200000
	s_add_u32 s42, s42, 0x9a1c080
	s_add_u32 s42, s42, s44
	s_add_u32 s40, s88, s42
	s_addc_u32 s41, s89, 0
	global_store_dword v21, v54, s[40:41]
	s_mul_i32 s42, s14, 0x200000
	s_add_u32 s42, s42, 0x9a9c080
	s_add_u32 s42, s42, s44
	s_add_u32 s40, s88, s42
	s_addc_u32 s41, s89, 0
	global_store_dword v21, v55, s[40:41]
	s_mul_i32 s42, s14, 0x200000
	s_add_u32 s42, s42, 0x9b1c080
	s_add_u32 s42, s42, s44
	s_add_u32 s40, s88, s42
	s_addc_u32 s41, s89, 0
	global_store_dword v21, v56, s[40:41]
	s_mul_i32 s42, s14, 0x200000
	s_add_u32 s42, s42, 0x9b9c080
	s_add_u32 s42, s42, s44
	s_add_u32 s40, s88, s42
	s_addc_u32 s41, s89, 0
	global_store_dword v21, v57, s[40:41]
	s_cmp_lt_u32 s72, 0xc0
	s_cbranch_scc0 .Lcopy_st_done
	v_lshlrev_b32_e32 v58, 16, v58
	s_mul_i32 s42, s14, 0x60000
	s_add_u32 s42, s42, 0x9e1c080
	s_add_u32 s42, s42, s44
	s_add_u32 s40, s88, s42
	s_addc_u32 s41, s89, 0
	global_store_dword v21, v58, s[40:41]
	s_cmp_lt_u32 s72, 24
	s_cbranch_scc0 .Lcopy_st_done
	v_lshlrev_b32_e32 v59, 16, v59
	s_mul_i32 s42, s14, 0xc000
	s_add_u32 s42, s42, 0x9400000
	s_add_u32 s42, s42, s44
	s_add_u32 s40, s88, s42
	s_addc_u32 s41, s89, 0
	global_store_dword v21, v59, s[40:41]
.Lcopy_st_done:
	s_mov_b64 s[4:5], exec
	s_branch .LBB0_565

; #define LAS __attribute__((address_space(3)))
; __device__ __forceinline__ unsigned pk2(float lo, float hi) { f32x2_t v = {lo, hi}; bf16x2_t b = __builtin_convertvector(v, bf16x2_t); return __builtin_bit_cast(unsigned, b); }
; #define MFMA32(a, b, c) __builtin_amdgcn_mfma_f32_32x32x16_bf16((a), (b), (c), 0, 0, 0)
;     __device__ __forceinline__ bf16* U() const { return (bf16*)(ws + WS_U); }
;     __device__ __forceinline__ bf16* KVt() const { return (bf16*)(ws + WS_KVT); }
; template <bool SAMPLE>
; __device__ __forceinline__ void mout_task(Ctx& C, int l, int unit, int h, int tb, const LAS float* cwl, const LAS float* gainl, LAS float* gsbuf, LAS s16x8* qfl, const bool st) {
;     ...
;         const int sl = 32 * sb + r;
;         { s16x8 tk[8];
;           const bf16* kp = C.U() + (grow0 + sl) * UW + C_KM + h * 128 + 8 * hi;
; #pragma unroll
;           for (int ks = 0; ks < 8; ++ks) tk[ks] = *(const s16x8*)(kp + 16 * ks);
; #pragma unroll
;           for (int ks = 0; ks < 8; ++ks) S = MFMA32(tk[ks], qfl[ks * 64 + lane], S); }
;         const float e0 = (bt - mt) * LOG2E;
; #pragma unroll
;         for (int i4 = 0; i4 < 4; ++i4) { const f32x4 gs = *(const LAS f32x4*)(gsbuf + 32 * sb + 8 * i4 + 4 * hi);
; #pragma unroll
;             for (int e = 0; e < 4; ++e) { const int sidx = 32 * sb + 8 * i4 + 4 * hi + e;
;                 const float wv = (sidx <= tl) ? __builtin_amdgcn_exp2f(e0 + gs[e] * LOG2E) : 0.f;
;                 S[4 * i4 + e] *= wv; den += S[4 * i4 + e]; } }
; #pragma unroll
;         for (int s2 = 0; s2 < 2; ++s2) { u32x4 w; w.x = pk2(S[8 * s2], S[8 * s2 + 1]); w.y = pk2(S[8 * s2 + 2], S[8 * s2 + 3]); w.z = pk2(S[8 * s2 + 4], S[8 * s2 + 5]); w.w = pk2(S[8 * s2 + 6], S[8 * s2 + 7]);
;             const s16x8 pf = __builtin_bit_cast(s16x8, w);
;             const bf16* vp0 = C.KVt() + (size_t)(R_VM + h * 128 + r) * MT + grow0 + 32 * sb + 16 * s2 + 4 * hi;
; #pragma unroll
;             for (int vb = 0; vb < 4; ++vb) { const bf16* vp = vp0 + (size_t)(32 * vb) * MT;
;                 const u32x2 a = *(const u32x2*)vp, bq = *(const u32x2*)(vp + 8); u32x4 vw; vw.x = a.x; vw.y = a.y; vw.z = bq.x; vw.w = bq.y;
;                 acc[vb] = MFMA32(__builtin_bit_cast(s16x8, vw), pf, acc[vb]); } }
.LBB0_909:
	v_lshl_add_u64 v[68:69], s[90:91], 0, v[138:139]
	global_load_dwordx4 v[64:67], v[68:69], off offset:3072
	global_load_dwordx4 v[140:143], v[68:69], off offset:3104
	global_load_dwordx4 v[160:163], v[68:69], off offset:3136
	global_load_dwordx4 v[164:167], v[68:69], off offset:3168
	global_load_dwordx4 v[168:171], v[68:69], off offset:3200
	global_load_dwordx4 v[172:175], v[68:69], off offset:3232
	global_load_dwordx4 v[176:179], v[68:69], off offset:3264
	global_load_dwordx4 v[180:183], v[68:69], off offset:3296
	v_cmp_gt_u32_e32 vcc, v120, v158
	s_mov_b32 s37, 0x12900000
	s_add_i32 s40, s40, -1
	s_mov_b64 s[72:73], 0x48000
	v_lshl_add_u64 v[138:139], v[138:139], 0, s[72:73]
	s_cmp_lg_u32 s40, 0
	s_waitcnt vmcnt(7) lgkmcnt(7)
	v_mfma_f32_32x32x16_bf16 v[64:79], v[64:67], v[80:83], 0
	s_waitcnt vmcnt(6) lgkmcnt(6)
	v_mfma_f32_32x32x16_bf16 v[64:79], v[140:143], v[84:87], v[64:79]
	s_waitcnt vmcnt(5) lgkmcnt(5)
	v_mfma_f32_32x32x16_bf16 v[64:79], v[160:163], v[88:91], v[64:79]
	ds_read_b128 v[140:143], v157
	ds_read_b128 v[160:163], v157 offset:32
	s_waitcnt lgkmcnt(1)
	v_fmamk_f32 v141, v141, 0x3fb8aa3b, v154
	v_fmamk_f32 v140, v140, 0x3fb8aa3b, v154
	v_exp_f32_e32 v141, v141
	s_waitcnt vmcnt(4)
	v_mfma_f32_32x32x16_bf16 v[64:79], v[164:167], v[92:95], v[64:79]
	v_exp_f32_e32 v140, v140
	v_cndmask_b32_e32 v141, 0, v141, vcc
	v_cmp_le_u32_e32 vcc, v158, v120
	s_nop 1
	v_cndmask_b32_e32 v140, 0, v140, vcc
	s_waitcnt vmcnt(3)
	v_mfma_f32_32x32x16_bf16 v[64:79], v[168:171], v[96:99], v[64:79]
	s_waitcnt vmcnt(2)
	v_mfma_f32_32x32x16_bf16 v[64:79], v[172:175], v[100:103], v[64:79]
	s_waitcnt vmcnt(1)
	v_mfma_f32_32x32x16_bf16 v[64:79], v[176:179], v[104:107], v[64:79]
	s_waitcnt vmcnt(0)
	v_mfma_f32_32x32x16_bf16 v[64:79], v[180:183], v[108:111], v[64:79]
	v_lshl_add_u64 v[190:191], s[90:91], 0, v[136:137]
	s_mov_b64 s[72:73], 0x12900000
	v_lshl_add_u64 v[198:199], v[190:191], 0, s[72:73]
	s_mov_b64 s[72:73], 0x12b10000
	v_lshl_add_u64 v[218:219], v[190:191], 0, s[72:73]
	s_mov_b64 s[72:73], 0x12d20000
	v_lshl_add_u64 v[246:247], v[190:191], 0, s[72:73]
	s_mov_b64 s[72:73], 0x12f30000
	v_lshl_add_u64 v[248:249], v[190:191], 0, s[72:73]
	global_load_dwordx2 v[166:167], v[198:199], off
	global_load_dwordx2 v[168:169], v[198:199], off offset:16
	global_load_dwordx2 v[170:171], v[218:219], off
	global_load_dwordx2 v[172:173], v[218:219], off offset:16
	global_load_dwordx2 v[174:175], v[246:247], off
	global_load_dwordx2 v[176:177], v[246:247], off offset:16
	global_load_dwordx2 v[178:179], v[248:249], off
	global_load_dwordx2 v[180:181], v[248:249], off offset:16
	global_load_dwordx2 v[182:183], v[198:199], off offset:32
	global_load_dwordx2 v[184:185], v[198:199], off offset:48
	global_load_dwordx2 v[186:187], v[218:219], off offset:32
	global_load_dwordx2 v[188:189], v[218:219], off offset:48
	global_load_dwordx2 v[194:195], v[246:247], off offset:32
	global_load_dwordx2 v[196:197], v[246:247], off offset:48
	global_load_dwordx2 v[214:215], v[248:249], off offset:32
	global_load_dwordx2 v[216:217], v[248:249], off offset:48
	v_pk_mul_f32 v[140:141], v[64:65], v[140:141]
	v_fmamk_f32 v65, v143, 0x3fb8aa3b, v154
	v_add_f32_e32 v64, v123, v140
	v_add_f32_e32 v123, v141, v64
	v_fmamk_f32 v64, v142, 0x3fb8aa3b, v154
	v_exp_f32_e32 v65, v65
	v_exp_f32_e32 v64, v64
	v_or_b32_e32 v142, 3, v158
	v_or_b32_e32 v143, 2, v158
	v_cmp_le_u32_e32 vcc, v142, v113
	s_nop 1
	v_cndmask_b32_e32 v65, 0, v65, vcc
	v_cmp_le_u32_e32 vcc, v143, v120
	s_nop 1
	v_cndmask_b32_e32 v64, 0, v64, vcc
	v_pk_mul_f32 v[142:143], v[66:67], v[64:65]
	v_cmp_le_i32_e32 vcc, v158, v155
	v_add_f32_e32 v64, v142, v123
	v_add_f32_e32 v123, v143, v64
	s_waitcnt lgkmcnt(0)
	v_fmamk_f32 v64, v160, 0x3fb8aa3b, v154
	v_exp_f32_e32 v64, v64
	v_fmamk_f32 v65, v162, 0x3fb8aa3b, v154
	v_exp_f32_e32 v65, v65
	v_mov_b32_e32 v66, v69
	v_cndmask_b32_e32 v64, 0, v64, vcc
	v_mul_f32_e32 v159, v68, v64
	v_fmac_f32_e32 v123, v68, v64
	v_fmamk_f32 v64, v161, 0x3fb8aa3b, v154
	v_exp_f32_e32 v64, v64
	v_cmp_le_i32_e32 vcc, v158, v115
	v_mov_b32_e32 v67, v70
	v_mov_b32_e32 v70, v71
	v_cndmask_b32_e32 v65, 0, v65, vcc
	v_cmp_le_i32_e32 vcc, v158, v126
	v_mov_b32_e32 v71, v72
	s_nop 0
	v_cndmask_b32_e32 v64, 0, v64, vcc
	v_pk_mul_f32 v[144:145], v[66:67], v[64:65]
	v_cmp_le_i32_e32 vcc, v158, v117
	v_add_f32_e32 v64, v144, v123
	v_add_f32_e32 v123, v145, v64
	v_fmamk_f32 v64, v163, 0x3fb8aa3b, v154
	v_exp_f32_e32 v68, v64
	ds_read_b128 v[64:67], v157 offset:64
	ds_read_b128 v[160:163], v157 offset:96
	v_add_u32_e32 v157, 0x80, v157
	s_waitcnt lgkmcnt(1)
	v_fmamk_f32 v64, v64, 0x3fb8aa3b, v154
	v_exp_f32_e32 v64, v64
	s_nop 0
	v_cndmask_b32_e32 v69, 0, v64, vcc
	v_cmp_le_i32_e32 vcc, v158, v128
	s_nop 1
	v_cndmask_b32_e32 v68, 0, v68, vcc
	v_pk_mul_f32 v[68:69], v[70:71], v[68:69]
	v_cmp_le_i32_e32 vcc, v158, v119
	v_add_f32_e32 v64, v68, v123
	v_add_f32_e32 v72, v69, v64
	v_fmamk_f32 v64, v65, 0x3fb8aa3b, v154
	v_fmamk_f32 v65, v66, 0x3fb8aa3b, v154
	v_exp_f32_e32 v65, v65
	v_exp_f32_e32 v64, v64
	v_mov_b32_e32 v70, v73
	v_mov_b32_e32 v71, v74
	v_cndmask_b32_e32 v65, 0, v65, vcc
	v_cmp_le_i32_e32 vcc, v158, v130
	v_mov_b32_e32 v66, v75
	s_waitcnt lgkmcnt(0)
; #define LAS __attribute__((address_space(3)))
; __device__ __forceinline__ unsigned pk2(float lo, float hi) { f32x2_t v = {lo, hi}; bf16x2_t b = __builtin_convertvector(v, bf16x2_t); return __builtin_bit_cast(unsigned, b); }
; __device__ __forceinline__ float fexp(float x) { return __builtin_amdgcn_exp2f(x * LOG2E); }
; #define MFMA32(a, b, c) __builtin_amdgcn_mfma_f32_32x32x16_bf16((a), (b), (c), 0, 0, 0)
;     __device__ __forceinline__ bf16* KVt() const { return (bf16*)(ws + WS_KVT); }
; template <bool SAMPLE>
; __device__ __forceinline__ void mout_task(Ctx& C, int l, int unit, int h, int tb, const LAS float* cwl, const LAS float* gainl, LAS float* gsbuf, LAS s16x8* qfl, const bool st) {
;     ...
;         const float e0 = (bt - mt) * LOG2E;
; #pragma unroll
;         for (int i4 = 0; i4 < 4; ++i4) { const f32x4 gs = *(const LAS f32x4*)(gsbuf + 32 * sb + 8 * i4 + 4 * hi);
; #pragma unroll
;             for (int e = 0; e < 4; ++e) { const int sidx = 32 * sb + 8 * i4 + 4 * hi + e;
;                 const float wv = (sidx <= tl) ? __builtin_amdgcn_exp2f(e0 + gs[e] * LOG2E) : 0.f;
;                 S[4 * i4 + e] *= wv; den += S[4 * i4 + e]; } }
; #pragma unroll
;         for (int s2 = 0; s2 < 2; ++s2) { u32x4 w; w.x = pk2(S[8 * s2], S[8 * s2 + 1]); w.y = pk2(S[8 * s2 + 2], S[8 * s2 + 3]); w.z = pk2(S[8 * s2 + 4], S[8 * s2 + 5]); w.w = pk2(S[8 * s2 + 6], S[8 * s2 + 7]);
;             const s16x8 pf = __builtin_bit_cast(s16x8, w);
;             const bf16* vp0 = C.KVt() + (size_t)(R_VM + h * 128 + r) * MT + grow0 + 32 * sb + 16 * s2 + 4 * hi;
; #pragma unroll
;             for (int vb = 0; vb < 4; ++vb) { const bf16* vp = vp0 + (size_t)(32 * vb) * MT;
;                 const u32x2 a = *(const u32x2*)vp, bq = *(const u32x2*)(vp + 8); u32x4 vw; vw.x = a.x; vw.y = a.y; vw.z = bq.x; vw.w = bq.y;
;                 acc[vb] = MFMA32(__builtin_bit_cast(s16x8, vw), pf, acc[vb]); } }
;     }
;     den += __shfl_xor(den, 32);
;     den += winter * qn;
;     const float inv = __builtin_amdgcn_rcpf(fmaxf(fabsf(den), fexp(-mt)));
;     float ss = 0.f;
; #pragma unroll
;     for (int vb = 0; vb < 4; ++vb)
; #pragma unroll
;         for (int i = 0; i < 16; ++i) { acc[vb][i] *= inv; ss += acc[vb][i] * acc[vb][i]; }
;     ss += __shfl_xor(ss, 32);
;     const float rn = rsqrtf(ss * (1.f / 128.f) + EPS);
	v_fmamk_f32 v73, v163, 0x3fb8aa3b, v154
	v_cndmask_b32_e32 v64, 0, v64, vcc
	v_pk_mul_f32 v[70:71], v[70:71], v[64:65]
	v_fmamk_f32 v65, v160, 0x3fb8aa3b, v154
	v_add_f32_e32 v64, v70, v72
	v_add_f32_e32 v72, v71, v64
	v_fmamk_f32 v64, v67, 0x3fb8aa3b, v154
	v_exp_f32_e32 v65, v65
	v_exp_f32_e32 v64, v64
	v_cmp_le_i32_e32 vcc, v158, v121
	v_mov_b32_e32 v67, v76
	v_exp_f32_e32 v73, v73
	v_cndmask_b32_e32 v65, 0, v65, vcc
	v_cmp_le_i32_e32 vcc, v158, v132
	v_mov_b32_e32 v74, v77
	v_mov_b32_e32 v75, v78
	v_cndmask_b32_e32 v64, 0, v64, vcc
	v_pk_mul_f32 v[64:65], v[66:67], v[64:65]
	v_fmamk_f32 v67, v162, 0x3fb8aa3b, v154
	v_fmamk_f32 v66, v161, 0x3fb8aa3b, v154
	v_exp_f32_e32 v67, v67
	v_exp_f32_e32 v66, v66
	v_cmp_le_i32_e32 vcc, v158, v125
	v_lshl_add_u64 v[160:161], s[90:91], 0, v[136:137]
	v_cvt_pk_bf16_f32 v76, v159, v144
	v_cndmask_b32_e32 v67, 0, v67, vcc
	v_cmp_le_i32_e32 vcc, v158, v134
	v_add_f32_e32 v72, v64, v72
	v_lshl_add_u64 v[136:137], v[136:137], 0, 64
	v_cndmask_b32_e32 v66, 0, v66, vcc
	v_cmp_le_i32_e32 vcc, v158, v156
	v_pk_mul_f32 v[66:67], v[74:75], v[66:67]
	v_cvt_pk_bf16_f32 v74, v140, v141
	v_cndmask_b32_e32 v73, 0, v73, vcc
	v_pk_mov_b32 v[140:141], v[144:145], v[68:69] op_sel:[1,0]
	v_add_co_u32_e32 v144, vcc, s37, v160
	v_cvt_pk_bf16_f32 v75, v142, v143
	s_nop 0
	v_addc_co_u32_e32 v145, vcc, 0, v161, vcc
	v_cvt_pk_bf16_f32 v77, v140, v141
	s_mov_b32 s37, 0x12b10000
	v_add_co_u32_e32 v162, vcc, s37, v160
	s_mov_b32 s37, 0x12d20000
	s_nop 0
	v_addc_co_u32_e32 v163, vcc, 0, v161, vcc
	v_add_co_u32_e32 v164, vcc, s37, v160
	s_mov_b32 s37, 0x12f30000
	s_nop 0
	v_addc_co_u32_e32 v165, vcc, 0, v161, vcc
	v_add_co_u32_e32 v160, vcc, s37, v160
	v_pk_mov_b32 v[68:69], v[68:69], v[70:71] op_sel:[1,0]
	s_nop 0
	v_addc_co_u32_e32 v161, vcc, 0, v161, vcc
	v_pk_mov_b32 v[70:71], v[70:71], v[64:65] op_sel:[1,0]
	v_mul_f32_e32 v78, v79, v73
	v_cvt_pk_bf16_f32 v68, v68, v69
	v_cvt_pk_bf16_f32 v69, v70, v71
	v_pk_mov_b32 v[70:71], v[64:65], v[66:67] op_sel:[1,0]
	v_add_f32_e32 v64, v65, v72
	v_cvt_pk_bf16_f32 v70, v70, v71
	s_waitcnt vmcnt(14)
	v_mfma_f32_32x32x16_bf16 v[0:15], v[166:169], v[74:77], v[0:15]
	v_cvt_pk_bf16_f32 v71, v67, v78
	v_add_f32_e32 v64, v66, v64
	v_add_f32_e32 v123, v67, v64
	v_fmac_f32_e32 v123, v79, v73
	v_add_u32_e32 v158, 32, v158
	s_waitcnt vmcnt(12)
	v_mfma_f32_32x32x16_bf16 v[16:31], v[170:173], v[74:77], v[16:31]
	s_waitcnt vmcnt(10)
	v_mfma_f32_32x32x16_bf16 v[32:47], v[174:177], v[74:77], v[32:47]
	s_waitcnt vmcnt(8)
	v_mfma_f32_32x32x16_bf16 v[48:63], v[178:181], v[74:77], v[48:63]
	s_waitcnt vmcnt(6)
	v_mfma_f32_32x32x16_bf16 v[0:15], v[182:185], v[68:71], v[0:15]
	s_waitcnt vmcnt(4)
	v_mfma_f32_32x32x16_bf16 v[16:31], v[186:189], v[68:71], v[16:31]
	s_waitcnt vmcnt(2)
	v_mfma_f32_32x32x16_bf16 v[32:47], v[194:197], v[68:71], v[32:47]
	s_waitcnt vmcnt(0)
	v_mfma_f32_32x32x16_bf16 v[48:63], v[214:217], v[68:71], v[48:63]
	s_cbranch_scc1 .LBB0_909
	v_mov_b32_e32 v66, v112
	s_mov_b64 s[18:19], 0x1000
	v_and_or_b32 v64, v66, 31, s39
	v_or_b32_e32 v67, s20, v64
	v_mov_b64_e32 v[64:65], s[90:91]
	v_mad_u64_u32 v[64:65], s[72:73], v67, s61, v[64:65]
	v_ashrrev_i32_e32 v66, 3, v66
	v_mad_i32_i24 v65, s21, v221, v65
	v_and_b32_e32 v66, -4, v66
	v_lshl_add_u64 v[64:65], s[22:23], 1, v[64:65]
	v_ashrrev_i32_e32 v67, 31, v66
	v_lshl_add_u64 v[64:65], v[66:67], 1, v[64:65]
	v_add_co_u32_e32 v76, vcc, s60, v64
	v_lshl_add_u64 v[72:73], v[64:65], 0, s[18:19]
	s_nop 0
	v_addc_co_u32_e32 v77, vcc, 0, v65, vcc
	global_load_dwordx2 v[78:79], v[76:77], off
	global_load_dwordx2 v[80:81], v[72:73], off offset:16
	global_load_dwordx2 v[86:87], v[72:73], off offset:32
	global_load_dwordx2 v[82:83], v[72:73], off offset:48
	v_xor_b32_e32 v64, 32, v220
	v_add_u32_e32 v65, 64, v133
	v_cmp_lt_i32_e32 vcc, v64, v65
	v_mul_f32_e32 v67, 0xbfb8aa3b, v153
	v_exp_f32_e32 v67, v67
	v_cndmask_b32_e32 v64, v220, v64, vcc
	v_lshlrev_b32_e32 v125, 2, v64
	ds_bpermute_b32 v64, v125, v122
	ds_bpermute_b32 v65, v125, v123
	s_lshl_b32 s20, s22, 2
	s_add_i32 s20, s20, 0
	v_lshl_add_u32 v103, v66, 2, s20
	s_cmp_eq_u32 s47, 0
	s_waitcnt lgkmcnt(0)
	v_pk_add_f32 v[64:65], v[122:123], v[64:65]
	s_cselect_b64 s[20:21], -1, 0
	v_fmac_f32_e32 v65, v124, v64
	v_max_f32_e64 v64, |v65|, v67
	v_rcp_f32_e32 v102, v64
	ds_read_b128 v[68:71], v103 offset:20480
	ds_read_b128 v[64:67], v103 offset:20512
	ds_read_b128 v[136:139], v103 offset:20544
	ds_read_b128 v[140:143], v103 offset:20576
	s_cmp_lt_u32 s78, 64
	v_pk_mul_f32 v[94:95], v[0:1], v[102:103] op_sel_hi:[1,0]
	v_pk_mul_f32 v[92:93], v[2:3], v[102:103] op_sel_hi:[1,0]
	v_pk_mul_f32 v[74:75], v[58:59], v[102:103] op_sel_hi:[1,0]
	v_pk_mul_f32 v[58:59], v[62:63], v[102:103] op_sel_hi:[1,0]
	v_pk_mul_f32 v[88:89], v[4:5], v[102:103] op_sel_hi:[1,0]
	v_pk_mul_f32 v[144:145], v[94:95], v[94:95]
	v_pk_mul_f32 v[60:61], v[60:61], v[102:103] op_sel_hi:[1,0]
	v_pk_mul_f32 v[84:85], v[6:7], v[102:103] op_sel_hi:[1,0]
	v_pk_mul_f32 v[122:123], v[92:93], v[92:93]
	v_pk_mul_f32 v[160:161], v[10:11], v[102:103] op_sel_hi:[1,0]
	v_pk_mul_f32 v[164:165], v[8:9], v[102:103] op_sel_hi:[1,0]
	v_pk_mul_f32 v[170:171], v[14:15], v[102:103] op_sel_hi:[1,0]
	v_pk_mul_f32 v[174:175], v[12:13], v[102:103] op_sel_hi:[1,0]
	v_pk_mul_f32 v[90:91], v[18:19], v[102:103] op_sel_hi:[1,0]
	v_pk_mul_f32 v[96:97], v[16:17], v[102:103] op_sel_hi:[1,0]
	v_pk_mul_f32 v[30:31], v[30:31], v[102:103] op_sel_hi:[1,0]
	v_pk_mul_f32 v[28:29], v[28:29], v[102:103] op_sel_hi:[1,0]
	v_pk_mul_f32 v[16:17], v[42:43], v[102:103] op_sel_hi:[1,0]
	v_pk_mul_f32 v[18:19], v[40:41], v[102:103] op_sel_hi:[1,0]
	v_pk_mul_f32 v[12:13], v[46:47], v[102:103] op_sel_hi:[1,0]
	v_pk_mul_f32 v[14:15], v[44:45], v[102:103] op_sel_hi:[1,0]
	v_pk_mul_f32 v[8:9], v[50:51], v[102:103] op_sel_hi:[1,0]
	v_pk_mul_f32 v[10:11], v[48:49], v[102:103] op_sel_hi:[1,0]
	v_pk_mul_f32 v[154:155], v[88:89], v[88:89]
	v_pk_mul_f32 v[120:121], v[84:85], v[84:85]
	v_pk_mul_f32 v[166:167], v[164:165], v[164:165]
	v_pk_mul_f32 v[162:163], v[160:161], v[160:161]
	v_pk_mul_f32 v[176:177], v[174:175], v[174:175]
	v_pk_mul_f32 v[172:173], v[170:171], v[170:171]
	v_pk_mul_f32 v[180:181], v[96:97], v[96:97]
	v_pk_mul_f32 v[178:179], v[90:91], v[90:91]
	v_pk_mul_f32 v[194:195], v[28:29], v[28:29]
	v_pk_mul_f32 v[190:191], v[30:31], v[30:31]
	v_pk_mul_f32 v[40:41], v[18:19], v[18:19]
	v_pk_mul_f32 v[42:43], v[16:17], v[16:17]
	v_pk_mul_f32 v[44:45], v[14:15], v[14:15]
	v_pk_mul_f32 v[46:47], v[12:13], v[12:13]
	v_pk_mul_f32 v[48:49], v[10:11], v[10:11]
	v_pk_mul_f32 v[50:51], v[8:9], v[8:9]
	v_pk_mul_f32 v[100:101], v[74:75], v[74:75]
	v_pk_mul_f32 v[98:99], v[60:61], v[60:61]
	v_pk_mul_f32 v[6:7], v[58:59], v[58:59]
	s_cselect_b64 s[22:23], -1, 0
	s_and_b64 s[20:21], s[20:21], s[22:23]
	s_cmpk_lt_i32 s2, 0x80
	s_cselect_b64 s[22:23], -1, 0
	s_and_b64 s[20:21], s[20:21], s[22:23]
	v_readlane_b32 s74, v255, 43
	v_readlane_b32 s39, v255, 42
	v_readlane_b32 s75, v255, 44
	s_movk_i32 s80, 0x1ff
	s_movk_i32 s37, 0xffc2
	s_waitcnt vmcnt(3)
; #define LAS __attribute__((address_space(3)))
; __device__ __forceinline__ float bflo(unsigned w) { return __uint_as_float(w << 16); }
; __device__ __forceinline__ float bfhi(unsigned w) { return __uint_as_float(w & 0xffff0000u); }
; __device__ __forceinline__ float fexp(float x) { return __builtin_amdgcn_exp2f(x * LOG2E); }
; __device__ __forceinline__ float sigmoidf_(float x) { return __builtin_amdgcn_rcpf(1.f + fexp(-x)); }
;     __device__ __forceinline__ bf16* U() const { return (bf16*)(ws + WS_U); }
; template <bool SAMPLE>
; __device__ __forceinline__ void mout_task(Ctx& C, int l, int unit, int h, int tb, const LAS float* cwl, const LAS float* gainl, LAS float* gsbuf, LAS s16x8* qfl, const bool st) {
;     ...
;     den += __shfl_xor(den, 32);
;     den += winter * qn;
;     const float inv = __builtin_amdgcn_rcpf(fmaxf(fabsf(den), fexp(-mt)));
;     float ss = 0.f;
; #pragma unroll
;     for (int vb = 0; vb < 4; ++vb)
; #pragma unroll
;         for (int i = 0; i < 16; ++i) { acc[vb][i] *= inv; ss += acc[vb][i] * acc[vb][i]; }
;     ss += __shfl_xor(ss, 32);
;     const float rn = rsqrtf(ss * (1.f / 128.f) + EPS);
;     int lane2 = lane; asm volatile("" : "+v"(lane2));
;     const int hi2 = lane2 >> 5;
;     bf16* orow = C.U() + (grow0 + 32 * tb + (lane2 & 31)) * UW + C_OM + h * 128;
; #pragma unroll
;     for (int vb = 0; vb < 4; ++vb)
; #pragma unroll
;         for (int i4 = 0; i4 < 4; ++i4) { const int v0 = 32 * vb + 8 * i4 + 4 * hi2;
;             const u32x2 ow = *(const u32x2*)(orow + v0); const f32x4 gn = *(const LAS f32x4*)(gainl + h * 128 + v0);
;             const float y0 = acc[vb][4 * i4] * rn * gn[0] * sigmoidf_(bflo(ow.x)), y1 = acc[vb][4 * i4 + 1] * rn * gn[1] * sigmoidf_(bfhi(ow.x));
;             const float y2 = acc[vb][4 * i4 + 2] * rn * gn[2] * sigmoidf_(bflo(ow.y)), y3 = acc[vb][4 * i4 + 3] * rn * gn[3] * sigmoidf_(bfhi(ow.y));
	v_and_b32_e32 v1, 0xffff0000, v78
	v_lshlrev_b32_e32 v0, 16, v78
	s_waitcnt vmcnt(1)
	v_lshlrev_b32_e32 v78, 16, v86
	v_mul_f32_e32 v1, 0xbfb8aa3b, v1
	v_lshlrev_b32_e32 v2, 16, v79
	v_mul_f32_e32 v0, 0xbfb8aa3b, v0
	v_mul_f32_e32 v78, 0xbfb8aa3b, v78
	v_exp_f32_e32 v1, v1
	v_mul_f32_e32 v2, 0xbfb8aa3b, v2
	v_exp_f32_e32 v0, v0
	v_exp_f32_e32 v78, v78
	v_exp_f32_e32 v2, v2
	v_add_f32_e32 v1, 1.0, v1
	v_and_b32_e32 v3, 0xffff0000, v79
	v_and_b32_e32 v79, 0xffff0000, v86
	v_add_f32_e32 v0, 1.0, v0
	v_rcp_f32_e32 v111, v1
	v_add_f32_e32 v1, 1.0, v78
	v_add_f32_e32 v2, 1.0, v2
	v_rcp_f32_e32 v110, v0
	v_mul_f32_e32 v0, 0xbfb8aa3b, v79
	v_rcp_f32_e32 v156, v1
	v_lshlrev_b32_e32 v1, 16, v87
	v_rcp_f32_e32 v108, v2
	v_exp_f32_e32 v0, v0
	v_mul_f32_e32 v1, 0xbfb8aa3b, v1
	v_and_b32_e32 v2, 0xffff0000, v87
	v_exp_f32_e32 v1, v1
	v_mul_f32_e32 v2, 0xbfb8aa3b, v2
	v_exp_f32_e32 v2, v2
	v_add_f32_e32 v0, 1.0, v0
	v_rcp_f32_e32 v157, v0
	v_add_f32_e32 v0, 1.0, v1
	v_rcp_f32_e32 v158, v0
	v_add_f32_e32 v0, 1.0, v2
	v_rcp_f32_e32 v159, v0
	s_waitcnt vmcnt(0)
	v_lshlrev_b32_e32 v0, 16, v82
	v_mul_f32_e32 v0, 0xbfb8aa3b, v0
	v_and_b32_e32 v1, 0xffff0000, v82
	v_exp_f32_e32 v0, v0
	v_mul_f32_e32 v1, 0xbfb8aa3b, v1
	v_lshlrev_b32_e32 v4, 16, v80
	v_and_b32_e32 v5, 0xffff0000, v80
	v_lshlrev_b32_e32 v62, 16, v81
	v_and_b32_e32 v63, 0xffff0000, v81
	v_exp_f32_e32 v1, v1
	v_mul_f32_e32 v3, 0xbfb8aa3b, v3
	v_mul_f32_e32 v4, 0xbfb8aa3b, v4
	v_mul_f32_e32 v5, 0xbfb8aa3b, v5
	v_mul_f32_e32 v62, 0xbfb8aa3b, v62
	v_mul_f32_e32 v63, 0xbfb8aa3b, v63
	v_exp_f32_e32 v3, v3
	v_exp_f32_e32 v4, v4
	v_exp_f32_e32 v5, v5
	v_exp_f32_e32 v62, v62
	v_exp_f32_e32 v63, v63
	v_add_f32_e32 v0, 1.0, v0
	v_rcp_f32_e32 v168, v0
	v_add_f32_e32 v0, 1.0, v1
	v_rcp_f32_e32 v169, v0
	v_lshlrev_b32_e32 v0, 16, v83
	v_add_f32_e32 v3, 1.0, v3
	v_add_f32_e32 v4, 1.0, v4
	v_add_f32_e32 v5, 1.0, v5
	v_add_f32_e32 v62, 1.0, v62
	v_add_f32_e32 v63, 1.0, v63
	v_mul_f32_e32 v0, 0xbfb8aa3b, v0
	v_rcp_f32_e32 v109, v3
	v_rcp_f32_e32 v106, v4
	v_rcp_f32_e32 v107, v5
	v_rcp_f32_e32 v104, v62
	v_rcp_f32_e32 v105, v63
	v_exp_f32_e32 v82, v0
	v_pk_mul_f32 v[80:81], v[22:23], v[102:103] op_sel_hi:[1,0]
	v_pk_mul_f32 v[86:87], v[20:21], v[102:103] op_sel_hi:[1,0]
	v_pk_mul_f32 v[62:63], v[26:27], v[102:103] op_sel_hi:[1,0]
	v_pk_mul_f32 v[78:79], v[24:25], v[102:103] op_sel_hi:[1,0]
	v_pk_mul_f32 v[24:25], v[34:35], v[102:103] op_sel_hi:[1,0]
	v_pk_mul_f32 v[26:27], v[32:33], v[102:103] op_sel_hi:[1,0]
	v_pk_mul_f32 v[20:21], v[38:39], v[102:103] op_sel_hi:[1,0]
	v_pk_mul_f32 v[22:23], v[36:37], v[102:103] op_sel_hi:[1,0]
	v_pk_mul_f32 v[2:3], v[54:55], v[102:103] op_sel_hi:[1,0]
	v_pk_mul_f32 v[4:5], v[52:53], v[102:103] op_sel_hi:[1,0]
	v_pk_mul_f32 v[0:1], v[56:57], v[102:103] op_sel_hi:[1,0]
	v_add_f32_e32 v102, v144, v145
	v_add_f32_e32 v102, v122, v102
	v_add_f32_e32 v102, v123, v102
	v_add_f32_e32 v102, v154, v102
	v_add_f32_e32 v102, v155, v102
	v_add_f32_e32 v102, v120, v102
	v_add_f32_e32 v102, v121, v102
	v_add_f32_e32 v102, v166, v102
	v_add_f32_e32 v102, v167, v102
	v_add_f32_e32 v102, v162, v102
	v_add_f32_e32 v102, v163, v102
	v_add_f32_e32 v102, v176, v102
	v_add_f32_e32 v102, v177, v102
	v_add_f32_e32 v102, v172, v102
	v_add_f32_e32 v102, v173, v102
	v_add_f32_e32 v102, v180, v102
	v_add_f32_e32 v102, v181, v102
	v_add_f32_e32 v102, v178, v102
	v_pk_mul_f32 v[184:185], v[86:87], v[86:87]
	v_add_f32_e32 v102, v179, v102
	v_add_f32_e32 v102, v184, v102
	v_pk_mul_f32 v[182:183], v[80:81], v[80:81]
	v_add_f32_e32 v102, v185, v102
	v_add_f32_e32 v102, v182, v102
	v_pk_mul_f32 v[188:189], v[78:79], v[78:79]
	v_add_f32_e32 v102, v183, v102
	v_add_f32_e32 v102, v188, v102
	v_pk_mul_f32 v[186:187], v[62:63], v[62:63]
	v_add_f32_e32 v102, v189, v102
	v_add_f32_e32 v102, v186, v102
	v_add_f32_e32 v102, v187, v102
	v_add_f32_e32 v102, v194, v102
	v_add_f32_e32 v102, v195, v102
	v_add_f32_e32 v102, v190, v102
	v_pk_mul_f32 v[32:33], v[26:27], v[26:27]
	v_add_f32_e32 v102, v191, v102
	v_add_f32_e32 v32, v32, v102
	v_pk_mul_f32 v[34:35], v[24:25], v[24:25]
	v_add_f32_e32 v32, v33, v32
	v_add_f32_e32 v32, v34, v32
	v_pk_mul_f32 v[36:37], v[22:23], v[22:23]
	v_add_f32_e32 v32, v35, v32
	v_add_f32_e32 v32, v36, v32
	v_pk_mul_f32 v[38:39], v[20:21], v[20:21]
	v_add_f32_e32 v32, v37, v32
	v_add_f32_e32 v32, v38, v32
	v_add_f32_e32 v32, v39, v32
	v_add_f32_e32 v32, v40, v32
	v_add_f32_e32 v32, v41, v32
	v_add_f32_e32 v32, v42, v32
	v_add_f32_e32 v32, v43, v32
	v_add_f32_e32 v32, v44, v32
	v_add_f32_e32 v32, v45, v32
	v_add_f32_e32 v32, v46, v32
	v_add_f32_e32 v32, v47, v32
	v_add_f32_e32 v32, v48, v32
	v_add_f32_e32 v32, v49, v32
	v_add_f32_e32 v32, v50, v32
	v_pk_mul_f32 v[52:53], v[4:5], v[4:5]
	v_add_f32_e32 v32, v51, v32
	v_add_f32_e32 v32, v52, v32
	v_pk_mul_f32 v[54:55], v[2:3], v[2:3]
	v_add_f32_e32 v32, v53, v32
	v_add_f32_e32 v32, v54, v32
	v_pk_mul_f32 v[56:57], v[0:1], v[0:1]
	v_add_f32_e32 v32, v55, v32
	v_add_f32_e32 v32, v56, v32
	v_add_f32_e32 v32, v57, v32
	v_add_f32_e32 v32, v100, v32
	v_add_f32_e32 v32, v101, v32
	v_add_f32_e32 v32, v98, v32
	v_add_f32_e32 v32, v99, v32
	v_add_f32_e32 v6, v6, v32
	v_add_f32_e32 v6, v7, v6
	ds_bpermute_b32 v7, v125, v6
	v_mov_b32_e32 v34, 0x358637bd
	v_and_b32_e32 v33, 0xffff0000, v83
	v_mul_f32_e32 v33, 0xbfb8aa3b, v33
	v_exp_f32_e32 v33, v33
	s_waitcnt lgkmcnt(0)
; #define LAS __attribute__((address_space(3)))
; __device__ __forceinline__ unsigned pk2(float lo, float hi) { f32x2_t v = {lo, hi}; bf16x2_t b = __builtin_convertvector(v, bf16x2_t); return __builtin_bit_cast(unsigned, b); }
; __device__ __forceinline__ float bflo(unsigned w) { return __uint_as_float(w << 16); }
; __device__ __forceinline__ float bfhi(unsigned w) { return __uint_as_float(w & 0xffff0000u); }
; __device__ __forceinline__ float sigmoidf_(float x) { return __builtin_amdgcn_rcpf(1.f + fexp(-x)); }
;     __device__ __forceinline__ bf16* U() const { return (bf16*)(ws + WS_U); }
; template <bool SAMPLE>
; __device__ __forceinline__ void mout_task(Ctx& C, int l, int unit, int h, int tb, const LAS float* cwl, const LAS float* gainl, LAS float* gsbuf, LAS s16x8* qfl, const bool st) {
;     ...
;     ss += __shfl_xor(ss, 32);
;     const float rn = rsqrtf(ss * (1.f / 128.f) + EPS);
;     int lane2 = lane; asm volatile("" : "+v"(lane2));
;     const int hi2 = lane2 >> 5;
;     bf16* orow = C.U() + (grow0 + 32 * tb + (lane2 & 31)) * UW + C_OM + h * 128;
; #pragma unroll
;     for (int vb = 0; vb < 4; ++vb)
; #pragma unroll
;         for (int i4 = 0; i4 < 4; ++i4) { const int v0 = 32 * vb + 8 * i4 + 4 * hi2;
;             const u32x2 ow = *(const u32x2*)(orow + v0); const f32x4 gn = *(const LAS f32x4*)(gainl + h * 128 + v0);
;             const float y0 = acc[vb][4 * i4] * rn * gn[0] * sigmoidf_(bflo(ow.x)), y1 = acc[vb][4 * i4 + 1] * rn * gn[1] * sigmoidf_(bfhi(ow.x));
;             const float y2 = acc[vb][4 * i4 + 2] * rn * gn[2] * sigmoidf_(bflo(ow.y)), y3 = acc[vb][4 * i4 + 3] * rn * gn[3] * sigmoidf_(bfhi(ow.y));
;             u32x2 w; w.x = pk2(y0, y1); w.y = pk2(y2, y3); if (st) *(u32x2*)(orow + v0) = w; if (i4 == 3) asm volatile("" ::: "memory"); }
	v_add_f32_e32 v6, v6, v7
	v_fmamk_f32 v6, v6, 0x3c000000, v34
	v_mul_f32_e32 v7, 0x4b800000, v6
	v_cmp_gt_f32_e32 vcc, s65, v6
	v_add_f32_e32 v32, 1.0, v82
	v_rcp_f32_e32 v32, v32
	v_cndmask_b32_e32 v6, v6, v7, vcc
	v_rsq_f32_e32 v6, v6
	v_add_f32_e32 v7, 1.0, v33
	v_rcp_f32_e32 v33, v7
	v_mul_f32_e32 v7, 0x45800000, v6
	v_cndmask_b32_e32 v6, v6, v7, vcc
	v_pk_mul_f32 v[34:35], v[94:95], v[6:7] op_sel_hi:[1,0]
	v_pk_mul_f32 v[36:37], v[92:93], v[6:7] op_sel_hi:[1,0]
	v_pk_mul_f32 v[34:35], v[68:69], v[34:35]
	v_pk_mul_f32 v[36:37], v[70:71], v[36:37]
	v_pk_mul_f32 v[34:35], v[110:111], v[34:35]
	v_pk_mul_f32 v[36:37], v[108:109], v[36:37]
	v_cvt_pk_bf16_f32 v34, v34, v35
	v_cvt_pk_bf16_f32 v35, v36, v37
	global_store_dwordx2 v[76:77], v[34:35], off
	v_pk_mul_f32 v[34:35], v[88:89], v[6:7] op_sel_hi:[1,0]
	v_pk_mul_f32 v[36:37], v[84:85], v[6:7] op_sel_hi:[1,0]
	v_pk_mul_f32 v[34:35], v[64:65], v[34:35]
	v_pk_mul_f32 v[36:37], v[66:67], v[36:37]
	v_pk_mul_f32 v[34:35], v[106:107], v[34:35]
	v_pk_mul_f32 v[36:37], v[104:105], v[36:37]
	v_cvt_pk_bf16_f32 v34, v34, v35
	v_cvt_pk_bf16_f32 v35, v36, v37
	global_store_dwordx2 v[72:73], v[34:35], off offset:16
	v_pk_mul_f32 v[34:35], v[164:165], v[6:7] op_sel_hi:[1,0]
	v_pk_mul_f32 v[36:37], v[160:161], v[6:7] op_sel_hi:[1,0]
	v_pk_mul_f32 v[34:35], v[136:137], v[34:35]
	v_pk_mul_f32 v[36:37], v[138:139], v[36:37]
	v_pk_mul_f32 v[34:35], v[156:157], v[34:35]
	v_pk_mul_f32 v[36:37], v[158:159], v[36:37]
	v_cvt_pk_bf16_f32 v34, v34, v35
	v_cvt_pk_bf16_f32 v35, v36, v37
	global_store_dwordx2 v[72:73], v[34:35], off offset:32
	v_pk_mul_f32 v[34:35], v[174:175], v[6:7] op_sel_hi:[1,0]
	v_pk_mul_f32 v[36:37], v[170:171], v[6:7] op_sel_hi:[1,0]
	v_pk_mul_f32 v[34:35], v[140:141], v[34:35]
	v_pk_mul_f32 v[36:37], v[142:143], v[36:37]
	v_pk_mul_f32 v[34:35], v[168:169], v[34:35]
	v_pk_mul_f32 v[32:33], v[32:33], v[36:37]
	v_cvt_pk_bf16_f32 v34, v34, v35
	v_cvt_pk_bf16_f32 v35, v32, v33
	global_store_dwordx2 v[72:73], v[34:35], off offset:48
	global_load_dwordx2 v[40:41], v[72:73], off offset:64
	global_load_dwordx2 v[42:43], v[72:73], off offset:80
	global_load_dwordx2 v[44:45], v[72:73], off offset:96
	global_load_dwordx2 v[46:47], v[72:73], off offset:112
	ds_read_b128 v[32:35], v103 offset:20608
	ds_read_b128 v[36:39], v103 offset:20640
	s_andn2_b64 vcc, exec, s[20:21]
	s_waitcnt vmcnt(3)
	v_lshlrev_b32_e32 v7, 16, v40
	v_mul_f32_e32 v7, 0xbfb8aa3b, v7
	v_exp_f32_e32 v7, v7
	v_and_b32_e32 v40, 0xffff0000, v40
	v_mul_f32_e32 v40, 0xbfb8aa3b, v40
	v_exp_f32_e32 v50, v40
	v_add_f32_e32 v7, 1.0, v7
	v_pk_mul_f32 v[48:49], v[96:97], v[6:7] op_sel_hi:[1,0]
	v_rcp_f32_e32 v40, v7
	s_waitcnt lgkmcnt(1)
	v_pk_mul_f32 v[32:33], v[32:33], v[48:49]
	v_lshlrev_b32_e32 v48, 16, v41
	v_mul_f32_e32 v48, 0xbfb8aa3b, v48
	v_and_b32_e32 v41, 0xffff0000, v41
	v_exp_f32_e32 v48, v48
	v_mul_f32_e32 v41, 0xbfb8aa3b, v41
	v_exp_f32_e32 v49, v41
	v_add_f32_e32 v7, 1.0, v50
	v_rcp_f32_e32 v41, v7
	v_add_f32_e32 v7, 1.0, v48
	v_rcp_f32_e32 v48, v7
	v_add_f32_e32 v7, 1.0, v49
	v_rcp_f32_e32 v49, v7
	v_pk_mul_f32 v[32:33], v[40:41], v[32:33]
	v_pk_mul_f32 v[40:41], v[90:91], v[6:7] op_sel_hi:[1,0]
	s_waitcnt vmcnt(2)
	v_lshlrev_b32_e32 v7, 16, v42
	v_pk_mul_f32 v[34:35], v[34:35], v[40:41]
	v_cvt_pk_bf16_f32 v32, v32, v33
	v_pk_mul_f32 v[34:35], v[48:49], v[34:35]
	v_mul_f32_e32 v7, 0xbfb8aa3b, v7
	v_cvt_pk_bf16_f32 v33, v34, v35
	global_store_dwordx2 v[72:73], v[32:33], off offset:64
	v_and_b32_e32 v32, 0xffff0000, v42
	v_exp_f32_e32 v7, v7
	v_mul_f32_e32 v32, 0xbfb8aa3b, v32
	v_exp_f32_e32 v33, v32
	s_waitcnt vmcnt(2)
	v_lshlrev_b32_e32 v41, 16, v45
	v_add_f32_e32 v7, 1.0, v7
	v_rcp_f32_e32 v32, v7
	v_pk_mul_f32 v[34:35], v[86:87], v[6:7] op_sel_hi:[1,0]
	v_add_f32_e32 v7, 1.0, v33
	v_lshlrev_b32_e32 v33, 16, v43
	v_mul_f32_e32 v33, 0xbfb8aa3b, v33
	s_waitcnt lgkmcnt(0)
	v_pk_mul_f32 v[34:35], v[36:37], v[34:35]
	v_exp_f32_e32 v36, v33
	v_and_b32_e32 v33, 0xffff0000, v43
	v_mul_f32_e32 v33, 0xbfb8aa3b, v33
	v_exp_f32_e32 v37, v33
	v_rcp_f32_e32 v33, v7
	v_add_f32_e32 v7, 1.0, v36
	v_rcp_f32_e32 v36, v7
	v_add_f32_e32 v7, 1.0, v37
	v_rcp_f32_e32 v37, v7
	v_pk_mul_f32 v[32:33], v[32:33], v[34:35]
	v_pk_mul_f32 v[34:35], v[80:81], v[6:7] op_sel_hi:[1,0]
	v_lshlrev_b32_e32 v7, 16, v44
	v_mul_f32_e32 v7, 0xbfb8aa3b, v7
	v_exp_f32_e32 v7, v7
	v_pk_mul_f32 v[34:35], v[38:39], v[34:35]
	v_cvt_pk_bf16_f32 v32, v32, v33
	v_pk_mul_f32 v[34:35], v[36:37], v[34:35]
	v_add_f32_e32 v7, 1.0, v7
	v_rcp_f32_e32 v40, v7
	v_and_b32_e32 v7, 0xffff0000, v44
	v_cvt_pk_bf16_f32 v33, v34, v35
	v_mul_f32_e32 v7, 0xbfb8aa3b, v7
	global_store_dwordx2 v[72:73], v[32:33], off offset:80
	ds_read_b128 v[32:35], v103 offset:20672
	ds_read_b128 v[36:39], v103 offset:20704
	v_exp_f32_e32 v7, v7
	v_mul_f32_e32 v41, 0xbfb8aa3b, v41
	v_pk_mul_f32 v[42:43], v[78:79], v[6:7] op_sel_hi:[1,0]
	s_waitcnt lgkmcnt(1)
	v_pk_mul_f32 v[32:33], v[32:33], v[42:43]
	v_exp_f32_e32 v42, v41
	v_and_b32_e32 v41, 0xffff0000, v45
	v_mul_f32_e32 v41, 0xbfb8aa3b, v41
	v_exp_f32_e32 v43, v41
	v_add_f32_e32 v7, 1.0, v7
	v_rcp_f32_e32 v41, v7
	v_add_f32_e32 v7, 1.0, v42
	v_rcp_f32_e32 v42, v7
	v_add_f32_e32 v7, 1.0, v43
	v_rcp_f32_e32 v43, v7
	v_pk_mul_f32 v[32:33], v[40:41], v[32:33]
	v_pk_mul_f32 v[40:41], v[62:63], v[6:7] op_sel_hi:[1,0]
	s_waitcnt vmcnt(2)
; #define LAS __attribute__((address_space(3)))
; __device__ __forceinline__ unsigned pk2(float lo, float hi) { f32x2_t v = {lo, hi}; bf16x2_t b = __builtin_convertvector(v, bf16x2_t); return __builtin_bit_cast(unsigned, b); }
; __device__ __forceinline__ float bflo(unsigned w) { return __uint_as_float(w << 16); }
; __device__ __forceinline__ float bfhi(unsigned w) { return __uint_as_float(w & 0xffff0000u); }
; __device__ __forceinline__ float sigmoidf_(float x) { return __builtin_amdgcn_rcpf(1.f + fexp(-x)); }
; template <bool SAMPLE>
; __device__ __forceinline__ void mout_task(Ctx& C, int l, int unit, int h, int tb, const LAS float* cwl, const LAS float* gainl, LAS float* gsbuf, LAS s16x8* qfl, const bool st) {
;     ...
; #pragma unroll
;     for (int vb = 0; vb < 4; ++vb)
; #pragma unroll
;         for (int i4 = 0; i4 < 4; ++i4) { const int v0 = 32 * vb + 8 * i4 + 4 * hi2;
;             const u32x2 ow = *(const u32x2*)(orow + v0); const f32x4 gn = *(const LAS f32x4*)(gainl + h * 128 + v0);
;             const float y0 = acc[vb][4 * i4] * rn * gn[0] * sigmoidf_(bflo(ow.x)), y1 = acc[vb][4 * i4 + 1] * rn * gn[1] * sigmoidf_(bfhi(ow.x));
;             const float y2 = acc[vb][4 * i4 + 2] * rn * gn[2] * sigmoidf_(bflo(ow.y)), y3 = acc[vb][4 * i4 + 3] * rn * gn[3] * sigmoidf_(bfhi(ow.y));
;             u32x2 w; w.x = pk2(y0, y1); w.y = pk2(y2, y3); if (st) *(u32x2*)(orow + v0) = w; if (i4 == 3) asm volatile("" ::: "memory"); }
	v_lshlrev_b32_e32 v7, 16, v46
	v_pk_mul_f32 v[34:35], v[34:35], v[40:41]
	v_cvt_pk_bf16_f32 v32, v32, v33
	v_pk_mul_f32 v[34:35], v[42:43], v[34:35]
	v_mul_f32_e32 v7, 0xbfb8aa3b, v7
	v_cvt_pk_bf16_f32 v33, v34, v35
	global_store_dwordx2 v[72:73], v[32:33], off offset:96
	v_and_b32_e32 v32, 0xffff0000, v46
	v_exp_f32_e32 v7, v7
	v_mul_f32_e32 v32, 0xbfb8aa3b, v32
	v_exp_f32_e32 v33, v32
	v_add_f32_e32 v7, 1.0, v7
	v_rcp_f32_e32 v32, v7
	v_pk_mul_f32 v[28:29], v[28:29], v[6:7] op_sel_hi:[1,0]
	v_add_f32_e32 v7, 1.0, v33
	v_lshlrev_b32_e32 v33, 16, v47
	v_mul_f32_e32 v33, 0xbfb8aa3b, v33
	v_exp_f32_e32 v34, v33
	v_and_b32_e32 v33, 0xffff0000, v47
	v_mul_f32_e32 v33, 0xbfb8aa3b, v33
	v_exp_f32_e32 v35, v33
	v_rcp_f32_e32 v33, v7
	v_add_f32_e32 v7, 1.0, v34
	v_rcp_f32_e32 v34, v7
	v_add_f32_e32 v7, 1.0, v35
	v_rcp_f32_e32 v35, v7
	v_pk_mul_f32 v[30:31], v[30:31], v[6:7] op_sel_hi:[1,0]
	s_waitcnt lgkmcnt(0)
	v_pk_mul_f32 v[28:29], v[36:37], v[28:29]
	v_pk_mul_f32 v[30:31], v[38:39], v[30:31]
	v_pk_mul_f32 v[28:29], v[32:33], v[28:29]
	v_pk_mul_f32 v[30:31], v[34:35], v[30:31]
	v_cvt_pk_bf16_f32 v28, v28, v29
	v_cvt_pk_bf16_f32 v29, v30, v31
	global_store_dwordx2 v[72:73], v[28:29], off offset:112
	global_load_dwordx2 v[36:37], v[72:73], off offset:128
	global_load_dwordx2 v[38:39], v[72:73], off offset:144
	global_load_dwordx2 v[40:41], v[72:73], off offset:160
	global_load_dwordx2 v[42:43], v[72:73], off offset:176
	ds_read_b128 v[28:31], v103 offset:20736
	ds_read_b128 v[32:35], v103 offset:20768
	s_waitcnt vmcnt(3)
	v_lshlrev_b32_e32 v7, 16, v36
	v_mul_f32_e32 v7, 0xbfb8aa3b, v7
	v_exp_f32_e32 v7, v7
	v_and_b32_e32 v36, 0xffff0000, v36
	v_mul_f32_e32 v36, 0xbfb8aa3b, v36
	v_exp_f32_e32 v44, v36
	v_add_f32_e32 v7, 1.0, v7
	v_pk_mul_f32 v[26:27], v[26:27], v[6:7] op_sel_hi:[1,0]
	v_rcp_f32_e32 v36, v7
	s_waitcnt lgkmcnt(1)
	v_pk_mul_f32 v[26:27], v[28:29], v[26:27]
	v_lshlrev_b32_e32 v28, 16, v37
	v_mul_f32_e32 v28, 0xbfb8aa3b, v28
	v_and_b32_e32 v29, 0xffff0000, v37
	v_exp_f32_e32 v28, v28
	v_mul_f32_e32 v29, 0xbfb8aa3b, v29
	v_exp_f32_e32 v29, v29
	v_add_f32_e32 v7, 1.0, v44
	v_rcp_f32_e32 v37, v7
	v_add_f32_e32 v7, 1.0, v28
	v_rcp_f32_e32 v28, v7
	v_add_f32_e32 v7, 1.0, v29
	v_rcp_f32_e32 v29, v7
	v_pk_mul_f32 v[24:25], v[24:25], v[6:7] op_sel_hi:[1,0]
	v_pk_mul_f32 v[26:27], v[36:37], v[26:27]
	v_pk_mul_f32 v[24:25], v[30:31], v[24:25]
	s_waitcnt vmcnt(2)
	v_lshlrev_b32_e32 v7, 16, v38
	v_pk_mul_f32 v[24:25], v[28:29], v[24:25]
	v_mul_f32_e32 v7, 0xbfb8aa3b, v7
	v_cvt_pk_bf16_f32 v26, v26, v27
	v_cvt_pk_bf16_f32 v27, v24, v25
	v_and_b32_e32 v24, 0xffff0000, v38
	v_exp_f32_e32 v7, v7
	v_mul_f32_e32 v24, 0xbfb8aa3b, v24
	v_exp_f32_e32 v25, v24
	global_store_dwordx2 v[72:73], v[26:27], off offset:128
	v_add_f32_e32 v7, 1.0, v7
	v_rcp_f32_e32 v24, v7
	v_pk_mul_f32 v[22:23], v[22:23], v[6:7] op_sel_hi:[1,0]
	v_add_f32_e32 v7, 1.0, v25
	v_lshlrev_b32_e32 v25, 16, v39
	v_mul_f32_e32 v25, 0xbfb8aa3b, v25
	v_exp_f32_e32 v26, v25
	v_and_b32_e32 v25, 0xffff0000, v39
	v_mul_f32_e32 v25, 0xbfb8aa3b, v25
	v_exp_f32_e32 v27, v25
	v_rcp_f32_e32 v25, v7
	v_add_f32_e32 v7, 1.0, v26
	v_rcp_f32_e32 v26, v7
	v_add_f32_e32 v7, 1.0, v27
	v_rcp_f32_e32 v27, v7
	v_pk_mul_f32 v[20:21], v[20:21], v[6:7] op_sel_hi:[1,0]
	s_waitcnt vmcnt(2)
	v_lshlrev_b32_e32 v7, 16, v40
	v_mul_f32_e32 v7, 0xbfb8aa3b, v7
	v_exp_f32_e32 v7, v7
	s_waitcnt lgkmcnt(0)
	v_pk_mul_f32 v[22:23], v[32:33], v[22:23]
	v_pk_mul_f32 v[20:21], v[34:35], v[20:21]
	v_pk_mul_f32 v[22:23], v[24:25], v[22:23]
	v_add_f32_e32 v7, 1.0, v7
	v_pk_mul_f32 v[20:21], v[26:27], v[20:21]
	v_rcp_f32_e32 v28, v7
	v_and_b32_e32 v7, 0xffff0000, v40
	v_cvt_pk_bf16_f32 v22, v22, v23
	v_cvt_pk_bf16_f32 v23, v20, v21
	v_mul_f32_e32 v7, 0xbfb8aa3b, v7
	global_store_dwordx2 v[72:73], v[22:23], off offset:144
	ds_read_b128 v[20:23], v103 offset:20800
	ds_read_b128 v[24:27], v103 offset:20832
	v_exp_f32_e32 v7, v7
	s_nop 0
	v_pk_mul_f32 v[18:19], v[18:19], v[6:7] op_sel_hi:[1,0]
	s_waitcnt lgkmcnt(1)
	v_pk_mul_f32 v[18:19], v[20:21], v[18:19]
	v_lshlrev_b32_e32 v20, 16, v41
	v_mul_f32_e32 v20, 0xbfb8aa3b, v20
	v_and_b32_e32 v21, 0xffff0000, v41
	v_exp_f32_e32 v20, v20
	v_mul_f32_e32 v21, 0xbfb8aa3b, v21
	v_exp_f32_e32 v21, v21
	v_add_f32_e32 v7, 1.0, v7
	v_rcp_f32_e32 v29, v7
	v_add_f32_e32 v7, 1.0, v20
	v_rcp_f32_e32 v20, v7
	v_add_f32_e32 v7, 1.0, v21
	v_rcp_f32_e32 v21, v7
	v_pk_mul_f32 v[16:17], v[16:17], v[6:7] op_sel_hi:[1,0]
	v_pk_mul_f32 v[18:19], v[28:29], v[18:19]
	v_pk_mul_f32 v[16:17], v[22:23], v[16:17]
	s_waitcnt vmcnt(2)
	v_lshlrev_b32_e32 v7, 16, v42
	v_pk_mul_f32 v[16:17], v[20:21], v[16:17]
	v_mul_f32_e32 v7, 0xbfb8aa3b, v7
	v_cvt_pk_bf16_f32 v18, v18, v19
	v_cvt_pk_bf16_f32 v19, v16, v17
	v_and_b32_e32 v16, 0xffff0000, v42
	v_exp_f32_e32 v7, v7
	v_mul_f32_e32 v16, 0xbfb8aa3b, v16
	v_exp_f32_e32 v17, v16
	global_store_dwordx2 v[72:73], v[18:19], off offset:160
	v_add_f32_e32 v7, 1.0, v7
	v_rcp_f32_e32 v16, v7
	v_pk_mul_f32 v[14:15], v[14:15], v[6:7] op_sel_hi:[1,0]
	v_add_f32_e32 v7, 1.0, v17
	v_lshlrev_b32_e32 v17, 16, v43
	v_mul_f32_e32 v17, 0xbfb8aa3b, v17
	v_exp_f32_e32 v18, v17
	v_and_b32_e32 v17, 0xffff0000, v43
	v_mul_f32_e32 v17, 0xbfb8aa3b, v17
	v_exp_f32_e32 v19, v17
	v_rcp_f32_e32 v17, v7
	v_add_f32_e32 v7, 1.0, v18
	v_rcp_f32_e32 v18, v7
	v_add_f32_e32 v7, 1.0, v19
	v_rcp_f32_e32 v19, v7
	v_pk_mul_f32 v[12:13], v[12:13], v[6:7] op_sel_hi:[1,0]
	s_waitcnt lgkmcnt(0)
; #define LAS __attribute__((address_space(3)))
; __device__ __forceinline__ unsigned pk2(float lo, float hi) { f32x2_t v = {lo, hi}; bf16x2_t b = __builtin_convertvector(v, bf16x2_t); return __builtin_bit_cast(unsigned, b); }
; __device__ __forceinline__ float bflo(unsigned w) { return __uint_as_float(w << 16); }
; __device__ __forceinline__ float bfhi(unsigned w) { return __uint_as_float(w & 0xffff0000u); }
; __device__ __forceinline__ float sigmoidf_(float x) { return __builtin_amdgcn_rcpf(1.f + fexp(-x)); }
;     __device__ __forceinline__ float* GATES() const { return (float*)(ws + WS_GATES); }
;     __device__ __forceinline__ float* MST() const { return (float*)(ws + WS_MB) + 2 * (NSLOT_P + NSLOT_S); }
; template <bool SAMPLE>
; __device__ __forceinline__ void mout_task(Ctx& C, int l, int unit, int h, int tb, const LAS float* cwl, const LAS float* gainl, LAS float* gsbuf, LAS s16x8* qfl, const bool st) {
;     ...
;     const bool valid = lane < L;
;     const float li = valid ? C.GATES()[(grow0 + lane) * 8 + h] : -1e30f, lf = valid ? C.GATES()[(grow0 + lane) * 8 + 4 + h] : 0.f;
;     const float bc = scan_add(lf, lane);
;     const float gg = valid ? li - bc : -1e30f;
;     const float pmx = scan_max(gg, lane);
;     const float m0 = SAMPLE ? C.in[7][(size_t)l * NSLOT_S + unit * 4 + h] : C.MST()[slot];
;     ...
; #pragma unroll
;     for (int vb = 0; vb < 4; ++vb)
; #pragma unroll
;         for (int i4 = 0; i4 < 4; ++i4) { const int v0 = 32 * vb + 8 * i4 + 4 * hi2;
;             const u32x2 ow = *(const u32x2*)(orow + v0); const f32x4 gn = *(const LAS f32x4*)(gainl + h * 128 + v0);
;             const float y0 = acc[vb][4 * i4] * rn * gn[0] * sigmoidf_(bflo(ow.x)), y1 = acc[vb][4 * i4 + 1] * rn * gn[1] * sigmoidf_(bfhi(ow.x));
;             const float y2 = acc[vb][4 * i4 + 2] * rn * gn[2] * sigmoidf_(bflo(ow.y)), y3 = acc[vb][4 * i4 + 3] * rn * gn[3] * sigmoidf_(bfhi(ow.y));
;             u32x2 w; w.x = pk2(y0, y1); w.y = pk2(y2, y3); if (st) *(u32x2*)(orow + v0) = w; if (i4 == 3) asm volatile("" ::: "memory"); }
	v_pk_mul_f32 v[14:15], v[24:25], v[14:15]
	v_pk_mul_f32 v[12:13], v[26:27], v[12:13]
	v_pk_mul_f32 v[14:15], v[16:17], v[14:15]
	v_pk_mul_f32 v[12:13], v[18:19], v[12:13]
	v_cvt_pk_bf16_f32 v14, v14, v15
	v_cvt_pk_bf16_f32 v15, v12, v13
	global_store_dwordx2 v[72:73], v[14:15], off offset:176
	global_load_dwordx2 v[20:21], v[72:73], off offset:192
	global_load_dwordx2 v[22:23], v[72:73], off offset:208
	global_load_dwordx2 v[24:25], v[72:73], off offset:224
	global_load_dwordx2 v[26:27], v[72:73], off offset:240
	ds_read_b128 v[12:15], v103 offset:20864
	ds_read_b128 v[16:19], v103 offset:20896
	s_waitcnt vmcnt(3)
	v_lshlrev_b32_e32 v7, 16, v20
	v_mul_f32_e32 v7, 0xbfb8aa3b, v7
	v_exp_f32_e32 v7, v7
	v_and_b32_e32 v20, 0xffff0000, v20
	v_mul_f32_e32 v20, 0xbfb8aa3b, v20
	v_exp_f32_e32 v28, v20
	v_add_f32_e32 v7, 1.0, v7
	v_pk_mul_f32 v[10:11], v[10:11], v[6:7] op_sel_hi:[1,0]
	v_rcp_f32_e32 v20, v7
	s_waitcnt lgkmcnt(1)
	v_pk_mul_f32 v[10:11], v[12:13], v[10:11]
	v_lshlrev_b32_e32 v12, 16, v21
	v_mul_f32_e32 v12, 0xbfb8aa3b, v12
	v_and_b32_e32 v13, 0xffff0000, v21
	v_exp_f32_e32 v12, v12
	v_mul_f32_e32 v13, 0xbfb8aa3b, v13
	v_exp_f32_e32 v13, v13
	v_add_f32_e32 v7, 1.0, v28
	v_rcp_f32_e32 v21, v7
	v_add_f32_e32 v7, 1.0, v12
	v_rcp_f32_e32 v12, v7
	v_add_f32_e32 v7, 1.0, v13
	v_rcp_f32_e32 v13, v7
	v_pk_mul_f32 v[8:9], v[8:9], v[6:7] op_sel_hi:[1,0]
	v_pk_mul_f32 v[10:11], v[20:21], v[10:11]
	v_pk_mul_f32 v[8:9], v[14:15], v[8:9]
	s_waitcnt vmcnt(2)
	v_lshlrev_b32_e32 v7, 16, v22
	v_pk_mul_f32 v[8:9], v[12:13], v[8:9]
	v_mul_f32_e32 v7, 0xbfb8aa3b, v7
	v_cvt_pk_bf16_f32 v10, v10, v11
	v_cvt_pk_bf16_f32 v11, v8, v9
	v_and_b32_e32 v8, 0xffff0000, v22
	v_exp_f32_e32 v7, v7
	v_mul_f32_e32 v8, 0xbfb8aa3b, v8
	v_exp_f32_e32 v9, v8
	global_store_dwordx2 v[72:73], v[10:11], off offset:192
	v_add_f32_e32 v7, 1.0, v7
	v_rcp_f32_e32 v8, v7
	v_pk_mul_f32 v[4:5], v[4:5], v[6:7] op_sel_hi:[1,0]
	v_add_f32_e32 v7, 1.0, v9
	v_lshlrev_b32_e32 v9, 16, v23
	v_mul_f32_e32 v9, 0xbfb8aa3b, v9
	v_exp_f32_e32 v10, v9
	v_and_b32_e32 v9, 0xffff0000, v23
	v_mul_f32_e32 v9, 0xbfb8aa3b, v9
	v_exp_f32_e32 v11, v9
	v_rcp_f32_e32 v9, v7
	s_waitcnt lgkmcnt(0)
	v_pk_mul_f32 v[4:5], v[16:17], v[4:5]
	v_add_f32_e32 v7, 1.0, v10
	v_rcp_f32_e32 v10, v7
	v_pk_mul_f32 v[4:5], v[8:9], v[4:5]
	v_add_f32_e32 v7, 1.0, v11
	v_cvt_pk_bf16_f32 v4, v4, v5
	s_waitcnt vmcnt(2)
	v_lshlrev_b32_e32 v5, 16, v24
	v_mul_f32_e32 v5, 0xbfb8aa3b, v5
	v_rcp_f32_e32 v11, v7
	v_pk_mul_f32 v[2:3], v[2:3], v[6:7] op_sel_hi:[1,0]
	v_exp_f32_e32 v7, v5
	v_pk_mul_f32 v[2:3], v[18:19], v[2:3]
	v_add_f32_e32 v7, 1.0, v7
	v_pk_mul_f32 v[2:3], v[10:11], v[2:3]
	v_rcp_f32_e32 v12, v7
	v_and_b32_e32 v7, 0xffff0000, v24
	v_cvt_pk_bf16_f32 v5, v2, v3
	v_mul_f32_e32 v7, 0xbfb8aa3b, v7
	global_store_dwordx2 v[72:73], v[4:5], off offset:208
	ds_read_b128 v[2:5], v103 offset:20928
	ds_read_b128 v[8:11], v103 offset:20960
	v_exp_f32_e32 v7, v7
	s_nop 0
	v_pk_mul_f32 v[0:1], v[0:1], v[6:7] op_sel_hi:[1,0]
	s_waitcnt lgkmcnt(1)
	v_pk_mul_f32 v[0:1], v[2:3], v[0:1]
	v_add_f32_e32 v2, 1.0, v7
	v_lshlrev_b32_e32 v3, 16, v25
	v_and_b32_e32 v7, 0xffff0000, v25
	v_mul_f32_e32 v3, 0xbfb8aa3b, v3
	v_mul_f32_e32 v7, 0xbfb8aa3b, v7
	v_exp_f32_e32 v3, v3
	v_exp_f32_e32 v7, v7
	v_rcp_f32_e32 v13, v2
	v_add_f32_e32 v2, 1.0, v3
	v_add_f32_e32 v3, 1.0, v7
	v_rcp_f32_e32 v2, v2
	v_rcp_f32_e32 v3, v3
	v_pk_mul_f32 v[0:1], v[12:13], v[0:1]
	v_pk_mul_f32 v[12:13], v[74:75], v[6:7] op_sel_hi:[1,0]
	v_cvt_pk_bf16_f32 v0, v0, v1
	v_pk_mul_f32 v[4:5], v[4:5], v[12:13]
	s_nop 0
	v_pk_mul_f32 v[2:3], v[2:3], v[4:5]
	s_waitcnt vmcnt(2)
	v_lshlrev_b32_e32 v4, 16, v27
	v_cvt_pk_bf16_f32 v1, v2, v3
	v_lshlrev_b32_e32 v2, 16, v26
	v_and_b32_e32 v3, 0xffff0000, v26
	v_mul_f32_e32 v2, 0xbfb8aa3b, v2
	v_mul_f32_e32 v3, 0xbfb8aa3b, v3
	v_exp_f32_e32 v2, v2
	v_exp_f32_e32 v3, v3
	v_and_b32_e32 v5, 0xffff0000, v27
	v_mul_f32_e32 v4, 0xbfb8aa3b, v4
	v_mul_f32_e32 v5, 0xbfb8aa3b, v5
	v_exp_f32_e32 v4, v4
	v_exp_f32_e32 v5, v5
	global_store_dwordx2 v[72:73], v[0:1], off offset:224
	v_add_f32_e32 v0, 1.0, v2
	v_add_f32_e32 v1, 1.0, v3
	v_rcp_f32_e32 v0, v0
	v_rcp_f32_e32 v1, v1
	v_add_f32_e32 v4, 1.0, v4
	v_add_f32_e32 v5, 1.0, v5
	v_pk_mul_f32 v[2:3], v[60:61], v[6:7] op_sel_hi:[1,0]
	v_rcp_f32_e32 v4, v4
	v_rcp_f32_e32 v5, v5
	s_waitcnt lgkmcnt(0)
	v_pk_mul_f32 v[2:3], v[8:9], v[2:3]
	s_nop 0
	v_pk_mul_f32 v[0:1], v[0:1], v[2:3]
	v_pk_mul_f32 v[2:3], v[58:59], v[6:7] op_sel_hi:[1,0]
	v_cvt_pk_bf16_f32 v0, v0, v1
	v_pk_mul_f32 v[2:3], v[10:11], v[2:3]
	s_nop 0
	v_pk_mul_f32 v[2:3], v[4:5], v[2:3]
	s_nop 0
	v_cvt_pk_bf16_f32 v1, v2, v3
	global_store_dwordx2 v[72:73], v[0:1], off offset:240
	s_waitcnt lgkmcnt(0)
	s_cbranch_vccnz .LBB0_903
	s_ashr_i32 s20, s2, 2
	s_ashr_i32 s21, s20, 31
	s_and_b32 s78, s2, 3
	s_lshl_b64 s[20:21], s[20:21], 5
	s_add_u32 s40, s20, 0x8000
	s_addc_u32 s41, s21, 0
	v_mov_b32_e32 v4, 0xf149f2ca
	v_or_b32_e32 v2, s40, v112
	s_and_saveexec_b64 s[22:23], s[12:13]
	s_cbranch_execz .LBB0_913
	v_mov_b32_e32 v3, s41
	v_readlane_b32 s18, v254, 55
	v_lshlrev_b64 v[0:1], 5, v[2:3]
	v_readlane_b32 s19, v254, 56
	s_lshl_b32 s72, s78, 2
	s_mov_b32 s73, s79
	v_lshl_add_u64 v[0:1], s[18:19], 0, v[0:1]
	v_lshl_add_u64 v[0:1], v[0:1], 0, s[72:73]
	global_load_dword v4, v[0:1], off

; #define MFMA32(a, b, c) __builtin_amdgcn_mfma_f32_32x32x16_bf16((a), (b), (c), 0, 0, 0)
; __device__ __forceinline__ s16x8 pack8(const float (&x)[8]) { u32x4 p; p.x = pk2(x[0], x[1]); p.y = pk2(x[2], x[3]); p.z = pk2(x[4], x[5]); p.w = pk2(x[6], x[7]); return __builtin_bit_cast(s16x8, p); }
; template <bool SAMPLE>
; __device__ __forceinline__ void mout_task(Ctx& C, int l, int unit, int h, int tb, const LAS float* cwl, const LAS float* gainl, LAS float* gsbuf, LAS s16x8* qfl, const bool st) {
;     ...
;         const float* cp = C.in[5] + ((size_t)l * NSLOT_S + unit * 4 + h) * 16384 + r;
; #pragma unroll 1
;         for (int ks = 0; ks < 8; ++ks) { const s16x8 qv = qfl[ks * 64 + lane];
; #pragma unroll
;             for (int vb = 0; vb < 4; ++vb) { float x[8];
; #pragma unroll
;                 for (int e = 0; e < 8; ++e) x[e] = cp[(size_t)(16 * ks + 8 * hi + e) * 128 + 32 * vb];
;                 acc[vb] = MFMA32(pack8(x), qv, acc[vb]); } }
.LBB0_920:
	global_load_dword v132, v[36:37], off offset:-2048
	global_load_dword v133, v[36:37], off offset:-1536
	global_load_dword v134, v[36:37], off offset:-1024
	global_load_dword v135, v[36:37], off offset:-512
	global_load_dword v136, v[36:37], off
	global_load_dword v137, v[36:37], off offset:512
	global_load_dword v138, v[36:37], off offset:1024
	global_load_dword v139, v[36:37], off offset:1536
	global_load_dword v140, v[36:37], off offset:-1920
	global_load_dword v141, v[36:37], off offset:-1408
	global_load_dword v142, v[36:37], off offset:-896
	global_load_dword v143, v[36:37], off offset:-384
	global_load_dword v144, v[36:37], off offset:128
	global_load_dword v145, v[36:37], off offset:640
	global_load_dword v146, v[36:37], off offset:1152
	global_load_dword v147, v[36:37], off offset:1664
	global_load_dword v148, v[36:37], off offset:-1792
	global_load_dword v149, v[36:37], off offset:-1280
	global_load_dword v150, v[36:37], off offset:-768
	global_load_dword v151, v[36:37], off offset:-256
	global_load_dword v152, v[36:37], off offset:256
	global_load_dword v153, v[36:37], off offset:768
	global_load_dword v154, v[36:37], off offset:1280
	global_load_dword v155, v[36:37], off offset:1792
	global_load_dword v156, v[36:37], off offset:-1664
	global_load_dword v157, v[36:37], off offset:-1152
	global_load_dword v158, v[36:37], off offset:-640
	global_load_dword v159, v[36:37], off offset:-128
	global_load_dword v160, v[36:37], off offset:384
	global_load_dword v161, v[36:37], off offset:896
	global_load_dword v162, v[36:37], off offset:1408
	global_load_dword v163, v[36:37], off offset:1920
	v_lshl_add_u64 v[36:37], v[36:37], 0, s[28:29]
	global_load_dword v164, v[36:37], off offset:-2048
	global_load_dword v165, v[36:37], off offset:-1536
	global_load_dword v166, v[36:37], off offset:-1024
	global_load_dword v167, v[36:37], off offset:-512
	global_load_dword v168, v[36:37], off
	global_load_dword v169, v[36:37], off offset:512
	global_load_dword v170, v[36:37], off offset:1024
	global_load_dword v171, v[36:37], off offset:1536
	global_load_dword v172, v[36:37], off offset:-1920
	global_load_dword v173, v[36:37], off offset:-1408
	global_load_dword v174, v[36:37], off offset:-896
	global_load_dword v175, v[36:37], off offset:-384
	global_load_dword v176, v[36:37], off offset:128
	global_load_dword v177, v[36:37], off offset:640
	global_load_dword v178, v[36:37], off offset:1152
	global_load_dword v179, v[36:37], off offset:1664
	global_load_dword v180, v[36:37], off offset:-1792
	global_load_dword v181, v[36:37], off offset:-1280
	global_load_dword v182, v[36:37], off offset:-768
	global_load_dword v183, v[36:37], off offset:-256
	global_load_dword v184, v[36:37], off offset:256
	global_load_dword v47, v[36:37], off offset:768
	global_load_dword v48, v[36:37], off offset:1280
	global_load_dword v49, v[36:37], off offset:1792
	global_load_dword v50, v[36:37], off offset:-1664
	global_load_dword v51, v[36:37], off offset:-1152
	global_load_dword v52, v[36:37], off offset:-640
	global_load_dword v53, v[36:37], off offset:-128
	global_load_dword v54, v[36:37], off offset:384
	global_load_dword v55, v[36:37], off offset:896
	global_load_dword v56, v[36:37], off offset:1408
	global_load_dword v57, v[36:37], off offset:1920
	v_lshl_add_u64 v[36:37], v[36:37], 0, s[28:29]
	ds_read_b128 v[32:35], v131
	ds_read_b128 v[104:107], v131 offset:1024
	s_waitcnt vmcnt(56) lgkmcnt(1)
	v_cvt_pk_bf16_f32 v40, v132, v133
	v_cvt_pk_bf16_f32 v41, v134, v135
	v_cvt_pk_bf16_f32 v42, v136, v137
	v_cvt_pk_bf16_f32 v43, v138, v139
	global_load_dword v132, v[36:37], off offset:-2048
	global_load_dword v133, v[36:37], off offset:-1536
	global_load_dword v134, v[36:37], off offset:-1024
	global_load_dword v135, v[36:37], off offset:-512
	global_load_dword v136, v[36:37], off
	global_load_dword v137, v[36:37], off offset:512
	global_load_dword v138, v[36:37], off offset:1024
	global_load_dword v139, v[36:37], off offset:1536
	v_mfma_f32_32x32x16_bf16 v[0:15], v[40:43], v[32:35], v[0:15]
	s_waitcnt vmcnt(56)
	v_cvt_pk_bf16_f32 v60, v140, v141
	v_cvt_pk_bf16_f32 v61, v142, v143
	v_cvt_pk_bf16_f32 v62, v144, v145
	v_cvt_pk_bf16_f32 v63, v146, v147
	global_load_dword v140, v[36:37], off offset:-1920
	global_load_dword v141, v[36:37], off offset:-1408
	global_load_dword v142, v[36:37], off offset:-896
	global_load_dword v143, v[36:37], off offset:-384
	global_load_dword v144, v[36:37], off offset:128
	global_load_dword v145, v[36:37], off offset:640
	global_load_dword v146, v[36:37], off offset:1152
	global_load_dword v147, v[36:37], off offset:1664
	v_mfma_f32_32x32x16_bf16 v[16:31], v[60:63], v[32:35], v[16:31]
	s_waitcnt vmcnt(56)
	v_cvt_pk_bf16_f32 v40, v148, v149
	v_cvt_pk_bf16_f32 v41, v150, v151
	v_cvt_pk_bf16_f32 v42, v152, v153
	v_cvt_pk_bf16_f32 v43, v154, v155
	global_load_dword v148, v[36:37], off offset:-1792
	global_load_dword v149, v[36:37], off offset:-1280
	global_load_dword v150, v[36:37], off offset:-768
	global_load_dword v151, v[36:37], off offset:-256
	global_load_dword v152, v[36:37], off offset:256
	global_load_dword v153, v[36:37], off offset:768
	global_load_dword v154, v[36:37], off offset:1280
	global_load_dword v155, v[36:37], off offset:1792
	v_mfma_f32_32x32x16_bf16 v[64:79], v[40:43], v[32:35], v[64:79]
	s_waitcnt vmcnt(56)
; #define MFMA32(a, b, c) __builtin_amdgcn_mfma_f32_32x32x16_bf16((a), (b), (c), 0, 0, 0)
; __device__ __forceinline__ s16x8 pack8(const float (&x)[8]) { u32x4 p; p.x = pk2(x[0], x[1]); p.y = pk2(x[2], x[3]); p.z = pk2(x[4], x[5]); p.w = pk2(x[6], x[7]); return __builtin_bit_cast(s16x8, p); }
; template <bool SAMPLE>
; __device__ __forceinline__ void mout_task(Ctx& C, int l, int unit, int h, int tb, const LAS float* cwl, const LAS float* gainl, LAS float* gsbuf, LAS s16x8* qfl, const bool st) {
;     ...
;         const float* cp = C.in[5] + ((size_t)l * NSLOT_S + unit * 4 + h) * 16384 + r;
; #pragma unroll 1
;         for (int ks = 0; ks < 8; ++ks) { const s16x8 qv = qfl[ks * 64 + lane];
; #pragma unroll
;             for (int vb = 0; vb < 4; ++vb) { float x[8];
; #pragma unroll
;                 for (int e = 0; e < 8; ++e) x[e] = cp[(size_t)(16 * ks + 8 * hi + e) * 128 + 32 * vb];
;                 acc[vb] = MFMA32(pack8(x), qv, acc[vb]); } }
	v_cvt_pk_bf16_f32 v60, v156, v157
	v_cvt_pk_bf16_f32 v61, v158, v159
	v_cvt_pk_bf16_f32 v62, v160, v161
	v_cvt_pk_bf16_f32 v63, v162, v163
	global_load_dword v156, v[36:37], off offset:-1664
	global_load_dword v157, v[36:37], off offset:-1152
	global_load_dword v158, v[36:37], off offset:-640
	global_load_dword v159, v[36:37], off offset:-128
	global_load_dword v160, v[36:37], off offset:384
	global_load_dword v161, v[36:37], off offset:896
	global_load_dword v162, v[36:37], off offset:1408
	global_load_dword v163, v[36:37], off offset:1920
	v_mfma_f32_32x32x16_bf16 v[80:95], v[60:63], v[32:35], v[80:95]
	v_lshl_add_u64 v[36:37], v[36:37], 0, s[28:29]
	ds_read_b128 v[32:35], v131 offset:2048
	s_waitcnt vmcnt(56) lgkmcnt(1)
	v_cvt_pk_bf16_f32 v40, v164, v165
	v_cvt_pk_bf16_f32 v41, v166, v167
	v_cvt_pk_bf16_f32 v42, v168, v169
	v_cvt_pk_bf16_f32 v43, v170, v171
	global_load_dword v164, v[36:37], off offset:-2048
	global_load_dword v165, v[36:37], off offset:-1536
	global_load_dword v166, v[36:37], off offset:-1024
	global_load_dword v167, v[36:37], off offset:-512
	global_load_dword v168, v[36:37], off
	global_load_dword v169, v[36:37], off offset:512
	global_load_dword v170, v[36:37], off offset:1024
	global_load_dword v171, v[36:37], off offset:1536
	v_mfma_f32_32x32x16_bf16 v[0:15], v[40:43], v[104:107], v[0:15]
	s_waitcnt vmcnt(56)
	v_cvt_pk_bf16_f32 v60, v172, v173
	v_cvt_pk_bf16_f32 v61, v174, v175
	v_cvt_pk_bf16_f32 v62, v176, v177
	v_cvt_pk_bf16_f32 v63, v178, v179
	global_load_dword v172, v[36:37], off offset:-1920
	global_load_dword v173, v[36:37], off offset:-1408
	global_load_dword v174, v[36:37], off offset:-896
	global_load_dword v175, v[36:37], off offset:-384
	global_load_dword v176, v[36:37], off offset:128
	global_load_dword v177, v[36:37], off offset:640
	global_load_dword v178, v[36:37], off offset:1152
	global_load_dword v179, v[36:37], off offset:1664
	v_mfma_f32_32x32x16_bf16 v[16:31], v[60:63], v[104:107], v[16:31]
	s_waitcnt vmcnt(56)
	v_cvt_pk_bf16_f32 v40, v180, v181
	v_cvt_pk_bf16_f32 v41, v182, v183
	v_cvt_pk_bf16_f32 v42, v184, v47
	v_cvt_pk_bf16_f32 v43, v48, v49
	global_load_dword v180, v[36:37], off offset:-1792
	global_load_dword v181, v[36:37], off offset:-1280
	global_load_dword v182, v[36:37], off offset:-768
	global_load_dword v183, v[36:37], off offset:-256
	global_load_dword v184, v[36:37], off offset:256
	global_load_dword v47, v[36:37], off offset:768
	global_load_dword v48, v[36:37], off offset:1280
	global_load_dword v49, v[36:37], off offset:1792
	v_mfma_f32_32x32x16_bf16 v[64:79], v[40:43], v[104:107], v[64:79]
	s_waitcnt vmcnt(56)
	v_cvt_pk_bf16_f32 v60, v50, v51
	v_cvt_pk_bf16_f32 v61, v52, v53
	v_cvt_pk_bf16_f32 v62, v54, v55
	v_cvt_pk_bf16_f32 v63, v56, v57
	global_load_dword v50, v[36:37], off offset:-1664
	global_load_dword v51, v[36:37], off offset:-1152
	global_load_dword v52, v[36:37], off offset:-640
	global_load_dword v53, v[36:37], off offset:-128
	global_load_dword v54, v[36:37], off offset:384
	global_load_dword v55, v[36:37], off offset:896
	global_load_dword v56, v[36:37], off offset:1408
	global_load_dword v57, v[36:37], off offset:1920
	v_mfma_f32_32x32x16_bf16 v[80:95], v[60:63], v[104:107], v[80:95]
	v_lshl_add_u64 v[36:37], v[36:37], 0, s[28:29]
	ds_read_b128 v[104:107], v131 offset:3072
	s_waitcnt vmcnt(56) lgkmcnt(1)
	v_cvt_pk_bf16_f32 v40, v132, v133
	v_cvt_pk_bf16_f32 v41, v134, v135
	v_cvt_pk_bf16_f32 v42, v136, v137
	v_cvt_pk_bf16_f32 v43, v138, v139
	global_load_dword v132, v[36:37], off offset:-2048
	global_load_dword v133, v[36:37], off offset:-1536
	global_load_dword v134, v[36:37], off offset:-1024
	global_load_dword v135, v[36:37], off offset:-512
	global_load_dword v136, v[36:37], off
	global_load_dword v137, v[36:37], off offset:512
	global_load_dword v138, v[36:37], off offset:1024
	global_load_dword v139, v[36:37], off offset:1536
	v_mfma_f32_32x32x16_bf16 v[0:15], v[40:43], v[32:35], v[0:15]
	s_waitcnt vmcnt(56)
	v_cvt_pk_bf16_f32 v60, v140, v141
	v_cvt_pk_bf16_f32 v61, v142, v143
	v_cvt_pk_bf16_f32 v62, v144, v145
	v_cvt_pk_bf16_f32 v63, v146, v147
	global_load_dword v140, v[36:37], off offset:-1920
	global_load_dword v141, v[36:37], off offset:-1408
	global_load_dword v142, v[36:37], off offset:-896
	global_load_dword v143, v[36:37], off offset:-384
	global_load_dword v144, v[36:37], off offset:128
	global_load_dword v145, v[36:37], off offset:640
	global_load_dword v146, v[36:37], off offset:1152
	global_load_dword v147, v[36:37], off offset:1664
	v_mfma_f32_32x32x16_bf16 v[16:31], v[60:63], v[32:35], v[16:31]
	s_waitcnt vmcnt(56)
	v_cvt_pk_bf16_f32 v40, v148, v149
	v_cvt_pk_bf16_f32 v41, v150, v151
	v_cvt_pk_bf16_f32 v42, v152, v153
	v_cvt_pk_bf16_f32 v43, v154, v155
	global_load_dword v148, v[36:37], off offset:-1792
	global_load_dword v149, v[36:37], off offset:-1280
	global_load_dword v150, v[36:37], off offset:-768
	global_load_dword v151, v[36:37], off offset:-256
	global_load_dword v152, v[36:37], off offset:256
	global_load_dword v153, v[36:37], off offset:768
	global_load_dword v154, v[36:37], off offset:1280
	global_load_dword v155, v[36:37], off offset:1792
	v_mfma_f32_32x32x16_bf16 v[64:79], v[40:43], v[32:35], v[64:79]
	s_waitcnt vmcnt(56)
	v_cvt_pk_bf16_f32 v60, v156, v157
	v_cvt_pk_bf16_f32 v61, v158, v159
	v_cvt_pk_bf16_f32 v62, v160, v161
	v_cvt_pk_bf16_f32 v63, v162, v163
	global_load_dword v156, v[36:37], off offset:-1664
	global_load_dword v157, v[36:37], off offset:-1152
	global_load_dword v158, v[36:37], off offset:-640
	global_load_dword v159, v[36:37], off offset:-128
	global_load_dword v160, v[36:37], off offset:384
	global_load_dword v161, v[36:37], off offset:896
	global_load_dword v162, v[36:37], off offset:1408
	global_load_dword v163, v[36:37], off offset:1920
	v_mfma_f32_32x32x16_bf16 v[80:95], v[60:63], v[32:35], v[80:95]
	v_lshl_add_u64 v[36:37], v[36:37], 0, s[28:29]
	ds_read_b128 v[32:35], v131 offset:4096
	s_waitcnt vmcnt(56) lgkmcnt(1)
; #define MFMA32(a, b, c) __builtin_amdgcn_mfma_f32_32x32x16_bf16((a), (b), (c), 0, 0, 0)
; __device__ __forceinline__ s16x8 pack8(const float (&x)[8]) { u32x4 p; p.x = pk2(x[0], x[1]); p.y = pk2(x[2], x[3]); p.z = pk2(x[4], x[5]); p.w = pk2(x[6], x[7]); return __builtin_bit_cast(s16x8, p); }
; template <bool SAMPLE>
; __device__ __forceinline__ void mout_task(Ctx& C, int l, int unit, int h, int tb, const LAS float* cwl, const LAS float* gainl, LAS float* gsbuf, LAS s16x8* qfl, const bool st) {
;     ...
;         const float* cp = C.in[5] + ((size_t)l * NSLOT_S + unit * 4 + h) * 16384 + r;
; #pragma unroll 1
;         for (int ks = 0; ks < 8; ++ks) { const s16x8 qv = qfl[ks * 64 + lane];
; #pragma unroll
;             for (int vb = 0; vb < 4; ++vb) { float x[8];
; #pragma unroll
;                 for (int e = 0; e < 8; ++e) x[e] = cp[(size_t)(16 * ks + 8 * hi + e) * 128 + 32 * vb];
;                 acc[vb] = MFMA32(pack8(x), qv, acc[vb]); } }
	v_cvt_pk_bf16_f32 v40, v164, v165
	v_cvt_pk_bf16_f32 v41, v166, v167
	v_cvt_pk_bf16_f32 v42, v168, v169
	v_cvt_pk_bf16_f32 v43, v170, v171
	global_load_dword v164, v[36:37], off offset:-2048
	global_load_dword v165, v[36:37], off offset:-1536
	global_load_dword v166, v[36:37], off offset:-1024
	global_load_dword v167, v[36:37], off offset:-512
	global_load_dword v168, v[36:37], off
	global_load_dword v169, v[36:37], off offset:512
	global_load_dword v170, v[36:37], off offset:1024
	global_load_dword v171, v[36:37], off offset:1536
	v_mfma_f32_32x32x16_bf16 v[0:15], v[40:43], v[104:107], v[0:15]
	s_waitcnt vmcnt(56)
	v_cvt_pk_bf16_f32 v60, v172, v173
	v_cvt_pk_bf16_f32 v61, v174, v175
	v_cvt_pk_bf16_f32 v62, v176, v177
	v_cvt_pk_bf16_f32 v63, v178, v179
	global_load_dword v172, v[36:37], off offset:-1920
	global_load_dword v173, v[36:37], off offset:-1408
	global_load_dword v174, v[36:37], off offset:-896
	global_load_dword v175, v[36:37], off offset:-384
	global_load_dword v176, v[36:37], off offset:128
	global_load_dword v177, v[36:37], off offset:640
	global_load_dword v178, v[36:37], off offset:1152
	global_load_dword v179, v[36:37], off offset:1664
	v_mfma_f32_32x32x16_bf16 v[16:31], v[60:63], v[104:107], v[16:31]
	s_waitcnt vmcnt(56)
	v_cvt_pk_bf16_f32 v40, v180, v181
	v_cvt_pk_bf16_f32 v41, v182, v183
	v_cvt_pk_bf16_f32 v42, v184, v47
	v_cvt_pk_bf16_f32 v43, v48, v49
	global_load_dword v180, v[36:37], off offset:-1792
	global_load_dword v181, v[36:37], off offset:-1280
	global_load_dword v182, v[36:37], off offset:-768
	global_load_dword v183, v[36:37], off offset:-256
	global_load_dword v184, v[36:37], off offset:256
	global_load_dword v47, v[36:37], off offset:768
	global_load_dword v48, v[36:37], off offset:1280
	global_load_dword v49, v[36:37], off offset:1792
	v_mfma_f32_32x32x16_bf16 v[64:79], v[40:43], v[104:107], v[64:79]
	s_waitcnt vmcnt(56)
	v_cvt_pk_bf16_f32 v60, v50, v51
	v_cvt_pk_bf16_f32 v61, v52, v53
	v_cvt_pk_bf16_f32 v62, v54, v55
	v_cvt_pk_bf16_f32 v63, v56, v57
	global_load_dword v50, v[36:37], off offset:-1664
	global_load_dword v51, v[36:37], off offset:-1152
	global_load_dword v52, v[36:37], off offset:-640
	global_load_dword v53, v[36:37], off offset:-128
	global_load_dword v54, v[36:37], off offset:384
	global_load_dword v55, v[36:37], off offset:896
	global_load_dword v56, v[36:37], off offset:1408
	global_load_dword v57, v[36:37], off offset:1920
	v_mfma_f32_32x32x16_bf16 v[80:95], v[60:63], v[104:107], v[80:95]
	v_lshl_add_u64 v[36:37], v[36:37], 0, s[28:29]
	ds_read_b128 v[104:107], v131 offset:5120
	s_waitcnt vmcnt(56) lgkmcnt(1)
	v_cvt_pk_bf16_f32 v40, v132, v133
	v_cvt_pk_bf16_f32 v41, v134, v135
	v_cvt_pk_bf16_f32 v42, v136, v137
	v_cvt_pk_bf16_f32 v43, v138, v139
	global_load_dword v132, v[36:37], off offset:-2048
	global_load_dword v133, v[36:37], off offset:-1536
	global_load_dword v134, v[36:37], off offset:-1024
	global_load_dword v135, v[36:37], off offset:-512
	global_load_dword v136, v[36:37], off
	global_load_dword v137, v[36:37], off offset:512
	global_load_dword v138, v[36:37], off offset:1024
	global_load_dword v139, v[36:37], off offset:1536
	v_mfma_f32_32x32x16_bf16 v[0:15], v[40:43], v[32:35], v[0:15]
	s_waitcnt vmcnt(56)
	v_cvt_pk_bf16_f32 v60, v140, v141
	v_cvt_pk_bf16_f32 v61, v142, v143
	v_cvt_pk_bf16_f32 v62, v144, v145
	v_cvt_pk_bf16_f32 v63, v146, v147
	global_load_dword v140, v[36:37], off offset:-1920
	global_load_dword v141, v[36:37], off offset:-1408
	global_load_dword v142, v[36:37], off offset:-896
	global_load_dword v143, v[36:37], off offset:-384
	global_load_dword v144, v[36:37], off offset:128
	global_load_dword v145, v[36:37], off offset:640
	global_load_dword v146, v[36:37], off offset:1152
	global_load_dword v147, v[36:37], off offset:1664
	v_mfma_f32_32x32x16_bf16 v[16:31], v[60:63], v[32:35], v[16:31]
	s_waitcnt vmcnt(56)
	v_cvt_pk_bf16_f32 v40, v148, v149
	v_cvt_pk_bf16_f32 v41, v150, v151
	v_cvt_pk_bf16_f32 v42, v152, v153
	v_cvt_pk_bf16_f32 v43, v154, v155
	global_load_dword v148, v[36:37], off offset:-1792
	global_load_dword v149, v[36:37], off offset:-1280
	global_load_dword v150, v[36:37], off offset:-768
	global_load_dword v151, v[36:37], off offset:-256
	global_load_dword v152, v[36:37], off offset:256
	global_load_dword v153, v[36:37], off offset:768
	global_load_dword v154, v[36:37], off offset:1280
	global_load_dword v155, v[36:37], off offset:1792
	v_mfma_f32_32x32x16_bf16 v[64:79], v[40:43], v[32:35], v[64:79]
	s_waitcnt vmcnt(56)
	v_cvt_pk_bf16_f32 v60, v156, v157
	v_cvt_pk_bf16_f32 v61, v158, v159
	v_cvt_pk_bf16_f32 v62, v160, v161
	v_cvt_pk_bf16_f32 v63, v162, v163
	global_load_dword v156, v[36:37], off offset:-1664
	global_load_dword v157, v[36:37], off offset:-1152
	global_load_dword v158, v[36:37], off offset:-640
	global_load_dword v159, v[36:37], off offset:-128
	global_load_dword v160, v[36:37], off offset:384
	global_load_dword v161, v[36:37], off offset:896
	global_load_dword v162, v[36:37], off offset:1408
	global_load_dword v163, v[36:37], off offset:1920
	v_mfma_f32_32x32x16_bf16 v[80:95], v[60:63], v[32:35], v[80:95]
	v_lshl_add_u64 v[36:37], v[36:37], 0, s[28:29]
	ds_read_b128 v[32:35], v131 offset:6144
	s_waitcnt vmcnt(56) lgkmcnt(1)
	v_cvt_pk_bf16_f32 v40, v164, v165
	v_cvt_pk_bf16_f32 v41, v166, v167
	v_cvt_pk_bf16_f32 v42, v168, v169
	v_cvt_pk_bf16_f32 v43, v170, v171
	global_load_dword v164, v[36:37], off offset:-2048
	global_load_dword v165, v[36:37], off offset:-1536
	global_load_dword v166, v[36:37], off offset:-1024
	global_load_dword v167, v[36:37], off offset:-512
	global_load_dword v168, v[36:37], off
	global_load_dword v169, v[36:37], off offset:512
	global_load_dword v170, v[36:37], off offset:1024
	global_load_dword v171, v[36:37], off offset:1536
	v_mfma_f32_32x32x16_bf16 v[0:15], v[40:43], v[104:107], v[0:15]
	s_waitcnt vmcnt(56)
; #define MFMA32(a, b, c) __builtin_amdgcn_mfma_f32_32x32x16_bf16((a), (b), (c), 0, 0, 0)
; __device__ __forceinline__ s16x8 pack8(const float (&x)[8]) { u32x4 p; p.x = pk2(x[0], x[1]); p.y = pk2(x[2], x[3]); p.z = pk2(x[4], x[5]); p.w = pk2(x[6], x[7]); return __builtin_bit_cast(s16x8, p); }
;     __device__ __forceinline__ bf16* U() const { return (bf16*)(ws + WS_U); }
;     __device__ __forceinline__ bf16* DC() const { return (bf16*)(ws + WS_XN); }
; template <bool SAMPLE>
; __device__ __forceinline__ void mout_task(Ctx& C, int l, int unit, int h, int tb, const LAS float* cwl, const LAS float* gainl, LAS float* gsbuf, LAS s16x8* qfl, const bool st) {
;     ...
;         for (int ks = 0; ks < 8; ++ks) { const s16x8 qv = qfl[ks * 64 + lane];
; #pragma unroll
;             for (int vb = 0; vb < 4; ++vb) { float x[8];
; #pragma unroll
;                 for (int e = 0; e < 8; ++e) x[e] = cp[(size_t)(16 * ks + 8 * hi + e) * 128 + 32 * vb];
;                 acc[vb] = MFMA32(pack8(x), qv, acc[vb]); } }
;     } else {
;         const bf16* cp = C.DC() + (size_t)slot * 16384 + (size_t)r * 128 + 8 * hi;
; #pragma unroll 1
;         for (int ks = 0; ks < 8; ++ks) { const s16x8 qv = qfl[ks * 64 + lane];
; #pragma unroll
;             for (int vb = 0; vb < 4; ++vb) acc[vb] = MFMA32(*(const s16x8*)(cp + (size_t)vb * 4096 + 16 * ks), qv, acc[vb]); }
;     }
; #pragma unroll
;     for (int vb = 0; vb < 4; ++vb)
; #pragma unroll
;         for (int i = 0; i < 16; ++i) acc[vb][i] *= winter;
;     float den = 0.f;
;     const int nsb = SAMPLE ? 1 : tb + 1;
; #pragma unroll 1
;     for (int sb = 0; sb < nsb; ++sb) {
;         f32x16 S;
; #pragma unroll
;         for (int i = 0; i < 16; ++i) S[i] = 0.f;
;         const int sl = 32 * sb + r;
;         { s16x8 tk[8];
;           const bf16* kp = C.U() + (grow0 + sl) * UW + C_KM + h * 128 + 8 * hi;
; #pragma unroll
;           for (int ks = 0; ks < 8; ++ks) tk[ks] = *(const s16x8*)(kp + 16 * ks);
; #pragma unroll
;           for (int ks = 0; ks < 8; ++ks) S = MFMA32(tk[ks], qfl[ks * 64 + lane], S); }
	v_cvt_pk_bf16_f32 v60, v172, v173
	v_cvt_pk_bf16_f32 v61, v174, v175
	v_cvt_pk_bf16_f32 v62, v176, v177
	v_cvt_pk_bf16_f32 v63, v178, v179
	global_load_dword v172, v[36:37], off offset:-1920
	global_load_dword v173, v[36:37], off offset:-1408
	global_load_dword v174, v[36:37], off offset:-896
	global_load_dword v175, v[36:37], off offset:-384
	global_load_dword v176, v[36:37], off offset:128
	global_load_dword v177, v[36:37], off offset:640
	global_load_dword v178, v[36:37], off offset:1152
	global_load_dword v179, v[36:37], off offset:1664
	v_mfma_f32_32x32x16_bf16 v[16:31], v[60:63], v[104:107], v[16:31]
	s_waitcnt vmcnt(56)
	v_cvt_pk_bf16_f32 v40, v180, v181
	v_cvt_pk_bf16_f32 v41, v182, v183
	v_cvt_pk_bf16_f32 v42, v184, v47
	v_cvt_pk_bf16_f32 v43, v48, v49
	global_load_dword v180, v[36:37], off offset:-1792
	global_load_dword v181, v[36:37], off offset:-1280
	global_load_dword v182, v[36:37], off offset:-768
	global_load_dword v183, v[36:37], off offset:-256
	global_load_dword v184, v[36:37], off offset:256
	global_load_dword v47, v[36:37], off offset:768
	global_load_dword v48, v[36:37], off offset:1280
	global_load_dword v49, v[36:37], off offset:1792
	v_mfma_f32_32x32x16_bf16 v[64:79], v[40:43], v[104:107], v[64:79]
	s_waitcnt vmcnt(56)
	v_cvt_pk_bf16_f32 v60, v50, v51
	v_cvt_pk_bf16_f32 v61, v52, v53
	v_cvt_pk_bf16_f32 v62, v54, v55
	v_cvt_pk_bf16_f32 v63, v56, v57
	global_load_dword v50, v[36:37], off offset:-1664
	global_load_dword v51, v[36:37], off offset:-1152
	global_load_dword v52, v[36:37], off offset:-640
	global_load_dword v53, v[36:37], off offset:-128
	global_load_dword v54, v[36:37], off offset:384
	global_load_dword v55, v[36:37], off offset:896
	global_load_dword v56, v[36:37], off offset:1408
	global_load_dword v57, v[36:37], off offset:1920
	v_mfma_f32_32x32x16_bf16 v[80:95], v[60:63], v[104:107], v[80:95]
	v_lshl_add_u64 v[36:37], v[36:37], 0, s[28:29]
	ds_read_b128 v[104:107], v131 offset:7168
	s_waitcnt vmcnt(56) lgkmcnt(1)
	v_cvt_pk_bf16_f32 v40, v132, v133
	v_cvt_pk_bf16_f32 v41, v134, v135
	v_cvt_pk_bf16_f32 v42, v136, v137
	v_cvt_pk_bf16_f32 v43, v138, v139
	s_nop 1
	v_mfma_f32_32x32x16_bf16 v[0:15], v[40:43], v[32:35], v[0:15]
	s_waitcnt vmcnt(48)
	v_cvt_pk_bf16_f32 v60, v140, v141
	v_cvt_pk_bf16_f32 v61, v142, v143
	v_cvt_pk_bf16_f32 v62, v144, v145
	v_cvt_pk_bf16_f32 v63, v146, v147
	s_nop 1
	v_mfma_f32_32x32x16_bf16 v[16:31], v[60:63], v[32:35], v[16:31]
	s_waitcnt vmcnt(40)
	v_cvt_pk_bf16_f32 v40, v148, v149
	v_cvt_pk_bf16_f32 v41, v150, v151
	v_cvt_pk_bf16_f32 v42, v152, v153
	v_cvt_pk_bf16_f32 v43, v154, v155
	s_nop 1
	v_mfma_f32_32x32x16_bf16 v[64:79], v[40:43], v[32:35], v[64:79]
	s_waitcnt vmcnt(32)
	v_cvt_pk_bf16_f32 v60, v156, v157
	v_cvt_pk_bf16_f32 v61, v158, v159
	v_cvt_pk_bf16_f32 v62, v160, v161
	v_cvt_pk_bf16_f32 v63, v162, v163
	s_nop 1
	v_mfma_f32_32x32x16_bf16 v[80:95], v[60:63], v[32:35], v[80:95]
	s_waitcnt vmcnt(24) lgkmcnt(0)
	v_cvt_pk_bf16_f32 v40, v164, v165
	v_cvt_pk_bf16_f32 v41, v166, v167
	v_cvt_pk_bf16_f32 v42, v168, v169
	v_cvt_pk_bf16_f32 v43, v170, v171
	s_nop 1
	v_mfma_f32_32x32x16_bf16 v[0:15], v[40:43], v[104:107], v[0:15]
	s_waitcnt vmcnt(16)
	v_cvt_pk_bf16_f32 v60, v172, v173
	v_cvt_pk_bf16_f32 v61, v174, v175
	v_cvt_pk_bf16_f32 v62, v176, v177
	v_cvt_pk_bf16_f32 v63, v178, v179
	s_nop 1
	v_mfma_f32_32x32x16_bf16 v[16:31], v[60:63], v[104:107], v[16:31]
	s_waitcnt vmcnt(8)
	v_cvt_pk_bf16_f32 v40, v180, v181
	v_cvt_pk_bf16_f32 v41, v182, v183
	v_cvt_pk_bf16_f32 v42, v184, v47
	v_cvt_pk_bf16_f32 v43, v48, v49
	s_nop 1
	v_mfma_f32_32x32x16_bf16 v[64:79], v[40:43], v[104:107], v[64:79]
	s_waitcnt vmcnt(0)
	v_cvt_pk_bf16_f32 v60, v50, v51
	v_cvt_pk_bf16_f32 v61, v52, v53
	v_cvt_pk_bf16_f32 v62, v54, v55
	v_cvt_pk_bf16_f32 v63, v56, v57
	s_nop 1
	v_mfma_f32_32x32x16_bf16 v[80:95], v[60:63], v[104:107], v[80:95]
	s_movk_i32 s5, 0x2000
	v_add_f32_e32 v32, v38, v97
	v_sub_f32_e32 v32, v32, v101
	v_mul_f32_e32 v32, 0x3fb8aa3b, v32
	v_exp_f32_e32 v100, v32
	v_lshl_add_u32 v103, v116, 2, s3
	s_mov_b32 s6, 0x3fb8aa3b
	v_cmp_gt_u32_e32 vcc, v192, v129
	v_pk_mul_f32 v[32:33], v[100:101], v[16:17] op_sel_hi:[0,1]
	v_pk_mul_f32 v[16:17], v[100:101], v[64:65] op_sel_hi:[0,1]
	v_or_b32_e32 v64, s4, v192
	v_mul_u32_u24_e32 v64, 0x8400, v64
	v_lshlrev_b32_e32 v64, 1, v64
	v_mov_b32_e32 v65, v193
	v_lshl_add_u64 v[64:65], s[90:91], 0, v[64:65]
	v_pk_mul_f32 v[60:61], v[100:101], v[12:13] op_sel_hi:[0,1]
	v_pk_mul_f32 v[58:59], v[100:101], v[10:11] op_sel_hi:[0,1]
	v_pk_mul_f32 v[56:57], v[100:101], v[8:9] op_sel_hi:[0,1]
	v_pk_mul_f32 v[54:55], v[100:101], v[6:7] op_sel_hi:[0,1]
	v_pk_mul_f32 v[52:53], v[100:101], v[4:5] op_sel_hi:[0,1]
	v_pk_mul_f32 v[50:51], v[100:101], v[2:3] op_sel_hi:[0,1]
	v_pk_mul_f32 v[48:49], v[100:101], v[0:1] op_sel_hi:[0,1]
	v_pk_mul_f32 v[34:35], v[100:101], v[18:19] op_sel_hi:[0,1]
	v_pk_mul_f32 v[18:19], v[100:101], v[66:67] op_sel_hi:[0,1]
	v_pk_mul_f32 v[12:13], v[100:101], v[92:93] op_sel_hi:[0,1]
	v_pk_mul_f32 v[10:11], v[100:101], v[90:91] op_sel_hi:[0,1]
	v_pk_mul_f32 v[8:9], v[100:101], v[88:89] op_sel_hi:[0,1]
	v_pk_mul_f32 v[6:7], v[100:101], v[86:87] op_sel_hi:[0,1]
	v_pk_mul_f32 v[4:5], v[100:101], v[84:85] op_sel_hi:[0,1]
	v_pk_mul_f32 v[2:3], v[100:101], v[82:83] op_sel_hi:[0,1]
	v_pk_mul_f32 v[0:1], v[100:101], v[80:81] op_sel_hi:[0,1]
	v_lshl_add_u64 v[92:93], s[40:41], 1, v[64:65]
	global_load_dwordx4 v[64:67], v[98:99], off offset:3072
	global_load_dwordx4 v[80:83], v[98:99], off offset:3104
	global_load_dwordx4 v[84:87], v[98:99], off offset:3136
	global_load_dwordx4 v[88:91], v[98:99], off offset:3168
	global_load_dwordx4 v[104:107], v[98:99], off offset:3200
; #define LAS __attribute__((address_space(3)))
; __device__ __forceinline__ unsigned pk2(float lo, float hi) { f32x2_t v = {lo, hi}; bf16x2_t b = __builtin_convertvector(v, bf16x2_t); return __builtin_bit_cast(unsigned, b); }
; #define MFMA32(a, b, c) __builtin_amdgcn_mfma_f32_32x32x16_bf16((a), (b), (c), 0, 0, 0)
;     __device__ __forceinline__ bf16* U() const { return (bf16*)(ws + WS_U); }
;     __device__ __forceinline__ bf16* KVt() const { return (bf16*)(ws + WS_KVT); }
; template <bool SAMPLE>
; __device__ __forceinline__ void mout_task(Ctx& C, int l, int unit, int h, int tb, const LAS float* cwl, const LAS float* gainl, LAS float* gsbuf, LAS s16x8* qfl, const bool st) {
;     ...
;         const int sl = 32 * sb + r;
;         { s16x8 tk[8];
;           const bf16* kp = C.U() + (grow0 + sl) * UW + C_KM + h * 128 + 8 * hi;
; #pragma unroll
;           for (int ks = 0; ks < 8; ++ks) tk[ks] = *(const s16x8*)(kp + 16 * ks);
; #pragma unroll
;           for (int ks = 0; ks < 8; ++ks) S = MFMA32(tk[ks], qfl[ks * 64 + lane], S); }
;         const float e0 = (bt - mt) * LOG2E;
; #pragma unroll
;         for (int i4 = 0; i4 < 4; ++i4) { const f32x4 gs = *(const LAS f32x4*)(gsbuf + 32 * sb + 8 * i4 + 4 * hi);
; #pragma unroll
;             for (int e = 0; e < 4; ++e) { const int sidx = 32 * sb + 8 * i4 + 4 * hi + e;
;                 const float wv = (sidx <= tl) ? __builtin_amdgcn_exp2f(e0 + gs[e] * LOG2E) : 0.f;
;                 S[4 * i4 + e] *= wv; den += S[4 * i4 + e]; } }
; #pragma unroll
;         for (int s2 = 0; s2 < 2; ++s2) { u32x4 w; w.x = pk2(S[8 * s2], S[8 * s2 + 1]); w.y = pk2(S[8 * s2 + 2], S[8 * s2 + 3]); w.z = pk2(S[8 * s2 + 4], S[8 * s2 + 5]); w.w = pk2(S[8 * s2 + 6], S[8 * s2 + 7]);
;             const s16x8 pf = __builtin_bit_cast(s16x8, w);
;             const bf16* vp0 = C.KVt() + (size_t)(R_VM + h * 128 + r) * MT + grow0 + 32 * sb + 16 * s2 + 4 * hi;
; #pragma unroll
;             for (int vb = 0; vb < 4; ++vb) { const bf16* vp = vp0 + (size_t)(32 * vb) * MT;
;                 const u32x2 a = *(const u32x2*)vp, bq = *(const u32x2*)(vp + 8); u32x4 vw; vw.x = a.x; vw.y = a.y; vw.z = bq.x; vw.w = bq.y;
;                 acc[vb] = MFMA32(__builtin_bit_cast(s16x8, vw), pf, acc[vb]); } }
	global_load_dwordx4 v[108:111], v[98:99], off offset:3232
	global_load_dwordx4 v[116:119], v[98:99], off offset:3264
	global_load_dwordx4 v[120:123], v[98:99], off offset:3296
	v_pk_mul_f32 v[38:39], v[100:101], v[22:23] op_sel_hi:[0,1]
	v_pk_mul_f32 v[36:37], v[100:101], v[20:21] op_sel_hi:[0,1]
	v_pk_mul_f32 v[22:23], v[100:101], v[70:71] op_sel_hi:[0,1]
	v_pk_mul_f32 v[20:21], v[100:101], v[68:69] op_sel_hi:[0,1]
	ds_read_b128 v[68:71], v127 offset:32768
	ds_read_b128 v[130:133], v127 offset:33792
	v_pk_mul_f32 v[46:47], v[100:101], v[30:31] op_sel_hi:[0,1]
	v_pk_mul_f32 v[44:45], v[100:101], v[28:29] op_sel_hi:[0,1]
	v_pk_mul_f32 v[42:43], v[100:101], v[26:27] op_sel_hi:[0,1]
	v_pk_mul_f32 v[40:41], v[100:101], v[24:25] op_sel_hi:[0,1]
	v_pk_mul_f32 v[30:31], v[100:101], v[78:79] op_sel_hi:[0,1]
	v_pk_mul_f32 v[28:29], v[100:101], v[76:77] op_sel_hi:[0,1]
	v_pk_mul_f32 v[26:27], v[100:101], v[74:75] op_sel_hi:[0,1]
	v_pk_mul_f32 v[24:25], v[100:101], v[72:73] op_sel_hi:[0,1]
	v_pk_mul_f32 v[62:63], v[100:101], v[14:15] op_sel_hi:[0,1]
	v_pk_mul_f32 v[14:15], v[100:101], v[94:95] op_sel_hi:[0,1]
	v_sub_f32_e32 v94, v97, v101
	v_or_b32_e32 v97, 3, v129
	v_or_b32_e32 v113, 17, v129
	v_or_b32_e32 v115, 19, v129
	s_mov_b32 s5, 0x14a00000
	ds_bpermute_b32 v102, v125, v96
	s_lshl_b32 s78, s4, 1
	s_lshl_b32 s4, s4, 2
	s_add_i32 s4, s4, 0
	s_waitcnt vmcnt(7) lgkmcnt(2)
	v_mfma_f32_32x32x16_bf16 v[64:79], v[64:67], v[68:71], 0
	s_waitcnt vmcnt(6) lgkmcnt(1)
	v_mfma_f32_32x32x16_bf16 v[64:79], v[80:83], v[130:133], v[64:79]
	ds_read_b128 v[80:83], v127 offset:34816
	s_waitcnt vmcnt(5) lgkmcnt(0)
	v_mfma_f32_32x32x16_bf16 v[64:79], v[84:87], v[80:83], v[64:79]
	ds_read_b128 v[80:83], v127 offset:35840
	s_waitcnt vmcnt(4) lgkmcnt(0)
	v_mfma_f32_32x32x16_bf16 v[64:79], v[88:91], v[80:83], v[64:79]
	ds_read_b128 v[80:83], v127 offset:36864
	s_waitcnt vmcnt(3) lgkmcnt(0)
	v_mfma_f32_32x32x16_bf16 v[64:79], v[104:107], v[80:83], v[64:79]
	ds_read_b128 v[80:83], v127 offset:37888
	s_waitcnt vmcnt(2) lgkmcnt(0)
	v_mfma_f32_32x32x16_bf16 v[64:79], v[108:111], v[80:83], v[64:79]
	ds_read_b128 v[80:83], v127 offset:38912
	v_or_b32_e32 v108, 9, v129
	v_or_b32_e32 v109, 8, v129
	v_or_b32_e32 v110, 11, v129
	v_or_b32_e32 v111, 10, v129
	s_waitcnt vmcnt(1) lgkmcnt(0)
	v_mfma_f32_32x32x16_bf16 v[64:79], v[116:119], v[80:83], v[64:79]
	ds_read_b128 v[80:83], v127 offset:39936
	v_or_b32_e32 v116, 18, v129
	v_or_b32_e32 v117, 25, v129
	v_or_b32_e32 v118, 24, v129
	v_or_b32_e32 v119, 27, v129
	s_waitcnt vmcnt(0) lgkmcnt(0)
	v_mfma_f32_32x32x16_bf16 v[64:79], v[120:123], v[80:83], v[64:79]
	v_sub_u32_e32 v80, v103, v114
	ds_read_b128 v[104:107], v80 offset:22528
	ds_read_b128 v[88:91], v80 offset:22560
	ds_read_b128 v[84:87], v80 offset:22592
	ds_read_b128 v[80:83], v80 offset:22624
	v_or_b32_e32 v103, 2, v129
	v_or_b32_e32 v114, 16, v129
	v_or_b32_e32 v120, 26, v129
	s_waitcnt lgkmcnt(0)
	v_mov_b32_e32 v95, v83
	v_pk_mul_f32 v[94:95], v[94:95], s[6:7] op_sel_hi:[1,0]
	s_mov_b64 s[6:7], 0x14a00000
	v_fmamk_f32 v98, v105, 0x3fb8aa3b, v94
	v_fmamk_f32 v83, v104, 0x3fb8aa3b, v94
	v_exp_f32_e32 v98, v98
	v_exp_f32_e32 v83, v83
	v_cndmask_b32_e32 v99, 0, v98, vcc
	v_cmp_le_u32_e32 vcc, v129, v192
	s_nop 1
	v_cndmask_b32_e32 v98, 0, v83, vcc
	v_pk_mul_f32 v[64:65], v[64:65], v[98:99]
	v_fmamk_f32 v99, v107, 0x3fb8aa3b, v94
	v_fmamk_f32 v98, v106, 0x3fb8aa3b, v94
	v_exp_f32_e32 v99, v99
	v_exp_f32_e32 v98, v98
	v_cmp_le_u32_e32 vcc, v97, v192
	v_add_f32_e32 v83, 0, v64
	v_add_f32_e32 v83, v65, v83
	v_cndmask_b32_e32 v99, 0, v99, vcc
	v_cmp_le_u32_e32 vcc, v103, v192
	s_nop 1
	v_cndmask_b32_e32 v98, 0, v98, vcc
	v_pk_mul_f32 v[98:99], v[66:67], v[98:99]
	v_fmamk_f32 v67, v89, 0x3fb8aa3b, v94
	v_add_f32_e32 v66, v98, v83
	v_add_f32_e32 v83, v99, v66
	v_fmamk_f32 v66, v88, 0x3fb8aa3b, v94
	v_exp_f32_e32 v67, v67
	v_exp_f32_e32 v66, v66
	v_cmp_le_u32_e32 vcc, v108, v192
	s_nop 1
	v_cndmask_b32_e32 v67, 0, v67, vcc
	v_cmp_le_u32_e32 vcc, v109, v192
	s_nop 1
	v_cndmask_b32_e32 v66, 0, v66, vcc
	v_pk_mul_f32 v[88:89], v[68:69], v[66:67]
	v_fmamk_f32 v67, v91, 0x3fb8aa3b, v94
	v_add_f32_e32 v66, v88, v83
	v_add_f32_e32 v68, v89, v66
	v_fmamk_f32 v66, v90, 0x3fb8aa3b, v94
	v_exp_f32_e32 v67, v67
	v_exp_f32_e32 v66, v66
	v_cmp_le_u32_e32 vcc, v110, v192
	s_nop 1
	v_cndmask_b32_e32 v67, 0, v67, vcc
	v_cmp_le_u32_e32 vcc, v111, v192
	s_nop 1
	v_cndmask_b32_e32 v66, 0, v66, vcc
	v_pk_mul_f32 v[90:91], v[70:71], v[66:67]
	v_fmamk_f32 v67, v85, 0x3fb8aa3b, v94
	v_add_f32_e32 v66, v90, v68
	v_add_f32_e32 v70, v91, v66
	v_fmamk_f32 v66, v84, 0x3fb8aa3b, v94
	v_exp_f32_e32 v67, v67
	v_exp_f32_e32 v66, v66
	v_cmp_le_u32_e32 vcc, v113, v192
	v_add_f32_e32 v71, v94, v95
	v_exp_f32_e32 v71, v71
	v_cndmask_b32_e32 v67, 0, v67, vcc
	v_cmp_le_u32_e32 vcc, v114, v192
	s_nop 1
	v_cndmask_b32_e32 v66, 0, v66, vcc
	v_pk_mul_f32 v[68:69], v[72:73], v[66:67]
	v_fmamk_f32 v67, v87, 0x3fb8aa3b, v94
	v_add_f32_e32 v66, v68, v70
	v_add_f32_e32 v70, v69, v66
	v_fmamk_f32 v66, v86, 0x3fb8aa3b, v94
	v_exp_f32_e32 v67, v67
	v_exp_f32_e32 v66, v66
	v_cmp_le_u32_e32 vcc, v115, v192
	s_nop 1
	v_cndmask_b32_e32 v67, 0, v67, vcc
	v_cmp_le_u32_e32 vcc, v116, v192
	s_nop 1
	v_cndmask_b32_e32 v66, 0, v66, vcc
	v_pk_mul_f32 v[72:73], v[74:75], v[66:67]
	v_fmamk_f32 v67, v81, 0x3fb8aa3b, v94
	v_add_f32_e32 v66, v72, v70
	v_add_f32_e32 v97, v73, v66
	v_fmamk_f32 v66, v80, 0x3fb8aa3b, v94
	v_exp_f32_e32 v67, v67
	v_exp_f32_e32 v66, v66
	v_cmp_le_u32_e32 vcc, v117, v192
	v_fmamk_f32 v70, v82, 0x3fb8aa3b, v94
	v_exp_f32_e32 v70, v70
	v_cndmask_b32_e32 v67, 0, v67, vcc
	v_cmp_le_u32_e32 vcc, v118, v192
	v_cvt_pk_bf16_f32 v74, v64, v65
	v_cvt_pk_bf16_f32 v75, v98, v99
	v_cndmask_b32_e32 v66, 0, v66, vcc
	v_cmp_le_u32_e32 vcc, v119, v192
	v_pk_mul_f32 v[66:67], v[76:77], v[66:67]
	v_cvt_pk_bf16_f32 v76, v88, v89
	v_cndmask_b32_e32 v71, 0, v71, vcc
	v_cmp_le_u32_e32 vcc, v120, v192
	v_lshlrev_b32_e32 v192, 1, v129
	v_lshl_add_u64 v[82:83], v[92:93], 0, v[192:193]
	v_cndmask_b32_e32 v70, 0, v70, vcc
	v_add_co_u32_e32 v64, vcc, s5, v82
	v_pk_mul_f32 v[70:71], v[78:79], v[70:71]
	s_nop 0
	v_addc_co_u32_e32 v65, vcc, 0, v83, vcc
	v_lshl_add_u64 v[84:85], v[82:83], 0, s[6:7]
	global_load_dwordx2 v[78:79], v[64:65], off
	global_load_dwordx2 v[80:81], v[84:85], off offset:16
	s_mov_b32 s5, 0x14c10000
	v_add_co_u32_e32 v64, vcc, s5, v82
	v_cvt_pk_bf16_f32 v77, v90, v91
	s_nop 0
	v_addc_co_u32_e32 v65, vcc, 0, v83, vcc
	s_waitcnt vmcnt(0)
; #define LAS __attribute__((address_space(3)))
; __device__ __forceinline__ unsigned pk2(float lo, float hi) { f32x2_t v = {lo, hi}; bf16x2_t b = __builtin_convertvector(v, bf16x2_t); return __builtin_bit_cast(unsigned, b); }
; __device__ __forceinline__ float fexp(float x) { return __builtin_amdgcn_exp2f(x * LOG2E); }
; #define MFMA32(a, b, c) __builtin_amdgcn_mfma_f32_32x32x16_bf16((a), (b), (c), 0, 0, 0)
;     __device__ __forceinline__ bf16* U() const { return (bf16*)(ws + WS_U); }
;     __device__ __forceinline__ bf16* KVt() const { return (bf16*)(ws + WS_KVT); }
; template <bool SAMPLE>
; __device__ __forceinline__ void mout_task(Ctx& C, int l, int unit, int h, int tb, const LAS float* cwl, const LAS float* gainl, LAS float* gsbuf, LAS s16x8* qfl, const bool st) {
;     ...
;         for (int s2 = 0; s2 < 2; ++s2) { u32x4 w; w.x = pk2(S[8 * s2], S[8 * s2 + 1]); w.y = pk2(S[8 * s2 + 2], S[8 * s2 + 3]); w.z = pk2(S[8 * s2 + 4], S[8 * s2 + 5]); w.w = pk2(S[8 * s2 + 6], S[8 * s2 + 7]);
;             const s16x8 pf = __builtin_bit_cast(s16x8, w);
;             const bf16* vp0 = C.KVt() + (size_t)(R_VM + h * 128 + r) * MT + grow0 + 32 * sb + 16 * s2 + 4 * hi;
; #pragma unroll
;             for (int vb = 0; vb < 4; ++vb) { const bf16* vp = vp0 + (size_t)(32 * vb) * MT;
;                 const u32x2 a = *(const u32x2*)vp, bq = *(const u32x2*)(vp + 8); u32x4 vw; vw.x = a.x; vw.y = a.y; vw.z = bq.x; vw.w = bq.y;
;                 acc[vb] = MFMA32(__builtin_bit_cast(s16x8, vw), pf, acc[vb]); } }
;     }
;     den += __shfl_xor(den, 32);
;     den += winter * qn;
;     const float inv = __builtin_amdgcn_rcpf(fmaxf(fabsf(den), fexp(-mt)));
;     float ss = 0.f;
; #pragma unroll
;     for (int vb = 0; vb < 4; ++vb)
; #pragma unroll
;         for (int i = 0; i < 16; ++i) { acc[vb][i] *= inv; ss += acc[vb][i] * acc[vb][i]; }
;     ss += __shfl_xor(ss, 32);
;     const float rn = rsqrtf(ss * (1.f / 128.f) + EPS);
;     int lane2 = lane; asm volatile("" : "+v"(lane2));
;     const int hi2 = lane2 >> 5;
;     bf16* orow = C.U() + (grow0 + 32 * tb + (lane2 & 31)) * UW + C_OM + h * 128;
; #pragma unroll
;     for (int vb = 0; vb < 4; ++vb)
; #pragma unroll
;         for (int i4 = 0; i4 < 4; ++i4) { const int v0 = 32 * vb + 8 * i4 + 4 * hi2;
;             const u32x2 ow = *(const u32x2*)(orow + v0); const f32x4 gn = *(const LAS f32x4*)(gainl + h * 128 + v0);
	v_mfma_f32_32x32x16_bf16 v[48:63], v[78:81], v[74:77], v[48:63]
	global_load_dwordx2 v[78:79], v[64:65], off
	global_load_dwordx2 v[80:81], v[64:65], off offset:16
	s_mov_b32 s5, 0x14e20000
	v_add_co_u32_e32 v86, vcc, s5, v82
	s_mov_b32 s5, 0x15030000
	s_nop 0
	v_addc_co_u32_e32 v87, vcc, 0, v83, vcc
	s_waitcnt vmcnt(0)
	v_mfma_f32_32x32x16_bf16 v[32:47], v[78:81], v[74:77], v[32:47]
	global_load_dwordx2 v[78:79], v[86:87], off
	global_load_dwordx2 v[80:81], v[86:87], off offset:16
	v_add_co_u32_e32 v82, vcc, s5, v82
	s_nop 1
	v_addc_co_u32_e32 v83, vcc, 0, v83, vcc
	s_waitcnt vmcnt(0)
	v_mfma_f32_32x32x16_bf16 v[16:31], v[78:81], v[74:77], v[16:31]
	global_load_dwordx2 v[78:79], v[82:83], off
	global_load_dwordx2 v[80:81], v[82:83], off offset:16
	s_waitcnt vmcnt(0)
	v_mfma_f32_32x32x16_bf16 v[0:15], v[78:81], v[74:77], v[0:15]
	global_load_dwordx2 v[78:79], v[84:85], off offset:32
	global_load_dwordx2 v[80:81], v[84:85], off offset:48
	v_cvt_pk_bf16_f32 v74, v68, v69
	v_cvt_pk_bf16_f32 v75, v72, v73
	v_cvt_pk_bf16_f32 v76, v66, v67
	v_cvt_pk_bf16_f32 v77, v70, v71
	s_waitcnt vmcnt(0)
	s_nop 0
	v_mfma_f32_32x32x16_bf16 v[48:63], v[78:81], v[74:77], v[48:63]
	global_load_dwordx2 v[78:79], v[64:65], off offset:32
	global_load_dwordx2 v[80:81], v[64:65], off offset:48
	v_add_f32_e32 v64, v66, v97
	v_add_f32_e32 v64, v67, v64
	v_add_f32_e32 v64, v70, v64
	v_add_f32_e32 v97, v71, v64
	ds_bpermute_b32 v103, v125, v97
	s_waitcnt lgkmcnt(0)
	v_pk_add_f32 v[64:65], v[96:97], v[102:103]
	s_waitcnt vmcnt(0)
	v_mfma_f32_32x32x16_bf16 v[32:47], v[78:81], v[74:77], v[32:47]
	global_load_dwordx2 v[78:79], v[86:87], off offset:32
	global_load_dwordx2 v[80:81], v[86:87], off offset:48
	v_fmac_f32_e32 v65, v100, v64
	v_mul_f32_e32 v64, 0xbfb8aa3b, v101
	v_exp_f32_e32 v64, v64
	s_nop 0
	v_max_f32_e64 v64, |v65|, v64
	s_waitcnt vmcnt(0)
	v_mfma_f32_32x32x16_bf16 v[16:31], v[78:81], v[74:77], v[16:31]
	global_load_dwordx2 v[78:79], v[82:83], off offset:32
	global_load_dwordx2 v[80:81], v[82:83], off offset:48
	s_waitcnt vmcnt(0)
	v_mfma_f32_32x32x16_bf16 v[0:15], v[78:81], v[74:77], v[0:15]
	v_rcp_f32_e32 v80, v64
	s_nop 10
	v_pk_mul_f32 v[72:73], v[10:11], v[80:81] op_sel_hi:[1,0]
	v_pk_mul_f32 v[68:69], v[12:13], v[80:81] op_sel_hi:[1,0]
	v_and_or_b32 v12, v112, 31, s40
	v_mov_b64_e32 v[10:11], s[90:91]
	v_mad_u64_u32 v[10:11], s[6:7], v12, s61, v[10:11]
	v_ashrrev_i32_e32 v12, 3, v112
	v_mad_i32_i24 v11, s41, v221, v11
	v_and_b32_e32 v12, -4, v12
	v_lshl_add_u64 v[10:11], v[10:11], 0, s[78:79]
	v_ashrrev_i32_e32 v13, 31, v12
	v_lshl_add_u64 v[10:11], v[12:13], 1, v[10:11]
	s_mov_b64 s[6:7], 0x1000
	v_add_co_u32_e32 v82, vcc, s60, v10
	v_pk_mul_f32 v[14:15], v[14:15], v[80:81] op_sel_hi:[1,0]
	v_lshl_add_u64 v[70:71], v[10:11], 0, s[6:7]
	v_addc_co_u32_e32 v83, vcc, 0, v11, vcc
	v_lshl_add_u32 v81, v12, 2, s4
	global_load_dwordx2 v[86:87], v[82:83], off
	ds_read_b128 v[64:67], v81 offset:20480
	ds_read_b128 v[10:13], v81 offset:20512
	v_pk_mul_f32 v[90:91], v[48:49], v[80:81] op_sel_hi:[1,0]
	global_load_dwordx2 v[48:49], v[70:71], off offset:16
	global_load_dwordx2 v[116:117], v[70:71], off offset:48
	v_pk_mul_f32 v[102:103], v[52:53], v[80:81] op_sel_hi:[1,0]
	global_load_dwordx2 v[52:53], v[70:71], off offset:32
	v_pk_mul_f32 v[88:89], v[50:51], v[80:81] op_sel_hi:[1,0]
	v_pk_mul_f32 v[94:95], v[90:91], v[90:91]
	v_pk_mul_f32 v[92:93], v[88:89], v[88:89]
	v_pk_mul_f32 v[100:101], v[54:55], v[80:81] op_sel_hi:[1,0]
	v_pk_mul_f32 v[58:59], v[58:59], v[80:81] op_sel_hi:[1,0]
	v_pk_mul_f32 v[56:57], v[56:57], v[80:81] op_sel_hi:[1,0]
	v_pk_mul_f32 v[126:127], v[62:63], v[80:81] op_sel_hi:[1,0]
	v_pk_mul_f32 v[130:131], v[60:61], v[80:81] op_sel_hi:[1,0]
	v_pk_mul_f32 v[134:135], v[34:35], v[80:81] op_sel_hi:[1,0]
	v_pk_mul_f32 v[138:139], v[32:33], v[80:81] op_sel_hi:[1,0]
	v_pk_mul_f32 v[60:61], v[42:43], v[80:81] op_sel_hi:[1,0]
	v_pk_mul_f32 v[62:63], v[40:41], v[80:81] op_sel_hi:[1,0]
	v_pk_mul_f32 v[46:47], v[46:47], v[80:81] op_sel_hi:[1,0]
	v_pk_mul_f32 v[44:45], v[44:45], v[80:81] op_sel_hi:[1,0]
	v_pk_mul_f32 v[40:41], v[18:19], v[80:81] op_sel_hi:[1,0]
	v_pk_mul_f32 v[42:43], v[16:17], v[80:81] op_sel_hi:[1,0]
	v_pk_mul_f32 v[32:33], v[26:27], v[80:81] op_sel_hi:[1,0]
	v_pk_mul_f32 v[34:35], v[24:25], v[80:81] op_sel_hi:[1,0]
	v_pk_mul_f32 v[24:25], v[30:31], v[80:81] op_sel_hi:[1,0]
	v_pk_mul_f32 v[26:27], v[28:29], v[80:81] op_sel_hi:[1,0]
	v_pk_mul_f32 v[16:17], v[6:7], v[80:81] op_sel_hi:[1,0]
	v_pk_mul_f32 v[18:19], v[4:5], v[80:81] op_sel_hi:[1,0]
	v_pk_mul_f32 v[6:7], v[8:9], v[80:81] op_sel_hi:[1,0]
	v_pk_mul_f32 v[106:107], v[102:103], v[102:103]
	v_pk_mul_f32 v[104:105], v[100:101], v[100:101]
	v_pk_mul_f32 v[114:115], v[56:57], v[56:57]
	v_pk_mul_f32 v[112:113], v[58:59], v[58:59]
	v_pk_mul_f32 v[132:133], v[130:131], v[130:131]
	v_pk_mul_f32 v[128:129], v[126:127], v[126:127]
	v_pk_mul_f32 v[140:141], v[138:139], v[138:139]
	v_pk_mul_f32 v[136:137], v[134:135], v[134:135]
	v_pk_mul_f32 v[148:149], v[62:63], v[62:63]
	v_pk_mul_f32 v[146:147], v[60:61], v[60:61]
	v_pk_mul_f32 v[152:153], v[44:45], v[44:45]
	v_pk_mul_f32 v[150:151], v[46:47], v[46:47]
	v_pk_mul_f32 v[156:157], v[42:43], v[42:43]
	v_pk_mul_f32 v[154:155], v[40:41], v[40:41]
	v_pk_mul_f32 v[164:165], v[34:35], v[34:35]
	v_pk_mul_f32 v[162:163], v[32:33], v[32:33]
	v_pk_mul_f32 v[28:29], v[26:27], v[26:27]
	v_pk_mul_f32 v[30:31], v[24:25], v[24:25]
	v_pk_mul_f32 v[4:5], v[18:19], v[18:19]
	v_pk_mul_f32 v[166:167], v[16:17], v[16:17]
	v_pk_mul_f32 v[8:9], v[6:7], v[6:7]
	v_pk_mul_f32 v[74:75], v[72:73], v[72:73]
	v_pk_mul_f32 v[76:77], v[68:69], v[68:69]
	v_pk_mul_f32 v[78:79], v[14:15], v[14:15]
	s_waitcnt vmcnt(3)
; #define LAS __attribute__((address_space(3)))
; __device__ __forceinline__ unsigned pk2(float lo, float hi) { f32x2_t v = {lo, hi}; bf16x2_t b = __builtin_convertvector(v, bf16x2_t); return __builtin_bit_cast(unsigned, b); }
; __device__ __forceinline__ float bflo(unsigned w) { return __uint_as_float(w << 16); }
; __device__ __forceinline__ float bfhi(unsigned w) { return __uint_as_float(w & 0xffff0000u); }
; __device__ __forceinline__ float sigmoidf_(float x) { return __builtin_amdgcn_rcpf(1.f + fexp(-x)); }
;     __device__ __forceinline__ bf16* U() const { return (bf16*)(ws + WS_U); }
; template <bool SAMPLE>
; __device__ __forceinline__ void mout_task(Ctx& C, int l, int unit, int h, int tb, const LAS float* cwl, const LAS float* gainl, LAS float* gsbuf, LAS s16x8* qfl, const bool st) {
;     ...
;     float ss = 0.f;
; #pragma unroll
;     for (int vb = 0; vb < 4; ++vb)
; #pragma unroll
;         for (int i = 0; i < 16; ++i) { acc[vb][i] *= inv; ss += acc[vb][i] * acc[vb][i]; }
;     ss += __shfl_xor(ss, 32);
;     const float rn = rsqrtf(ss * (1.f / 128.f) + EPS);
;     int lane2 = lane; asm volatile("" : "+v"(lane2));
;     const int hi2 = lane2 >> 5;
;     bf16* orow = C.U() + (grow0 + 32 * tb + (lane2 & 31)) * UW + C_OM + h * 128;
; #pragma unroll
;     for (int vb = 0; vb < 4; ++vb)
; #pragma unroll
;         for (int i4 = 0; i4 < 4; ++i4) { const int v0 = 32 * vb + 8 * i4 + 4 * hi2;
;             const u32x2 ow = *(const u32x2*)(orow + v0); const f32x4 gn = *(const LAS f32x4*)(gainl + h * 128 + v0);
;             const float y0 = acc[vb][4 * i4] * rn * gn[0] * sigmoidf_(bflo(ow.x)), y1 = acc[vb][4 * i4 + 1] * rn * gn[1] * sigmoidf_(bfhi(ow.x));
;             const float y2 = acc[vb][4 * i4 + 2] * rn * gn[2] * sigmoidf_(bflo(ow.y)), y3 = acc[vb][4 * i4 + 3] * rn * gn[3] * sigmoidf_(bfhi(ow.y));
;             u32x2 w; w.x = pk2(y0, y1); w.y = pk2(y2, y3); if (st) *(u32x2*)(orow + v0) = w; if (i4 == 3) asm volatile("" ::: "memory"); }
	v_lshlrev_b32_e32 v84, 16, v86
	v_and_b32_e32 v85, 0xffff0000, v86
	v_lshlrev_b32_e32 v86, 16, v87
	s_waitcnt vmcnt(2)
	v_lshlrev_b32_e32 v50, 16, v48
	s_waitcnt vmcnt(1)
	v_lshlrev_b32_e32 v118, 16, v116
	v_and_b32_e32 v116, 0xffff0000, v116
	v_mul_f32_e32 v116, 0xbfb8aa3b, v116
	v_exp_f32_e32 v116, v116
	v_mul_f32_e32 v118, 0xbfb8aa3b, v118
	v_exp_f32_e32 v118, v118
	v_and_b32_e32 v48, 0xffff0000, v48
	v_add_f32_e32 v116, 1.0, v116
	v_rcp_f32_e32 v121, v116
	v_lshlrev_b32_e32 v116, 16, v117
	v_mul_f32_e32 v116, 0xbfb8aa3b, v116
	v_exp_f32_e32 v116, v116
	v_add_f32_e32 v118, 1.0, v118
	v_rcp_f32_e32 v120, v118
	v_pk_mul_f32 v[118:119], v[36:37], v[80:81] op_sel_hi:[1,0]
	v_add_f32_e32 v116, 1.0, v116
	v_rcp_f32_e32 v122, v116
	v_and_b32_e32 v116, 0xffff0000, v117
	v_mul_f32_e32 v116, 0xbfb8aa3b, v116
	v_exp_f32_e32 v116, v116
	v_pk_mul_f32 v[36:37], v[22:23], v[80:81] op_sel_hi:[1,0]
	v_pk_mul_f32 v[22:23], v[0:1], v[80:81] op_sel_hi:[1,0]
	v_pk_mul_f32 v[144:145], v[118:119], v[118:119]
	v_add_f32_e32 v116, 1.0, v116
	v_rcp_f32_e32 v123, v116
	v_pk_mul_f32 v[116:117], v[38:39], v[80:81] op_sel_hi:[1,0]
	v_pk_mul_f32 v[38:39], v[20:21], v[80:81] op_sel_hi:[1,0]
	v_pk_mul_f32 v[20:21], v[2:3], v[80:81] op_sel_hi:[1,0]
	v_add_f32_e32 v80, v94, v95
	v_add_f32_e32 v80, v92, v80
	v_add_f32_e32 v80, v93, v80
	v_add_f32_e32 v80, v106, v80
	v_add_f32_e32 v80, v107, v80
	v_add_f32_e32 v80, v104, v80
	v_add_f32_e32 v80, v105, v80
	v_add_f32_e32 v80, v114, v80
	v_add_f32_e32 v80, v115, v80
	v_add_f32_e32 v80, v112, v80
	v_add_f32_e32 v80, v113, v80
	v_add_f32_e32 v80, v132, v80
	v_add_f32_e32 v80, v133, v80
	v_add_f32_e32 v80, v128, v80
	v_add_f32_e32 v80, v129, v80
	v_add_f32_e32 v80, v140, v80
	v_add_f32_e32 v80, v141, v80
	v_add_f32_e32 v80, v136, v80
	v_add_f32_e32 v80, v137, v80
	v_add_f32_e32 v80, v144, v80
	v_pk_mul_f32 v[142:143], v[116:117], v[116:117]
	v_add_f32_e32 v80, v145, v80
	v_add_f32_e32 v80, v142, v80
	v_add_f32_e32 v80, v143, v80
	v_add_f32_e32 v80, v148, v80
	v_add_f32_e32 v80, v149, v80
	v_add_f32_e32 v80, v146, v80
	v_add_f32_e32 v80, v147, v80
	v_add_f32_e32 v80, v152, v80
	v_add_f32_e32 v80, v153, v80
	v_add_f32_e32 v80, v150, v80
	v_add_f32_e32 v80, v151, v80
	v_add_f32_e32 v80, v156, v80
	v_add_f32_e32 v80, v157, v80
	v_add_f32_e32 v80, v154, v80
	v_pk_mul_f32 v[160:161], v[38:39], v[38:39]
	v_add_f32_e32 v80, v155, v80
	v_add_f32_e32 v80, v160, v80
	v_pk_mul_f32 v[158:159], v[36:37], v[36:37]
	v_add_f32_e32 v80, v161, v80
	v_add_f32_e32 v80, v158, v80
	v_add_f32_e32 v80, v159, v80
	v_add_f32_e32 v80, v164, v80
	v_add_f32_e32 v80, v165, v80
	v_add_f32_e32 v80, v162, v80
	v_add_f32_e32 v80, v163, v80
	v_add_f32_e32 v28, v28, v80
	v_add_f32_e32 v28, v29, v28
	v_add_f32_e32 v28, v30, v28
	v_pk_mul_f32 v[0:1], v[22:23], v[22:23]
	v_add_f32_e32 v28, v31, v28
	v_add_f32_e32 v0, v0, v28
	v_pk_mul_f32 v[2:3], v[20:21], v[20:21]
	v_add_f32_e32 v0, v1, v0
	v_add_f32_e32 v0, v2, v0
	v_add_f32_e32 v0, v3, v0
	v_add_f32_e32 v0, v4, v0
	v_add_f32_e32 v0, v5, v0
	v_add_f32_e32 v0, v166, v0
	v_add_f32_e32 v0, v167, v0
	v_add_f32_e32 v0, v8, v0
	v_add_f32_e32 v0, v9, v0
	v_add_f32_e32 v0, v74, v0
	v_add_f32_e32 v0, v75, v0
	v_add_f32_e32 v0, v76, v0
	v_mul_f32_e32 v48, 0xbfb8aa3b, v48
	v_add_f32_e32 v0, v77, v0
	v_exp_f32_e32 v48, v48
	v_add_f32_e32 v0, v78, v0
	v_add_f32_e32 v0, v79, v0
	s_waitcnt vmcnt(0)
	v_lshlrev_b32_e32 v54, 16, v52
	v_and_b32_e32 v52, 0xffff0000, v52
	ds_bpermute_b32 v1, v125, v0
	v_mul_f32_e32 v52, 0xbfb8aa3b, v52
	v_add_f32_e32 v48, 1.0, v48
	v_exp_f32_e32 v52, v52
	v_rcp_f32_e32 v97, v48
	v_lshlrev_b32_e32 v48, 16, v49
	v_mul_f32_e32 v48, 0xbfb8aa3b, v48
	v_exp_f32_e32 v48, v48
	s_waitcnt lgkmcnt(0)
	v_add_f32_e32 v0, v0, v1
	v_mov_b32_e32 v2, 0x358637bd
	v_and_b32_e32 v87, 0xffff0000, v87
	v_add_f32_e32 v52, 1.0, v52
	v_fmamk_f32 v0, v0, 0x3c000000, v2
	v_mul_f32_e32 v84, 0xbfb8aa3b, v84
	v_mul_f32_e32 v85, 0xbfb8aa3b, v85
	v_mul_f32_e32 v86, 0xbfb8aa3b, v86
	v_mul_f32_e32 v87, 0xbfb8aa3b, v87
	v_rcp_f32_e32 v109, v52
	v_lshlrev_b32_e32 v52, 16, v53
	v_cmp_gt_f32_e32 vcc, s65, v0
	v_mul_f32_e32 v1, 0x4b800000, v0
	v_exp_f32_e32 v84, v84
	v_exp_f32_e32 v85, v85
	v_exp_f32_e32 v86, v86
	v_exp_f32_e32 v87, v87
	v_mul_f32_e32 v52, 0xbfb8aa3b, v52
	v_cndmask_b32_e32 v0, v0, v1, vcc
	v_add_f32_e32 v48, 1.0, v48
	v_exp_f32_e32 v52, v52
	v_rsq_f32_e32 v0, v0
	v_rcp_f32_e32 v98, v48
	v_and_b32_e32 v48, 0xffff0000, v49
	v_mul_f32_e32 v50, 0xbfb8aa3b, v50
	v_mul_f32_e32 v48, 0xbfb8aa3b, v48
	v_add_f32_e32 v84, 1.0, v84
	v_add_f32_e32 v85, 1.0, v85
	v_add_f32_e32 v86, 1.0, v86
	v_add_f32_e32 v87, 1.0, v87
	v_exp_f32_e32 v50, v50
	v_exp_f32_e32 v48, v48
	v_rcp_f32_e32 v84, v84
	v_rcp_f32_e32 v85, v85
	v_rcp_f32_e32 v86, v86
	v_rcp_f32_e32 v87, v87
	v_add_f32_e32 v52, 1.0, v52
	v_mul_f32_e32 v1, 0x45800000, v0
	v_rcp_f32_e32 v110, v52
	v_and_b32_e32 v52, 0xffff0000, v53
	v_cndmask_b32_e32 v4, v0, v1, vcc
	v_mul_f32_e32 v54, 0xbfb8aa3b, v54
	v_mul_f32_e32 v52, 0xbfb8aa3b, v52
	v_pk_mul_f32 v[0:1], v[90:91], v[4:5] op_sel_hi:[1,0]
	v_pk_mul_f32 v[2:3], v[88:89], v[4:5] op_sel_hi:[1,0]
	v_add_f32_e32 v50, 1.0, v50
	v_add_f32_e32 v48, 1.0, v48
	v_exp_f32_e32 v54, v54
	v_exp_f32_e32 v52, v52
	v_pk_mul_f32 v[0:1], v[64:65], v[0:1]
	v_pk_mul_f32 v[2:3], v[66:67], v[2:3]
	v_rcp_f32_e32 v96, v50
	v_rcp_f32_e32 v99, v48
	v_pk_mul_f32 v[0:1], v[84:85], v[0:1]
	v_pk_mul_f32 v[2:3], v[86:87], v[2:3]
	v_cvt_pk_bf16_f32 v0, v0, v1
	v_cvt_pk_bf16_f32 v1, v2, v3
	ds_read_b128 v[48:51], v81 offset:20544
	global_store_dwordx2 v[82:83], v[0:1], off
	v_pk_mul_f32 v[0:1], v[102:103], v[4:5] op_sel_hi:[1,0]
	v_pk_mul_f32 v[2:3], v[100:101], v[4:5] op_sel_hi:[1,0]
	v_add_f32_e32 v54, 1.0, v54
	v_add_f32_e32 v52, 1.0, v52
	v_pk_mul_f32 v[0:1], v[10:11], v[0:1]
	v_pk_mul_f32 v[2:3], v[12:13], v[2:3]
	v_rcp_f32_e32 v108, v54
	v_rcp_f32_e32 v111, v52
	v_pk_mul_f32 v[0:1], v[96:97], v[0:1]
	v_pk_mul_f32 v[2:3], v[98:99], v[2:3]
	v_cvt_pk_bf16_f32 v0, v0, v1
	v_cvt_pk_bf16_f32 v1, v2, v3
	ds_read_b128 v[52:55], v81 offset:20576
	global_store_dwordx2 v[70:71], v[0:1], off offset:16
	v_pk_mul_f32 v[0:1], v[56:57], v[4:5] op_sel_hi:[1,0]
	v_pk_mul_f32 v[2:3], v[58:59], v[4:5] op_sel_hi:[1,0]
	s_waitcnt lgkmcnt(1)
; #define LAS __attribute__((address_space(3)))
; __device__ __forceinline__ unsigned pk2(float lo, float hi) { f32x2_t v = {lo, hi}; bf16x2_t b = __builtin_convertvector(v, bf16x2_t); return __builtin_bit_cast(unsigned, b); }
; __device__ __forceinline__ float bflo(unsigned w) { return __uint_as_float(w << 16); }
; __device__ __forceinline__ float bfhi(unsigned w) { return __uint_as_float(w & 0xffff0000u); }
; __device__ __forceinline__ float sigmoidf_(float x) { return __builtin_amdgcn_rcpf(1.f + fexp(-x)); }
; template <bool SAMPLE>
; __device__ __forceinline__ void mout_task(Ctx& C, int l, int unit, int h, int tb, const LAS float* cwl, const LAS float* gainl, LAS float* gsbuf, LAS s16x8* qfl, const bool st) {
;     ...
; #pragma unroll
;     for (int vb = 0; vb < 4; ++vb)
; #pragma unroll
;         for (int i4 = 0; i4 < 4; ++i4) { const int v0 = 32 * vb + 8 * i4 + 4 * hi2;
;             const u32x2 ow = *(const u32x2*)(orow + v0); const f32x4 gn = *(const LAS f32x4*)(gainl + h * 128 + v0);
;             const float y0 = acc[vb][4 * i4] * rn * gn[0] * sigmoidf_(bflo(ow.x)), y1 = acc[vb][4 * i4 + 1] * rn * gn[1] * sigmoidf_(bfhi(ow.x));
;             const float y2 = acc[vb][4 * i4 + 2] * rn * gn[2] * sigmoidf_(bflo(ow.y)), y3 = acc[vb][4 * i4 + 3] * rn * gn[3] * sigmoidf_(bfhi(ow.y));
;             u32x2 w; w.x = pk2(y0, y1); w.y = pk2(y2, y3); if (st) *(u32x2*)(orow + v0) = w; if (i4 == 3) asm volatile("" ::: "memory"); }
	v_pk_mul_f32 v[0:1], v[48:49], v[0:1]
	v_pk_mul_f32 v[2:3], v[50:51], v[2:3]
	v_pk_mul_f32 v[0:1], v[108:109], v[0:1]
	v_pk_mul_f32 v[2:3], v[110:111], v[2:3]
	v_cvt_pk_bf16_f32 v0, v0, v1
	v_cvt_pk_bf16_f32 v1, v2, v3
	global_store_dwordx2 v[70:71], v[0:1], off offset:32
	v_pk_mul_f32 v[0:1], v[130:131], v[4:5] op_sel_hi:[1,0]
	v_pk_mul_f32 v[2:3], v[126:127], v[4:5] op_sel_hi:[1,0]
	s_waitcnt lgkmcnt(0)
	v_pk_mul_f32 v[0:1], v[52:53], v[0:1]
	v_pk_mul_f32 v[2:3], v[54:55], v[2:3]
	v_pk_mul_f32 v[0:1], v[120:121], v[0:1]
	v_pk_mul_f32 v[2:3], v[122:123], v[2:3]
	v_cvt_pk_bf16_f32 v0, v0, v1
	v_cvt_pk_bf16_f32 v1, v2, v3
	global_store_dwordx2 v[70:71], v[0:1], off offset:48
	global_load_dwordx2 v[12:13], v[70:71], off offset:64
	ds_read_b128 v[0:3], v81 offset:20608
	ds_read_b128 v[8:11], v81 offset:20640
	s_waitcnt vmcnt(0)
	v_lshlrev_b32_e32 v5, 16, v12
	v_mul_f32_e32 v5, 0xbfb8aa3b, v5
	v_exp_f32_e32 v5, v5
	s_nop 0
	v_add_f32_e32 v5, 1.0, v5
	v_rcp_f32_e32 v28, v5
	v_pk_mul_f32 v[30:31], v[138:139], v[4:5] op_sel_hi:[1,0]
	v_and_b32_e32 v5, 0xffff0000, v12
	v_mul_f32_e32 v5, 0xbfb8aa3b, v5
	v_exp_f32_e32 v5, v5
	s_waitcnt lgkmcnt(1)
	v_pk_mul_f32 v[0:1], v[0:1], v[30:31]
	v_add_f32_e32 v5, 1.0, v5
	v_rcp_f32_e32 v29, v5
	v_lshlrev_b32_e32 v5, 16, v13
	v_mul_f32_e32 v5, 0xbfb8aa3b, v5
	v_exp_f32_e32 v5, v5
	v_pk_mul_f32 v[0:1], v[28:29], v[0:1]
	v_add_f32_e32 v5, 1.0, v5
	v_rcp_f32_e32 v12, v5
	v_pk_mul_f32 v[28:29], v[134:135], v[4:5] op_sel_hi:[1,0]
	v_and_b32_e32 v5, 0xffff0000, v13
	v_mul_f32_e32 v5, 0xbfb8aa3b, v5
	v_exp_f32_e32 v5, v5
	v_pk_mul_f32 v[2:3], v[2:3], v[28:29]
	v_cvt_pk_bf16_f32 v0, v0, v1
	v_add_f32_e32 v5, 1.0, v5
	v_rcp_f32_e32 v13, v5
	s_nop 0
	v_pk_mul_f32 v[2:3], v[12:13], v[2:3]
	s_nop 0
	v_cvt_pk_bf16_f32 v1, v2, v3
	global_store_dwordx2 v[70:71], v[0:1], off offset:64
	global_load_dwordx2 v[0:1], v[70:71], off offset:80
	v_pk_mul_f32 v[12:13], v[118:119], v[4:5] op_sel_hi:[1,0]
	s_waitcnt vmcnt(0)
	v_lshlrev_b32_e32 v2, 16, v0
	v_and_b32_e32 v0, 0xffff0000, v0
	v_mul_f32_e32 v0, 0xbfb8aa3b, v0
	v_exp_f32_e32 v0, v0
	v_mul_f32_e32 v2, 0xbfb8aa3b, v2
	v_exp_f32_e32 v2, v2
	s_waitcnt lgkmcnt(0)
	v_pk_mul_f32 v[8:9], v[8:9], v[12:13]
	v_add_f32_e32 v0, 1.0, v0
	v_rcp_f32_e32 v3, v0
	v_lshlrev_b32_e32 v0, 16, v1
	v_and_b32_e32 v1, 0xffff0000, v1
	v_mul_f32_e32 v0, 0xbfb8aa3b, v0
	v_mul_f32_e32 v1, 0xbfb8aa3b, v1
	v_exp_f32_e32 v0, v0
	v_exp_f32_e32 v1, v1
	v_add_f32_e32 v2, 1.0, v2
	v_rcp_f32_e32 v2, v2
	v_add_f32_e32 v0, 1.0, v0
	v_add_f32_e32 v1, 1.0, v1
	v_rcp_f32_e32 v0, v0
	v_rcp_f32_e32 v1, v1
	v_pk_mul_f32 v[2:3], v[2:3], v[8:9]
	v_pk_mul_f32 v[8:9], v[116:117], v[4:5] op_sel_hi:[1,0]
	v_cvt_pk_bf16_f32 v2, v2, v3
	v_pk_mul_f32 v[8:9], v[10:11], v[8:9]
	s_nop 0
	v_pk_mul_f32 v[0:1], v[0:1], v[8:9]
	global_load_dwordx2 v[8:9], v[70:71], off offset:96
	v_cvt_pk_bf16_f32 v3, v0, v1
	global_store_dwordx2 v[70:71], v[2:3], off offset:80
	ds_read_b128 v[0:3], v81 offset:20672
	s_waitcnt vmcnt(1)
	v_lshlrev_b32_e32 v5, 16, v8
	v_mul_f32_e32 v5, 0xbfb8aa3b, v5
	v_exp_f32_e32 v5, v5
	s_nop 0
	v_add_f32_e32 v5, 1.0, v5
	v_rcp_f32_e32 v10, v5
	v_pk_mul_f32 v[12:13], v[62:63], v[4:5] op_sel_hi:[1,0]
	v_and_b32_e32 v5, 0xffff0000, v8
	v_mul_f32_e32 v5, 0xbfb8aa3b, v5
	v_exp_f32_e32 v5, v5
	s_waitcnt lgkmcnt(0)
	v_pk_mul_f32 v[0:1], v[0:1], v[12:13]
	v_add_f32_e32 v5, 1.0, v5
	v_rcp_f32_e32 v11, v5
	v_lshlrev_b32_e32 v5, 16, v9
	v_mul_f32_e32 v5, 0xbfb8aa3b, v5
	v_exp_f32_e32 v5, v5
	v_pk_mul_f32 v[0:1], v[10:11], v[0:1]
	v_add_f32_e32 v5, 1.0, v5
	v_rcp_f32_e32 v8, v5
	v_pk_mul_f32 v[10:11], v[60:61], v[4:5] op_sel_hi:[1,0]
	v_and_b32_e32 v5, 0xffff0000, v9
	v_mul_f32_e32 v5, 0xbfb8aa3b, v5
	v_exp_f32_e32 v5, v5
	v_pk_mul_f32 v[2:3], v[2:3], v[10:11]
	v_cvt_pk_bf16_f32 v0, v0, v1
	v_add_f32_e32 v5, 1.0, v5
	v_rcp_f32_e32 v9, v5
	s_nop 0
	v_pk_mul_f32 v[2:3], v[8:9], v[2:3]
	global_load_dwordx2 v[8:9], v[70:71], off offset:112
	v_cvt_pk_bf16_f32 v1, v2, v3
	global_store_dwordx2 v[70:71], v[0:1], off offset:96
	ds_read_b128 v[0:3], v81 offset:20704
	s_waitcnt vmcnt(1)
	v_lshlrev_b32_e32 v5, 16, v8
	v_mul_f32_e32 v5, 0xbfb8aa3b, v5
	v_exp_f32_e32 v5, v5
	s_nop 0
	v_add_f32_e32 v5, 1.0, v5
	v_rcp_f32_e32 v10, v5
	v_pk_mul_f32 v[12:13], v[44:45], v[4:5] op_sel_hi:[1,0]
	v_and_b32_e32 v5, 0xffff0000, v8
	v_mul_f32_e32 v5, 0xbfb8aa3b, v5
	v_exp_f32_e32 v5, v5
	s_waitcnt lgkmcnt(0)
	v_pk_mul_f32 v[0:1], v[0:1], v[12:13]
	v_add_f32_e32 v5, 1.0, v5
	v_rcp_f32_e32 v11, v5
	v_lshlrev_b32_e32 v5, 16, v9
	v_mul_f32_e32 v5, 0xbfb8aa3b, v5
	v_exp_f32_e32 v5, v5
	v_pk_mul_f32 v[0:1], v[10:11], v[0:1]
	v_add_f32_e32 v5, 1.0, v5
	v_rcp_f32_e32 v8, v5
	v_pk_mul_f32 v[10:11], v[46:47], v[4:5] op_sel_hi:[1,0]
	v_and_b32_e32 v5, 0xffff0000, v9
	v_mul_f32_e32 v5, 0xbfb8aa3b, v5
	v_exp_f32_e32 v5, v5
	v_pk_mul_f32 v[2:3], v[2:3], v[10:11]
	v_cvt_pk_bf16_f32 v0, v0, v1
	v_add_f32_e32 v5, 1.0, v5
	v_rcp_f32_e32 v9, v5
	s_nop 0
	v_pk_mul_f32 v[2:3], v[8:9], v[2:3]
	s_nop 0
	v_cvt_pk_bf16_f32 v1, v2, v3
	global_store_dwordx2 v[70:71], v[0:1], off offset:112
	global_load_dwordx2 v[12:13], v[70:71], off offset:128
	ds_read_b128 v[0:3], v81 offset:20736
	ds_read_b128 v[8:11], v81 offset:20768
	s_waitcnt vmcnt(0)
	v_lshlrev_b32_e32 v5, 16, v12
	v_mul_f32_e32 v5, 0xbfb8aa3b, v5
	v_exp_f32_e32 v5, v5
	s_nop 0
	v_add_f32_e32 v5, 1.0, v5
	v_rcp_f32_e32 v28, v5
	v_pk_mul_f32 v[30:31], v[42:43], v[4:5] op_sel_hi:[1,0]
	v_and_b32_e32 v5, 0xffff0000, v12
	v_mul_f32_e32 v5, 0xbfb8aa3b, v5
	v_exp_f32_e32 v5, v5
	s_waitcnt lgkmcnt(1)
; #define LAS __attribute__((address_space(3)))
; __device__ __forceinline__ unsigned pk2(float lo, float hi) { f32x2_t v = {lo, hi}; bf16x2_t b = __builtin_convertvector(v, bf16x2_t); return __builtin_bit_cast(unsigned, b); }
; __device__ __forceinline__ float bflo(unsigned w) { return __uint_as_float(w << 16); }
; __device__ __forceinline__ float bfhi(unsigned w) { return __uint_as_float(w & 0xffff0000u); }
; __device__ __forceinline__ float sigmoidf_(float x) { return __builtin_amdgcn_rcpf(1.f + fexp(-x)); }
; template <bool SAMPLE>
; __device__ __forceinline__ void mout_task(Ctx& C, int l, int unit, int h, int tb, const LAS float* cwl, const LAS float* gainl, LAS float* gsbuf, LAS s16x8* qfl, const bool st) {
;     ...
; #pragma unroll
;     for (int vb = 0; vb < 4; ++vb)
; #pragma unroll
;         for (int i4 = 0; i4 < 4; ++i4) { const int v0 = 32 * vb + 8 * i4 + 4 * hi2;
;             const u32x2 ow = *(const u32x2*)(orow + v0); const f32x4 gn = *(const LAS f32x4*)(gainl + h * 128 + v0);
;             const float y0 = acc[vb][4 * i4] * rn * gn[0] * sigmoidf_(bflo(ow.x)), y1 = acc[vb][4 * i4 + 1] * rn * gn[1] * sigmoidf_(bfhi(ow.x));
;             const float y2 = acc[vb][4 * i4 + 2] * rn * gn[2] * sigmoidf_(bflo(ow.y)), y3 = acc[vb][4 * i4 + 3] * rn * gn[3] * sigmoidf_(bfhi(ow.y));
;             u32x2 w; w.x = pk2(y0, y1); w.y = pk2(y2, y3); if (st) *(u32x2*)(orow + v0) = w; if (i4 == 3) asm volatile("" ::: "memory"); }
	v_pk_mul_f32 v[0:1], v[0:1], v[30:31]
	v_add_f32_e32 v5, 1.0, v5
	v_rcp_f32_e32 v29, v5
	v_lshlrev_b32_e32 v5, 16, v13
	v_mul_f32_e32 v5, 0xbfb8aa3b, v5
	v_exp_f32_e32 v5, v5
	v_pk_mul_f32 v[0:1], v[28:29], v[0:1]
	v_add_f32_e32 v5, 1.0, v5
	v_rcp_f32_e32 v12, v5
	v_pk_mul_f32 v[28:29], v[40:41], v[4:5] op_sel_hi:[1,0]
	v_and_b32_e32 v5, 0xffff0000, v13
	v_mul_f32_e32 v5, 0xbfb8aa3b, v5
	v_exp_f32_e32 v5, v5
	v_pk_mul_f32 v[2:3], v[2:3], v[28:29]
	v_cvt_pk_bf16_f32 v0, v0, v1
	v_add_f32_e32 v5, 1.0, v5
	v_rcp_f32_e32 v13, v5
	s_nop 0
	v_pk_mul_f32 v[2:3], v[12:13], v[2:3]
	s_nop 0
	v_cvt_pk_bf16_f32 v1, v2, v3
	global_store_dwordx2 v[70:71], v[0:1], off offset:128
	global_load_dwordx2 v[0:1], v[70:71], off offset:144
	v_pk_mul_f32 v[12:13], v[38:39], v[4:5] op_sel_hi:[1,0]
	s_waitcnt vmcnt(0)
	v_lshlrev_b32_e32 v2, 16, v0
	v_and_b32_e32 v0, 0xffff0000, v0
	v_mul_f32_e32 v0, 0xbfb8aa3b, v0
	v_exp_f32_e32 v0, v0
	v_mul_f32_e32 v2, 0xbfb8aa3b, v2
	v_exp_f32_e32 v2, v2
	s_waitcnt lgkmcnt(0)
	v_pk_mul_f32 v[8:9], v[8:9], v[12:13]
	v_add_f32_e32 v0, 1.0, v0
	v_rcp_f32_e32 v3, v0
	v_lshlrev_b32_e32 v0, 16, v1
	v_and_b32_e32 v1, 0xffff0000, v1
	v_mul_f32_e32 v0, 0xbfb8aa3b, v0
	v_mul_f32_e32 v1, 0xbfb8aa3b, v1
	v_exp_f32_e32 v0, v0
	v_exp_f32_e32 v1, v1
	v_add_f32_e32 v2, 1.0, v2
	v_rcp_f32_e32 v2, v2
	v_add_f32_e32 v0, 1.0, v0
	v_add_f32_e32 v1, 1.0, v1
	v_rcp_f32_e32 v0, v0
	v_rcp_f32_e32 v1, v1
	v_pk_mul_f32 v[2:3], v[2:3], v[8:9]
	v_pk_mul_f32 v[8:9], v[36:37], v[4:5] op_sel_hi:[1,0]
	v_cvt_pk_bf16_f32 v2, v2, v3
	v_pk_mul_f32 v[8:9], v[10:11], v[8:9]
	s_nop 0
	v_pk_mul_f32 v[0:1], v[0:1], v[8:9]
	global_load_dwordx2 v[8:9], v[70:71], off offset:160
	v_cvt_pk_bf16_f32 v3, v0, v1
	global_store_dwordx2 v[70:71], v[2:3], off offset:144
	ds_read_b128 v[0:3], v81 offset:20800
	s_waitcnt vmcnt(1)
	v_lshlrev_b32_e32 v5, 16, v8
	v_mul_f32_e32 v5, 0xbfb8aa3b, v5
	v_exp_f32_e32 v5, v5
	s_nop 0
	v_add_f32_e32 v5, 1.0, v5
	v_rcp_f32_e32 v10, v5
	v_pk_mul_f32 v[12:13], v[34:35], v[4:5] op_sel_hi:[1,0]
	v_and_b32_e32 v5, 0xffff0000, v8
	v_mul_f32_e32 v5, 0xbfb8aa3b, v5
	v_exp_f32_e32 v5, v5
	s_waitcnt lgkmcnt(0)
	v_pk_mul_f32 v[0:1], v[0:1], v[12:13]
	v_add_f32_e32 v5, 1.0, v5
	v_rcp_f32_e32 v11, v5
	v_lshlrev_b32_e32 v5, 16, v9
	v_mul_f32_e32 v5, 0xbfb8aa3b, v5
	v_exp_f32_e32 v5, v5
	v_pk_mul_f32 v[0:1], v[10:11], v[0:1]
	v_add_f32_e32 v5, 1.0, v5
	v_rcp_f32_e32 v8, v5
	v_pk_mul_f32 v[10:11], v[32:33], v[4:5] op_sel_hi:[1,0]
	v_and_b32_e32 v5, 0xffff0000, v9
	v_mul_f32_e32 v5, 0xbfb8aa3b, v5
	v_exp_f32_e32 v5, v5
	v_pk_mul_f32 v[2:3], v[2:3], v[10:11]
	v_cvt_pk_bf16_f32 v0, v0, v1
	v_add_f32_e32 v5, 1.0, v5
	v_rcp_f32_e32 v9, v5
	s_nop 0
	v_pk_mul_f32 v[2:3], v[8:9], v[2:3]
	global_load_dwordx2 v[8:9], v[70:71], off offset:176
	v_cvt_pk_bf16_f32 v1, v2, v3
	global_store_dwordx2 v[70:71], v[0:1], off offset:160
	ds_read_b128 v[0:3], v81 offset:20832
	s_waitcnt vmcnt(1)
	v_lshlrev_b32_e32 v5, 16, v8
	v_mul_f32_e32 v5, 0xbfb8aa3b, v5
	v_exp_f32_e32 v5, v5
	s_nop 0
	v_add_f32_e32 v5, 1.0, v5
	v_rcp_f32_e32 v10, v5
	v_pk_mul_f32 v[12:13], v[26:27], v[4:5] op_sel_hi:[1,0]
	v_and_b32_e32 v5, 0xffff0000, v8
	v_mul_f32_e32 v5, 0xbfb8aa3b, v5
	v_exp_f32_e32 v5, v5
	s_waitcnt lgkmcnt(0)
	v_pk_mul_f32 v[0:1], v[0:1], v[12:13]
	v_add_f32_e32 v5, 1.0, v5
	v_rcp_f32_e32 v11, v5
	v_lshlrev_b32_e32 v5, 16, v9
	v_mul_f32_e32 v5, 0xbfb8aa3b, v5
	v_exp_f32_e32 v5, v5
	v_pk_mul_f32 v[0:1], v[10:11], v[0:1]
	v_add_f32_e32 v5, 1.0, v5
	v_rcp_f32_e32 v8, v5
	v_pk_mul_f32 v[10:11], v[24:25], v[4:5] op_sel_hi:[1,0]
	v_and_b32_e32 v5, 0xffff0000, v9
	v_mul_f32_e32 v5, 0xbfb8aa3b, v5
	v_exp_f32_e32 v5, v5
	v_pk_mul_f32 v[2:3], v[2:3], v[10:11]
	v_cvt_pk_bf16_f32 v0, v0, v1
	v_add_f32_e32 v5, 1.0, v5
	v_rcp_f32_e32 v9, v5
	s_nop 0
	v_pk_mul_f32 v[2:3], v[8:9], v[2:3]
	s_nop 0
	v_cvt_pk_bf16_f32 v1, v2, v3
	global_store_dwordx2 v[70:71], v[0:1], off offset:176
	global_load_dwordx2 v[12:13], v[70:71], off offset:192
	ds_read_b128 v[0:3], v81 offset:20864
	ds_read_b128 v[8:11], v81 offset:20896
	s_waitcnt vmcnt(0)
; #define LAS __attribute__((address_space(3)))
; __device__ __forceinline__ unsigned pk2(float lo, float hi) { f32x2_t v = {lo, hi}; bf16x2_t b = __builtin_convertvector(v, bf16x2_t); return __builtin_bit_cast(unsigned, b); }
; __device__ __forceinline__ float bflo(unsigned w) { return __uint_as_float(w << 16); }
; __device__ __forceinline__ float bfhi(unsigned w) { return __uint_as_float(w & 0xffff0000u); }
; __device__ __forceinline__ float sigmoidf_(float x) { return __builtin_amdgcn_rcpf(1.f + fexp(-x)); }
; template <bool SAMPLE>
; __device__ __forceinline__ void mout_task(Ctx& C, int l, int unit, int h, int tb, const LAS float* cwl, const LAS float* gainl, LAS float* gsbuf, LAS s16x8* qfl, const bool st) {
;     ...
; #pragma unroll
;     for (int vb = 0; vb < 4; ++vb)
; #pragma unroll
;         for (int i4 = 0; i4 < 4; ++i4) { const int v0 = 32 * vb + 8 * i4 + 4 * hi2;
;             const u32x2 ow = *(const u32x2*)(orow + v0); const f32x4 gn = *(const LAS f32x4*)(gainl + h * 128 + v0);
;             const float y0 = acc[vb][4 * i4] * rn * gn[0] * sigmoidf_(bflo(ow.x)), y1 = acc[vb][4 * i4 + 1] * rn * gn[1] * sigmoidf_(bfhi(ow.x));
;             const float y2 = acc[vb][4 * i4 + 2] * rn * gn[2] * sigmoidf_(bflo(ow.y)), y3 = acc[vb][4 * i4 + 3] * rn * gn[3] * sigmoidf_(bfhi(ow.y));
;             u32x2 w; w.x = pk2(y0, y1); w.y = pk2(y2, y3); if (st) *(u32x2*)(orow + v0) = w; if (i4 == 3) asm volatile("" ::: "memory"); }
	v_lshlrev_b32_e32 v5, 16, v12
	v_mul_f32_e32 v5, 0xbfb8aa3b, v5
	v_exp_f32_e32 v5, v5
	s_nop 0
	v_add_f32_e32 v5, 1.0, v5
	v_rcp_f32_e32 v24, v5
	v_pk_mul_f32 v[22:23], v[22:23], v[4:5] op_sel_hi:[1,0]
	v_and_b32_e32 v5, 0xffff0000, v12
	v_mul_f32_e32 v5, 0xbfb8aa3b, v5
	v_exp_f32_e32 v5, v5
	s_waitcnt lgkmcnt(1)
	v_pk_mul_f32 v[0:1], v[0:1], v[22:23]
	v_add_f32_e32 v5, 1.0, v5
	v_rcp_f32_e32 v25, v5
	v_lshlrev_b32_e32 v5, 16, v13
	v_mul_f32_e32 v5, 0xbfb8aa3b, v5
	v_exp_f32_e32 v5, v5
	v_pk_mul_f32 v[0:1], v[24:25], v[0:1]
	v_add_f32_e32 v5, 1.0, v5
	v_rcp_f32_e32 v12, v5
	v_pk_mul_f32 v[20:21], v[20:21], v[4:5] op_sel_hi:[1,0]
	v_and_b32_e32 v5, 0xffff0000, v13
	v_mul_f32_e32 v5, 0xbfb8aa3b, v5
	v_exp_f32_e32 v5, v5
	v_pk_mul_f32 v[2:3], v[2:3], v[20:21]
	v_cvt_pk_bf16_f32 v0, v0, v1
	v_add_f32_e32 v5, 1.0, v5
	v_rcp_f32_e32 v13, v5
	s_nop 0
	v_pk_mul_f32 v[2:3], v[12:13], v[2:3]
	s_nop 0
	v_cvt_pk_bf16_f32 v1, v2, v3
	global_store_dwordx2 v[70:71], v[0:1], off offset:192
	global_load_dwordx2 v[0:1], v[70:71], off offset:208
	v_pk_mul_f32 v[12:13], v[18:19], v[4:5] op_sel_hi:[1,0]
	s_waitcnt vmcnt(0)
	v_lshlrev_b32_e32 v2, 16, v0
	v_and_b32_e32 v0, 0xffff0000, v0
	v_mul_f32_e32 v0, 0xbfb8aa3b, v0
	v_exp_f32_e32 v0, v0
	v_mul_f32_e32 v2, 0xbfb8aa3b, v2
	v_exp_f32_e32 v2, v2
	s_waitcnt lgkmcnt(0)
	v_pk_mul_f32 v[8:9], v[8:9], v[12:13]
	v_add_f32_e32 v0, 1.0, v0
	v_rcp_f32_e32 v3, v0
	v_lshlrev_b32_e32 v0, 16, v1
	v_and_b32_e32 v1, 0xffff0000, v1
	v_mul_f32_e32 v0, 0xbfb8aa3b, v0
	v_mul_f32_e32 v1, 0xbfb8aa3b, v1
	v_exp_f32_e32 v0, v0
	v_exp_f32_e32 v1, v1
	v_add_f32_e32 v2, 1.0, v2
	v_rcp_f32_e32 v2, v2
	v_add_f32_e32 v0, 1.0, v0
	v_add_f32_e32 v1, 1.0, v1
	v_rcp_f32_e32 v0, v0
	v_rcp_f32_e32 v1, v1
	v_pk_mul_f32 v[2:3], v[2:3], v[8:9]
	v_pk_mul_f32 v[8:9], v[16:17], v[4:5] op_sel_hi:[1,0]
	v_cvt_pk_bf16_f32 v2, v2, v3
	v_pk_mul_f32 v[8:9], v[10:11], v[8:9]
	s_nop 0
	v_pk_mul_f32 v[0:1], v[0:1], v[8:9]
	global_load_dwordx2 v[8:9], v[70:71], off offset:224
	v_cvt_pk_bf16_f32 v3, v0, v1
	global_store_dwordx2 v[70:71], v[2:3], off offset:208
	ds_read_b128 v[0:3], v81 offset:20928
	s_waitcnt vmcnt(1)
	v_lshlrev_b32_e32 v5, 16, v8
	v_mul_f32_e32 v5, 0xbfb8aa3b, v5
	v_exp_f32_e32 v5, v5
	s_nop 0
	v_add_f32_e32 v5, 1.0, v5
	v_rcp_f32_e32 v10, v5
	v_pk_mul_f32 v[6:7], v[6:7], v[4:5] op_sel_hi:[1,0]
	v_and_b32_e32 v5, 0xffff0000, v8
	v_mul_f32_e32 v5, 0xbfb8aa3b, v5
	v_exp_f32_e32 v5, v5
	s_waitcnt lgkmcnt(0)
	v_pk_mul_f32 v[0:1], v[0:1], v[6:7]
	v_add_f32_e32 v5, 1.0, v5
	v_rcp_f32_e32 v11, v5
	v_lshlrev_b32_e32 v5, 16, v9
	v_mul_f32_e32 v5, 0xbfb8aa3b, v5
	v_exp_f32_e32 v5, v5
	v_pk_mul_f32 v[0:1], v[10:11], v[0:1]
	v_add_f32_e32 v5, 1.0, v5
	v_rcp_f32_e32 v6, v5
	v_and_b32_e32 v5, 0xffff0000, v9
	v_mul_f32_e32 v5, 0xbfb8aa3b, v5
	v_exp_f32_e32 v5, v5
	v_cvt_pk_bf16_f32 v0, v0, v1
	v_add_f32_e32 v5, 1.0, v5
	v_rcp_f32_e32 v7, v5
	v_pk_mul_f32 v[8:9], v[72:73], v[4:5] op_sel_hi:[1,0]
	s_nop 0
	v_pk_mul_f32 v[2:3], v[2:3], v[8:9]
	s_nop 0
	v_pk_mul_f32 v[2:3], v[6:7], v[2:3]
	global_load_dwordx2 v[6:7], v[70:71], off offset:240
	v_cvt_pk_bf16_f32 v1, v2, v3
	global_store_dwordx2 v[70:71], v[0:1], off offset:224
	ds_read_b128 v[0:3], v81 offset:20960
	s_waitcnt vmcnt(1)
	v_lshlrev_b32_e32 v5, 16, v6
	v_mul_f32_e32 v5, 0xbfb8aa3b, v5
	v_exp_f32_e32 v5, v5
	s_nop 0
	v_add_f32_e32 v5, 1.0, v5
	v_rcp_f32_e32 v8, v5
	v_and_b32_e32 v5, 0xffff0000, v6
	v_mul_f32_e32 v5, 0xbfb8aa3b, v5
	v_exp_f32_e32 v5, v5
	s_nop 0
	v_add_f32_e32 v5, 1.0, v5
	v_rcp_f32_e32 v9, v5
	v_pk_mul_f32 v[10:11], v[68:69], v[4:5] op_sel_hi:[1,0]
	v_lshlrev_b32_e32 v5, 16, v7
	v_mul_f32_e32 v5, 0xbfb8aa3b, v5
	v_exp_f32_e32 v5, v5
	s_waitcnt lgkmcnt(0)
	v_pk_mul_f32 v[0:1], v[0:1], v[10:11]
	v_add_f32_e32 v5, 1.0, v5
	v_rcp_f32_e32 v6, v5
	v_and_b32_e32 v5, 0xffff0000, v7
	v_mul_f32_e32 v5, 0xbfb8aa3b, v5
	v_exp_f32_e32 v5, v5
	v_pk_mul_f32 v[0:1], v[8:9], v[0:1]
	v_add_f32_e32 v5, 1.0, v5
	v_rcp_f32_e32 v7, v5
	v_pk_mul_f32 v[4:5], v[14:15], v[4:5] op_sel_hi:[1,0]
	v_cvt_pk_bf16_f32 v0, v0, v1
	v_pk_mul_f32 v[2:3], v[2:3], v[4:5]
	s_nop 0
	v_pk_mul_f32 v[2:3], v[6:7], v[2:3]
	s_nop 0
	v_cvt_pk_bf16_f32 v1, v2, v3
	global_store_dwordx2 v[70:71], v[0:1], off offset:240
	s_waitcnt lgkmcnt(0)
	s_branch .LBB0_903
